# software-pipelined the serialized LoRA table loads in prep (both directions) and post phases
# speedup vs baseline: 1.1176x; 1.1176x over previous
.LBB0_543:
	s_mov_b32 s66, 0x1000
	s_mov_b32 s67, 0
	v_mov_b32_e32 v232, v12
	v_mov_b32_e32 v233, v13
	v_mov_b32_e32 v234, v72
	v_mov_b32_e32 v235, v73
	global_load_dwordx4 v[168:171], v[232:233], off offset:-1032
	global_load_dwordx4 v[172:175], v[234:235], off offset:-1032
	global_load_dwordx4 v[176:179], v[232:233], off offset:-8
	global_load_dwordx4 v[180:183], v[234:235], off offset:-8
	global_load_dwordx4 v[184:187], v[232:233], off offset:1016
	global_load_dwordx4 v[188:191], v[234:235], off offset:1016
	global_load_dwordx4 v[192:195], v[232:233], off offset:2040
	global_load_dwordx4 v[196:199], v[234:235], off offset:2040
	v_lshl_add_u64 v[232:233], v[232:233], 0, s[66:67]
	v_lshl_add_u64 v[234:235], v[234:235], 0, s[66:67]
	global_load_dwordx4 v[200:203], v[232:233], off offset:-1032
	global_load_dwordx4 v[204:207], v[234:235], off offset:-1032
	global_load_dwordx4 v[208:211], v[232:233], off offset:-8
	global_load_dwordx4 v[212:215], v[234:235], off offset:-8
	global_load_dwordx4 v[216:219], v[232:233], off offset:1016
	global_load_dwordx4 v[220:223], v[234:235], off offset:1016
	s_waitcnt vmcnt(12)
	v_readlane_b32 s50, v81, 0
	v_readlane_b32 s52, v80, 0
	v_readlane_b32 s54, v79, 0
	v_readlane_b32 s56, v82, 0
	v_readlane_b32 s58, v78, 0
	v_readlane_b32 s60, v76, 0
	v_readlane_b32 s62, v19, 0
	v_readlane_b32 s64, v77, 0
	v_pk_fma_f32 v[74:75], v[168:169], s[50:51], v[74:75] op_sel_hi:[1,0,1]
	v_pk_fma_f32 v[14:15], v[170:171], s[50:51], v[14:15] op_sel_hi:[1,0,1]
	v_pk_fma_f32 v[66:67], v[168:169], s[52:53], v[66:67] op_sel_hi:[1,0,1]
	v_pk_fma_f32 v[64:65], v[170:171], s[52:53], v[64:65] op_sel_hi:[1,0,1]
	v_pk_fma_f32 v[58:59], v[168:169], s[54:55], v[58:59] op_sel_hi:[1,0,1]
	v_pk_fma_f32 v[56:57], v[170:171], s[54:55], v[56:57] op_sel_hi:[1,0,1]
	v_pk_fma_f32 v[8:9], v[168:169], s[56:57], v[8:9] op_sel_hi:[1,0,1]
	v_pk_fma_f32 v[10:11], v[170:171], s[56:57], v[10:11] op_sel_hi:[1,0,1]
	v_pk_fma_f32 v[4:5], v[172:173], s[58:59], v[4:5] op_sel_hi:[1,0,1]
	v_pk_fma_f32 v[6:7], v[174:175], s[58:59], v[6:7] op_sel_hi:[1,0,1]
	v_pk_fma_f32 v[62:63], v[172:173], s[60:61], v[62:63] op_sel_hi:[1,0,1]
	v_pk_fma_f32 v[60:61], v[174:175], s[60:61], v[60:61] op_sel_hi:[1,0,1]
	v_pk_fma_f32 v[70:71], v[172:173], s[62:63], v[70:71] op_sel_hi:[1,0,1]
	v_pk_fma_f32 v[68:69], v[174:175], s[62:63], v[68:69] op_sel_hi:[1,0,1]
	v_pk_fma_f32 v[54:55], v[172:173], s[64:65], v[54:55] op_sel_hi:[1,0,1]
	v_pk_fma_f32 v[52:53], v[174:175], s[64:65], v[52:53] op_sel_hi:[1,0,1]
	global_load_dwordx4 v[224:227], v[232:233], off offset:2040
	global_load_dwordx4 v[228:231], v[234:235], off offset:2040
	v_lshl_add_u64 v[232:233], v[232:233], 0, s[66:67]
	v_lshl_add_u64 v[234:235], v[234:235], 0, s[66:67]
	s_waitcnt vmcnt(12)
	v_readlane_b32 s50, v81, 1
	v_readlane_b32 s52, v80, 1
	v_readlane_b32 s54, v79, 1
	v_readlane_b32 s56, v82, 1
	v_readlane_b32 s58, v78, 1
	v_readlane_b32 s60, v76, 1
	v_readlane_b32 s62, v19, 1
	v_readlane_b32 s64, v77, 1
	v_pk_fma_f32 v[74:75], v[176:177], s[50:51], v[74:75] op_sel_hi:[1,0,1]
	v_pk_fma_f32 v[14:15], v[178:179], s[50:51], v[14:15] op_sel_hi:[1,0,1]
	v_pk_fma_f32 v[66:67], v[176:177], s[52:53], v[66:67] op_sel_hi:[1,0,1]
	v_pk_fma_f32 v[64:65], v[178:179], s[52:53], v[64:65] op_sel_hi:[1,0,1]
	v_pk_fma_f32 v[58:59], v[176:177], s[54:55], v[58:59] op_sel_hi:[1,0,1]
	v_pk_fma_f32 v[56:57], v[178:179], s[54:55], v[56:57] op_sel_hi:[1,0,1]
	v_pk_fma_f32 v[8:9], v[176:177], s[56:57], v[8:9] op_sel_hi:[1,0,1]
	v_pk_fma_f32 v[10:11], v[178:179], s[56:57], v[10:11] op_sel_hi:[1,0,1]
	v_pk_fma_f32 v[4:5], v[180:181], s[58:59], v[4:5] op_sel_hi:[1,0,1]
	v_pk_fma_f32 v[6:7], v[182:183], s[58:59], v[6:7] op_sel_hi:[1,0,1]
	v_pk_fma_f32 v[62:63], v[180:181], s[60:61], v[62:63] op_sel_hi:[1,0,1]
	v_pk_fma_f32 v[60:61], v[182:183], s[60:61], v[60:61] op_sel_hi:[1,0,1]
	v_pk_fma_f32 v[70:71], v[180:181], s[62:63], v[70:71] op_sel_hi:[1,0,1]
	v_pk_fma_f32 v[68:69], v[182:183], s[62:63], v[68:69] op_sel_hi:[1,0,1]
	v_pk_fma_f32 v[54:55], v[180:181], s[64:65], v[54:55] op_sel_hi:[1,0,1]
	v_pk_fma_f32 v[52:53], v[182:183], s[64:65], v[52:53] op_sel_hi:[1,0,1]
	global_load_dwordx4 v[168:171], v[232:233], off offset:-1032
	global_load_dwordx4 v[172:175], v[234:235], off offset:-1032
	s_waitcnt vmcnt(12)
	v_readlane_b32 s50, v81, 2
	v_readlane_b32 s52, v80, 2
	v_readlane_b32 s54, v79, 2
	v_readlane_b32 s56, v82, 2
	v_readlane_b32 s58, v78, 2
	v_readlane_b32 s60, v76, 2
	v_readlane_b32 s62, v19, 2
	v_readlane_b32 s64, v77, 2
	v_pk_fma_f32 v[74:75], v[184:185], s[50:51], v[74:75] op_sel_hi:[1,0,1]
	v_pk_fma_f32 v[14:15], v[186:187], s[50:51], v[14:15] op_sel_hi:[1,0,1]
	v_pk_fma_f32 v[66:67], v[184:185], s[52:53], v[66:67] op_sel_hi:[1,0,1]
	v_pk_fma_f32 v[64:65], v[186:187], s[52:53], v[64:65] op_sel_hi:[1,0,1]
	v_pk_fma_f32 v[58:59], v[184:185], s[54:55], v[58:59] op_sel_hi:[1,0,1]
	v_pk_fma_f32 v[56:57], v[186:187], s[54:55], v[56:57] op_sel_hi:[1,0,1]
	v_pk_fma_f32 v[8:9], v[184:185], s[56:57], v[8:9] op_sel_hi:[1,0,1]
	v_pk_fma_f32 v[10:11], v[186:187], s[56:57], v[10:11] op_sel_hi:[1,0,1]
	v_pk_fma_f32 v[4:5], v[188:189], s[58:59], v[4:5] op_sel_hi:[1,0,1]
	v_pk_fma_f32 v[6:7], v[190:191], s[58:59], v[6:7] op_sel_hi:[1,0,1]
	v_pk_fma_f32 v[62:63], v[188:189], s[60:61], v[62:63] op_sel_hi:[1,0,1]
	v_pk_fma_f32 v[60:61], v[190:191], s[60:61], v[60:61] op_sel_hi:[1,0,1]
	v_pk_fma_f32 v[70:71], v[188:189], s[62:63], v[70:71] op_sel_hi:[1,0,1]
	v_pk_fma_f32 v[68:69], v[190:191], s[62:63], v[68:69] op_sel_hi:[1,0,1]
	v_pk_fma_f32 v[54:55], v[188:189], s[64:65], v[54:55] op_sel_hi:[1,0,1]
	v_pk_fma_f32 v[52:53], v[190:191], s[64:65], v[52:53] op_sel_hi:[1,0,1]
	global_load_dwordx4 v[176:179], v[232:233], off offset:-8
	global_load_dwordx4 v[180:183], v[234:235], off offset:-8
	s_waitcnt vmcnt(12)
	v_readlane_b32 s50, v81, 3
	v_readlane_b32 s52, v80, 3
	v_readlane_b32 s54, v79, 3
	v_readlane_b32 s56, v82, 3
	v_readlane_b32 s58, v78, 3
	v_readlane_b32 s60, v76, 3
	v_readlane_b32 s62, v19, 3
	v_readlane_b32 s64, v77, 3
	v_pk_fma_f32 v[74:75], v[192:193], s[50:51], v[74:75] op_sel_hi:[1,0,1]
	v_pk_fma_f32 v[14:15], v[194:195], s[50:51], v[14:15] op_sel_hi:[1,0,1]
	v_pk_fma_f32 v[66:67], v[192:193], s[52:53], v[66:67] op_sel_hi:[1,0,1]
	v_pk_fma_f32 v[64:65], v[194:195], s[52:53], v[64:65] op_sel_hi:[1,0,1]
	v_pk_fma_f32 v[58:59], v[192:193], s[54:55], v[58:59] op_sel_hi:[1,0,1]
	v_pk_fma_f32 v[56:57], v[194:195], s[54:55], v[56:57] op_sel_hi:[1,0,1]
	v_pk_fma_f32 v[8:9], v[192:193], s[56:57], v[8:9] op_sel_hi:[1,0,1]
	v_pk_fma_f32 v[10:11], v[194:195], s[56:57], v[10:11] op_sel_hi:[1,0,1]
	v_pk_fma_f32 v[4:5], v[196:197], s[58:59], v[4:5] op_sel_hi:[1,0,1]
	v_pk_fma_f32 v[6:7], v[198:199], s[58:59], v[6:7] op_sel_hi:[1,0,1]
	v_pk_fma_f32 v[62:63], v[196:197], s[60:61], v[62:63] op_sel_hi:[1,0,1]
	v_pk_fma_f32 v[60:61], v[198:199], s[60:61], v[60:61] op_sel_hi:[1,0,1]
	v_pk_fma_f32 v[70:71], v[196:197], s[62:63], v[70:71] op_sel_hi:[1,0,1]
	v_pk_fma_f32 v[68:69], v[198:199], s[62:63], v[68:69] op_sel_hi:[1,0,1]
	v_pk_fma_f32 v[54:55], v[196:197], s[64:65], v[54:55] op_sel_hi:[1,0,1]
	v_pk_fma_f32 v[52:53], v[198:199], s[64:65], v[52:53] op_sel_hi:[1,0,1]
	global_load_dwordx4 v[184:187], v[232:233], off offset:1016
	global_load_dwordx4 v[188:191], v[234:235], off offset:1016
	s_waitcnt vmcnt(12)
	v_readlane_b32 s50, v81, 4
	v_readlane_b32 s52, v80, 4
	v_readlane_b32 s54, v79, 4
	v_readlane_b32 s56, v82, 4
	v_readlane_b32 s58, v78, 4
	v_readlane_b32 s60, v76, 4
	v_readlane_b32 s62, v19, 4
	v_readlane_b32 s64, v77, 4
	v_pk_fma_f32 v[74:75], v[200:201], s[50:51], v[74:75] op_sel_hi:[1,0,1]
	v_pk_fma_f32 v[14:15], v[202:203], s[50:51], v[14:15] op_sel_hi:[1,0,1]
	v_pk_fma_f32 v[66:67], v[200:201], s[52:53], v[66:67] op_sel_hi:[1,0,1]
	v_pk_fma_f32 v[64:65], v[202:203], s[52:53], v[64:65] op_sel_hi:[1,0,1]
	v_pk_fma_f32 v[58:59], v[200:201], s[54:55], v[58:59] op_sel_hi:[1,0,1]
	v_pk_fma_f32 v[56:57], v[202:203], s[54:55], v[56:57] op_sel_hi:[1,0,1]
	v_pk_fma_f32 v[8:9], v[200:201], s[56:57], v[8:9] op_sel_hi:[1,0,1]
	v_pk_fma_f32 v[10:11], v[202:203], s[56:57], v[10:11] op_sel_hi:[1,0,1]
	v_pk_fma_f32 v[4:5], v[204:205], s[58:59], v[4:5] op_sel_hi:[1,0,1]
	v_pk_fma_f32 v[6:7], v[206:207], s[58:59], v[6:7] op_sel_hi:[1,0,1]
	v_pk_fma_f32 v[62:63], v[204:205], s[60:61], v[62:63] op_sel_hi:[1,0,1]
	v_pk_fma_f32 v[60:61], v[206:207], s[60:61], v[60:61] op_sel_hi:[1,0,1]
	v_pk_fma_f32 v[70:71], v[204:205], s[62:63], v[70:71] op_sel_hi:[1,0,1]
	v_pk_fma_f32 v[68:69], v[206:207], s[62:63], v[68:69] op_sel_hi:[1,0,1]
	v_pk_fma_f32 v[54:55], v[204:205], s[64:65], v[54:55] op_sel_hi:[1,0,1]
	v_pk_fma_f32 v[52:53], v[206:207], s[64:65], v[52:53] op_sel_hi:[1,0,1]
	global_load_dwordx4 v[192:195], v[232:233], off offset:2040
	global_load_dwordx4 v[196:199], v[234:235], off offset:2040
	v_lshl_add_u64 v[232:233], v[232:233], 0, s[66:67]
	v_lshl_add_u64 v[234:235], v[234:235], 0, s[66:67]
	s_waitcnt vmcnt(12)
	v_readlane_b32 s50, v81, 5
	v_readlane_b32 s52, v80, 5
	v_readlane_b32 s54, v79, 5
	v_readlane_b32 s56, v82, 5
	v_readlane_b32 s58, v78, 5
	v_readlane_b32 s60, v76, 5
	v_readlane_b32 s62, v19, 5
	v_readlane_b32 s64, v77, 5
	v_pk_fma_f32 v[74:75], v[208:209], s[50:51], v[74:75] op_sel_hi:[1,0,1]
	v_pk_fma_f32 v[14:15], v[210:211], s[50:51], v[14:15] op_sel_hi:[1,0,1]
	v_pk_fma_f32 v[66:67], v[208:209], s[52:53], v[66:67] op_sel_hi:[1,0,1]
	v_pk_fma_f32 v[64:65], v[210:211], s[52:53], v[64:65] op_sel_hi:[1,0,1]
	v_pk_fma_f32 v[58:59], v[208:209], s[54:55], v[58:59] op_sel_hi:[1,0,1]
	v_pk_fma_f32 v[56:57], v[210:211], s[54:55], v[56:57] op_sel_hi:[1,0,1]
	v_pk_fma_f32 v[8:9], v[208:209], s[56:57], v[8:9] op_sel_hi:[1,0,1]
	v_pk_fma_f32 v[10:11], v[210:211], s[56:57], v[10:11] op_sel_hi:[1,0,1]
	v_pk_fma_f32 v[4:5], v[212:213], s[58:59], v[4:5] op_sel_hi:[1,0,1]
	v_pk_fma_f32 v[6:7], v[214:215], s[58:59], v[6:7] op_sel_hi:[1,0,1]
	v_pk_fma_f32 v[62:63], v[212:213], s[60:61], v[62:63] op_sel_hi:[1,0,1]
	v_pk_fma_f32 v[60:61], v[214:215], s[60:61], v[60:61] op_sel_hi:[1,0,1]
	v_pk_fma_f32 v[70:71], v[212:213], s[62:63], v[70:71] op_sel_hi:[1,0,1]
	v_pk_fma_f32 v[68:69], v[214:215], s[62:63], v[68:69] op_sel_hi:[1,0,1]
	v_pk_fma_f32 v[54:55], v[212:213], s[64:65], v[54:55] op_sel_hi:[1,0,1]
	v_pk_fma_f32 v[52:53], v[214:215], s[64:65], v[52:53] op_sel_hi:[1,0,1]
	global_load_dwordx4 v[200:203], v[232:233], off offset:-1032
	global_load_dwordx4 v[204:207], v[234:235], off offset:-1032
	s_waitcnt vmcnt(12)
	v_readlane_b32 s50, v81, 6
	v_readlane_b32 s52, v80, 6
	v_readlane_b32 s54, v79, 6
	v_readlane_b32 s56, v82, 6
	v_readlane_b32 s58, v78, 6
	v_readlane_b32 s60, v76, 6
	v_readlane_b32 s62, v19, 6
	v_readlane_b32 s64, v77, 6
	v_pk_fma_f32 v[74:75], v[216:217], s[50:51], v[74:75] op_sel_hi:[1,0,1]
	v_pk_fma_f32 v[14:15], v[218:219], s[50:51], v[14:15] op_sel_hi:[1,0,1]
	v_pk_fma_f32 v[66:67], v[216:217], s[52:53], v[66:67] op_sel_hi:[1,0,1]
	v_pk_fma_f32 v[64:65], v[218:219], s[52:53], v[64:65] op_sel_hi:[1,0,1]
	v_pk_fma_f32 v[58:59], v[216:217], s[54:55], v[58:59] op_sel_hi:[1,0,1]
	v_pk_fma_f32 v[56:57], v[218:219], s[54:55], v[56:57] op_sel_hi:[1,0,1]
	v_pk_fma_f32 v[8:9], v[216:217], s[56:57], v[8:9] op_sel_hi:[1,0,1]
	v_pk_fma_f32 v[10:11], v[218:219], s[56:57], v[10:11] op_sel_hi:[1,0,1]
	v_pk_fma_f32 v[4:5], v[220:221], s[58:59], v[4:5] op_sel_hi:[1,0,1]
	v_pk_fma_f32 v[6:7], v[222:223], s[58:59], v[6:7] op_sel_hi:[1,0,1]
	v_pk_fma_f32 v[62:63], v[220:221], s[60:61], v[62:63] op_sel_hi:[1,0,1]
	v_pk_fma_f32 v[60:61], v[222:223], s[60:61], v[60:61] op_sel_hi:[1,0,1]
	v_pk_fma_f32 v[70:71], v[220:221], s[62:63], v[70:71] op_sel_hi:[1,0,1]
	v_pk_fma_f32 v[68:69], v[222:223], s[62:63], v[68:69] op_sel_hi:[1,0,1]
	v_pk_fma_f32 v[54:55], v[220:221], s[64:65], v[54:55] op_sel_hi:[1,0,1]
	v_pk_fma_f32 v[52:53], v[222:223], s[64:65], v[52:53] op_sel_hi:[1,0,1]
	global_load_dwordx4 v[208:211], v[232:233], off offset:-8
	global_load_dwordx4 v[212:215], v[234:235], off offset:-8
	s_waitcnt vmcnt(12)
	v_readlane_b32 s50, v81, 7
	v_readlane_b32 s52, v80, 7
	v_readlane_b32 s54, v79, 7
	v_readlane_b32 s56, v82, 7
	v_readlane_b32 s58, v78, 7
	v_readlane_b32 s60, v76, 7
	v_readlane_b32 s62, v19, 7
	v_readlane_b32 s64, v77, 7
	v_pk_fma_f32 v[74:75], v[224:225], s[50:51], v[74:75] op_sel_hi:[1,0,1]
	v_pk_fma_f32 v[14:15], v[226:227], s[50:51], v[14:15] op_sel_hi:[1,0,1]
	v_pk_fma_f32 v[66:67], v[224:225], s[52:53], v[66:67] op_sel_hi:[1,0,1]
	v_pk_fma_f32 v[64:65], v[226:227], s[52:53], v[64:65] op_sel_hi:[1,0,1]
	v_pk_fma_f32 v[58:59], v[224:225], s[54:55], v[58:59] op_sel_hi:[1,0,1]
	v_pk_fma_f32 v[56:57], v[226:227], s[54:55], v[56:57] op_sel_hi:[1,0,1]
	v_pk_fma_f32 v[8:9], v[224:225], s[56:57], v[8:9] op_sel_hi:[1,0,1]
	v_pk_fma_f32 v[10:11], v[226:227], s[56:57], v[10:11] op_sel_hi:[1,0,1]
	v_pk_fma_f32 v[4:5], v[228:229], s[58:59], v[4:5] op_sel_hi:[1,0,1]
	v_pk_fma_f32 v[6:7], v[230:231], s[58:59], v[6:7] op_sel_hi:[1,0,1]
	v_pk_fma_f32 v[62:63], v[228:229], s[60:61], v[62:63] op_sel_hi:[1,0,1]
	v_pk_fma_f32 v[60:61], v[230:231], s[60:61], v[60:61] op_sel_hi:[1,0,1]
	v_pk_fma_f32 v[70:71], v[228:229], s[62:63], v[70:71] op_sel_hi:[1,0,1]
	v_pk_fma_f32 v[68:69], v[230:231], s[62:63], v[68:69] op_sel_hi:[1,0,1]
	v_pk_fma_f32 v[54:55], v[228:229], s[64:65], v[54:55] op_sel_hi:[1,0,1]
	v_pk_fma_f32 v[52:53], v[230:231], s[64:65], v[52:53] op_sel_hi:[1,0,1]
	global_load_dwordx4 v[216:219], v[232:233], off offset:1016
	global_load_dwordx4 v[220:223], v[234:235], off offset:1016
	s_waitcnt vmcnt(12)
	v_readlane_b32 s50, v81, 8
	v_readlane_b32 s52, v80, 8
	v_readlane_b32 s54, v79, 8
	v_readlane_b32 s56, v82, 8
	v_readlane_b32 s58, v78, 8
	v_readlane_b32 s60, v76, 8
	v_readlane_b32 s62, v19, 8
	v_readlane_b32 s64, v77, 8
	v_pk_fma_f32 v[74:75], v[168:169], s[50:51], v[74:75] op_sel_hi:[1,0,1]
	v_pk_fma_f32 v[14:15], v[170:171], s[50:51], v[14:15] op_sel_hi:[1,0,1]
	v_pk_fma_f32 v[66:67], v[168:169], s[52:53], v[66:67] op_sel_hi:[1,0,1]
	v_pk_fma_f32 v[64:65], v[170:171], s[52:53], v[64:65] op_sel_hi:[1,0,1]
	v_pk_fma_f32 v[58:59], v[168:169], s[54:55], v[58:59] op_sel_hi:[1,0,1]
	v_pk_fma_f32 v[56:57], v[170:171], s[54:55], v[56:57] op_sel_hi:[1,0,1]
	v_pk_fma_f32 v[8:9], v[168:169], s[56:57], v[8:9] op_sel_hi:[1,0,1]
	v_pk_fma_f32 v[10:11], v[170:171], s[56:57], v[10:11] op_sel_hi:[1,0,1]
	v_pk_fma_f32 v[4:5], v[172:173], s[58:59], v[4:5] op_sel_hi:[1,0,1]
	v_pk_fma_f32 v[6:7], v[174:175], s[58:59], v[6:7] op_sel_hi:[1,0,1]
	v_pk_fma_f32 v[62:63], v[172:173], s[60:61], v[62:63] op_sel_hi:[1,0,1]
	v_pk_fma_f32 v[60:61], v[174:175], s[60:61], v[60:61] op_sel_hi:[1,0,1]
	v_pk_fma_f32 v[70:71], v[172:173], s[62:63], v[70:71] op_sel_hi:[1,0,1]
	v_pk_fma_f32 v[68:69], v[174:175], s[62:63], v[68:69] op_sel_hi:[1,0,1]
	v_pk_fma_f32 v[54:55], v[172:173], s[64:65], v[54:55] op_sel_hi:[1,0,1]
	v_pk_fma_f32 v[52:53], v[174:175], s[64:65], v[52:53] op_sel_hi:[1,0,1]
	global_load_dwordx4 v[224:227], v[232:233], off offset:2040
	global_load_dwordx4 v[228:231], v[234:235], off offset:2040
	v_lshl_add_u64 v[232:233], v[232:233], 0, s[66:67]
	v_lshl_add_u64 v[234:235], v[234:235], 0, s[66:67]
	s_waitcnt vmcnt(12)
	v_readlane_b32 s50, v81, 9
	v_readlane_b32 s52, v80, 9
	v_readlane_b32 s54, v79, 9
	v_readlane_b32 s56, v82, 9
	v_readlane_b32 s58, v78, 9
	v_readlane_b32 s60, v76, 9
	v_readlane_b32 s62, v19, 9
	v_readlane_b32 s64, v77, 9
	v_pk_fma_f32 v[74:75], v[176:177], s[50:51], v[74:75] op_sel_hi:[1,0,1]
	v_pk_fma_f32 v[14:15], v[178:179], s[50:51], v[14:15] op_sel_hi:[1,0,1]
	v_pk_fma_f32 v[66:67], v[176:177], s[52:53], v[66:67] op_sel_hi:[1,0,1]
	v_pk_fma_f32 v[64:65], v[178:179], s[52:53], v[64:65] op_sel_hi:[1,0,1]
	v_pk_fma_f32 v[58:59], v[176:177], s[54:55], v[58:59] op_sel_hi:[1,0,1]
	v_pk_fma_f32 v[56:57], v[178:179], s[54:55], v[56:57] op_sel_hi:[1,0,1]
	v_pk_fma_f32 v[8:9], v[176:177], s[56:57], v[8:9] op_sel_hi:[1,0,1]
	v_pk_fma_f32 v[10:11], v[178:179], s[56:57], v[10:11] op_sel_hi:[1,0,1]
	v_pk_fma_f32 v[4:5], v[180:181], s[58:59], v[4:5] op_sel_hi:[1,0,1]
	v_pk_fma_f32 v[6:7], v[182:183], s[58:59], v[6:7] op_sel_hi:[1,0,1]
	v_pk_fma_f32 v[62:63], v[180:181], s[60:61], v[62:63] op_sel_hi:[1,0,1]
	v_pk_fma_f32 v[60:61], v[182:183], s[60:61], v[60:61] op_sel_hi:[1,0,1]
	v_pk_fma_f32 v[70:71], v[180:181], s[62:63], v[70:71] op_sel_hi:[1,0,1]
	v_pk_fma_f32 v[68:69], v[182:183], s[62:63], v[68:69] op_sel_hi:[1,0,1]
	v_pk_fma_f32 v[54:55], v[180:181], s[64:65], v[54:55] op_sel_hi:[1,0,1]
	v_pk_fma_f32 v[52:53], v[182:183], s[64:65], v[52:53] op_sel_hi:[1,0,1]
	global_load_dwordx4 v[168:171], v[232:233], off offset:-1032
	global_load_dwordx4 v[172:175], v[234:235], off offset:-1032
	s_waitcnt vmcnt(12)
	v_readlane_b32 s50, v81, 10
	v_readlane_b32 s52, v80, 10
	v_readlane_b32 s54, v79, 10
	v_readlane_b32 s56, v82, 10
	v_readlane_b32 s58, v78, 10
	v_readlane_b32 s60, v76, 10
	v_readlane_b32 s62, v19, 10
	v_readlane_b32 s64, v77, 10
	v_pk_fma_f32 v[74:75], v[184:185], s[50:51], v[74:75] op_sel_hi:[1,0,1]
	v_pk_fma_f32 v[14:15], v[186:187], s[50:51], v[14:15] op_sel_hi:[1,0,1]
	v_pk_fma_f32 v[66:67], v[184:185], s[52:53], v[66:67] op_sel_hi:[1,0,1]
	v_pk_fma_f32 v[64:65], v[186:187], s[52:53], v[64:65] op_sel_hi:[1,0,1]
	v_pk_fma_f32 v[58:59], v[184:185], s[54:55], v[58:59] op_sel_hi:[1,0,1]
	v_pk_fma_f32 v[56:57], v[186:187], s[54:55], v[56:57] op_sel_hi:[1,0,1]
	v_pk_fma_f32 v[8:9], v[184:185], s[56:57], v[8:9] op_sel_hi:[1,0,1]
	v_pk_fma_f32 v[10:11], v[186:187], s[56:57], v[10:11] op_sel_hi:[1,0,1]
	v_pk_fma_f32 v[4:5], v[188:189], s[58:59], v[4:5] op_sel_hi:[1,0,1]
	v_pk_fma_f32 v[6:7], v[190:191], s[58:59], v[6:7] op_sel_hi:[1,0,1]
	v_pk_fma_f32 v[62:63], v[188:189], s[60:61], v[62:63] op_sel_hi:[1,0,1]
	v_pk_fma_f32 v[60:61], v[190:191], s[60:61], v[60:61] op_sel_hi:[1,0,1]
	v_pk_fma_f32 v[70:71], v[188:189], s[62:63], v[70:71] op_sel_hi:[1,0,1]
	v_pk_fma_f32 v[68:69], v[190:191], s[62:63], v[68:69] op_sel_hi:[1,0,1]
	v_pk_fma_f32 v[54:55], v[188:189], s[64:65], v[54:55] op_sel_hi:[1,0,1]
	v_pk_fma_f32 v[52:53], v[190:191], s[64:65], v[52:53] op_sel_hi:[1,0,1]
	global_load_dwordx4 v[176:179], v[232:233], off offset:-8
	global_load_dwordx4 v[180:183], v[234:235], off offset:-8
	s_waitcnt vmcnt(12)
	v_readlane_b32 s50, v81, 11
	v_readlane_b32 s52, v80, 11
	v_readlane_b32 s54, v79, 11
	v_readlane_b32 s56, v82, 11
	v_readlane_b32 s58, v78, 11
	v_readlane_b32 s60, v76, 11
	v_readlane_b32 s62, v19, 11
	v_readlane_b32 s64, v77, 11
	v_pk_fma_f32 v[74:75], v[192:193], s[50:51], v[74:75] op_sel_hi:[1,0,1]
	v_pk_fma_f32 v[14:15], v[194:195], s[50:51], v[14:15] op_sel_hi:[1,0,1]
	v_pk_fma_f32 v[66:67], v[192:193], s[52:53], v[66:67] op_sel_hi:[1,0,1]
	v_pk_fma_f32 v[64:65], v[194:195], s[52:53], v[64:65] op_sel_hi:[1,0,1]
	v_pk_fma_f32 v[58:59], v[192:193], s[54:55], v[58:59] op_sel_hi:[1,0,1]
	v_pk_fma_f32 v[56:57], v[194:195], s[54:55], v[56:57] op_sel_hi:[1,0,1]
	v_pk_fma_f32 v[8:9], v[192:193], s[56:57], v[8:9] op_sel_hi:[1,0,1]
	v_pk_fma_f32 v[10:11], v[194:195], s[56:57], v[10:11] op_sel_hi:[1,0,1]
	v_pk_fma_f32 v[4:5], v[196:197], s[58:59], v[4:5] op_sel_hi:[1,0,1]
	v_pk_fma_f32 v[6:7], v[198:199], s[58:59], v[6:7] op_sel_hi:[1,0,1]
	v_pk_fma_f32 v[62:63], v[196:197], s[60:61], v[62:63] op_sel_hi:[1,0,1]
	v_pk_fma_f32 v[60:61], v[198:199], s[60:61], v[60:61] op_sel_hi:[1,0,1]
	v_pk_fma_f32 v[70:71], v[196:197], s[62:63], v[70:71] op_sel_hi:[1,0,1]
	v_pk_fma_f32 v[68:69], v[198:199], s[62:63], v[68:69] op_sel_hi:[1,0,1]
	v_pk_fma_f32 v[54:55], v[196:197], s[64:65], v[54:55] op_sel_hi:[1,0,1]
	v_pk_fma_f32 v[52:53], v[198:199], s[64:65], v[52:53] op_sel_hi:[1,0,1]
	global_load_dwordx4 v[184:187], v[232:233], off offset:1016
	global_load_dwordx4 v[188:191], v[234:235], off offset:1016
	s_waitcnt vmcnt(12)
	v_readlane_b32 s50, v81, 12
	v_readlane_b32 s52, v80, 12
	v_readlane_b32 s54, v79, 12
	v_readlane_b32 s56, v82, 12
	v_readlane_b32 s58, v78, 12
	v_readlane_b32 s60, v76, 12
	v_readlane_b32 s62, v19, 12
	v_readlane_b32 s64, v77, 12
	v_pk_fma_f32 v[74:75], v[200:201], s[50:51], v[74:75] op_sel_hi:[1,0,1]
	v_pk_fma_f32 v[14:15], v[202:203], s[50:51], v[14:15] op_sel_hi:[1,0,1]
	v_pk_fma_f32 v[66:67], v[200:201], s[52:53], v[66:67] op_sel_hi:[1,0,1]
	v_pk_fma_f32 v[64:65], v[202:203], s[52:53], v[64:65] op_sel_hi:[1,0,1]
	v_pk_fma_f32 v[58:59], v[200:201], s[54:55], v[58:59] op_sel_hi:[1,0,1]
	v_pk_fma_f32 v[56:57], v[202:203], s[54:55], v[56:57] op_sel_hi:[1,0,1]
	v_pk_fma_f32 v[8:9], v[200:201], s[56:57], v[8:9] op_sel_hi:[1,0,1]
	v_pk_fma_f32 v[10:11], v[202:203], s[56:57], v[10:11] op_sel_hi:[1,0,1]
	v_pk_fma_f32 v[4:5], v[204:205], s[58:59], v[4:5] op_sel_hi:[1,0,1]
	v_pk_fma_f32 v[6:7], v[206:207], s[58:59], v[6:7] op_sel_hi:[1,0,1]
	v_pk_fma_f32 v[62:63], v[204:205], s[60:61], v[62:63] op_sel_hi:[1,0,1]
	v_pk_fma_f32 v[60:61], v[206:207], s[60:61], v[60:61] op_sel_hi:[1,0,1]
	v_pk_fma_f32 v[70:71], v[204:205], s[62:63], v[70:71] op_sel_hi:[1,0,1]
	v_pk_fma_f32 v[68:69], v[206:207], s[62:63], v[68:69] op_sel_hi:[1,0,1]
	v_pk_fma_f32 v[54:55], v[204:205], s[64:65], v[54:55] op_sel_hi:[1,0,1]
	v_pk_fma_f32 v[52:53], v[206:207], s[64:65], v[52:53] op_sel_hi:[1,0,1]
	global_load_dwordx4 v[192:195], v[232:233], off offset:2040
	global_load_dwordx4 v[196:199], v[234:235], off offset:2040
	v_lshl_add_u64 v[232:233], v[232:233], 0, s[66:67]
	v_lshl_add_u64 v[234:235], v[234:235], 0, s[66:67]
	s_waitcnt vmcnt(12)
	v_readlane_b32 s50, v81, 13
	v_readlane_b32 s52, v80, 13
	v_readlane_b32 s54, v79, 13
	v_readlane_b32 s56, v82, 13
	v_readlane_b32 s58, v78, 13
	v_readlane_b32 s60, v76, 13
	v_readlane_b32 s62, v19, 13
	v_readlane_b32 s64, v77, 13
	v_pk_fma_f32 v[74:75], v[208:209], s[50:51], v[74:75] op_sel_hi:[1,0,1]
	v_pk_fma_f32 v[14:15], v[210:211], s[50:51], v[14:15] op_sel_hi:[1,0,1]
	v_pk_fma_f32 v[66:67], v[208:209], s[52:53], v[66:67] op_sel_hi:[1,0,1]
	v_pk_fma_f32 v[64:65], v[210:211], s[52:53], v[64:65] op_sel_hi:[1,0,1]
	v_pk_fma_f32 v[58:59], v[208:209], s[54:55], v[58:59] op_sel_hi:[1,0,1]
	v_pk_fma_f32 v[56:57], v[210:211], s[54:55], v[56:57] op_sel_hi:[1,0,1]
	v_pk_fma_f32 v[8:9], v[208:209], s[56:57], v[8:9] op_sel_hi:[1,0,1]
	v_pk_fma_f32 v[10:11], v[210:211], s[56:57], v[10:11] op_sel_hi:[1,0,1]
	v_pk_fma_f32 v[4:5], v[212:213], s[58:59], v[4:5] op_sel_hi:[1,0,1]
	v_pk_fma_f32 v[6:7], v[214:215], s[58:59], v[6:7] op_sel_hi:[1,0,1]
	v_pk_fma_f32 v[62:63], v[212:213], s[60:61], v[62:63] op_sel_hi:[1,0,1]
	v_pk_fma_f32 v[60:61], v[214:215], s[60:61], v[60:61] op_sel_hi:[1,0,1]
	v_pk_fma_f32 v[70:71], v[212:213], s[62:63], v[70:71] op_sel_hi:[1,0,1]
	v_pk_fma_f32 v[68:69], v[214:215], s[62:63], v[68:69] op_sel_hi:[1,0,1]
	v_pk_fma_f32 v[54:55], v[212:213], s[64:65], v[54:55] op_sel_hi:[1,0,1]
	v_pk_fma_f32 v[52:53], v[214:215], s[64:65], v[52:53] op_sel_hi:[1,0,1]
	global_load_dwordx4 v[200:203], v[232:233], off offset:-1032
	global_load_dwordx4 v[204:207], v[234:235], off offset:-1032
	s_waitcnt vmcnt(12)
	v_readlane_b32 s50, v81, 14
	v_readlane_b32 s52, v80, 14
	v_readlane_b32 s54, v79, 14
	v_readlane_b32 s56, v82, 14
	v_readlane_b32 s58, v78, 14
	v_readlane_b32 s60, v76, 14
	v_readlane_b32 s62, v19, 14
	v_readlane_b32 s64, v77, 14
	v_pk_fma_f32 v[74:75], v[216:217], s[50:51], v[74:75] op_sel_hi:[1,0,1]
	v_pk_fma_f32 v[14:15], v[218:219], s[50:51], v[14:15] op_sel_hi:[1,0,1]
	v_pk_fma_f32 v[66:67], v[216:217], s[52:53], v[66:67] op_sel_hi:[1,0,1]
	v_pk_fma_f32 v[64:65], v[218:219], s[52:53], v[64:65] op_sel_hi:[1,0,1]
	v_pk_fma_f32 v[58:59], v[216:217], s[54:55], v[58:59] op_sel_hi:[1,0,1]
	v_pk_fma_f32 v[56:57], v[218:219], s[54:55], v[56:57] op_sel_hi:[1,0,1]
	v_pk_fma_f32 v[8:9], v[216:217], s[56:57], v[8:9] op_sel_hi:[1,0,1]
	v_pk_fma_f32 v[10:11], v[218:219], s[56:57], v[10:11] op_sel_hi:[1,0,1]
	v_pk_fma_f32 v[4:5], v[220:221], s[58:59], v[4:5] op_sel_hi:[1,0,1]
	v_pk_fma_f32 v[6:7], v[222:223], s[58:59], v[6:7] op_sel_hi:[1,0,1]
	v_pk_fma_f32 v[62:63], v[220:221], s[60:61], v[62:63] op_sel_hi:[1,0,1]
	v_pk_fma_f32 v[60:61], v[222:223], s[60:61], v[60:61] op_sel_hi:[1,0,1]
	v_pk_fma_f32 v[70:71], v[220:221], s[62:63], v[70:71] op_sel_hi:[1,0,1]
	v_pk_fma_f32 v[68:69], v[222:223], s[62:63], v[68:69] op_sel_hi:[1,0,1]
	v_pk_fma_f32 v[54:55], v[220:221], s[64:65], v[54:55] op_sel_hi:[1,0,1]
	v_pk_fma_f32 v[52:53], v[222:223], s[64:65], v[52:53] op_sel_hi:[1,0,1]
	global_load_dwordx4 v[208:211], v[232:233], off offset:-8
	global_load_dwordx4 v[212:215], v[234:235], off offset:-8
	s_waitcnt vmcnt(12)
	v_readlane_b32 s50, v81, 15
	v_readlane_b32 s52, v80, 15
	v_readlane_b32 s54, v79, 15
	v_readlane_b32 s56, v82, 15
	v_readlane_b32 s58, v78, 15
	v_readlane_b32 s60, v76, 15
	v_readlane_b32 s62, v19, 15
	v_readlane_b32 s64, v77, 15
	v_pk_fma_f32 v[74:75], v[224:225], s[50:51], v[74:75] op_sel_hi:[1,0,1]
	v_pk_fma_f32 v[14:15], v[226:227], s[50:51], v[14:15] op_sel_hi:[1,0,1]
	v_pk_fma_f32 v[66:67], v[224:225], s[52:53], v[66:67] op_sel_hi:[1,0,1]
	v_pk_fma_f32 v[64:65], v[226:227], s[52:53], v[64:65] op_sel_hi:[1,0,1]
	v_pk_fma_f32 v[58:59], v[224:225], s[54:55], v[58:59] op_sel_hi:[1,0,1]
	v_pk_fma_f32 v[56:57], v[226:227], s[54:55], v[56:57] op_sel_hi:[1,0,1]
	v_pk_fma_f32 v[8:9], v[224:225], s[56:57], v[8:9] op_sel_hi:[1,0,1]
	v_pk_fma_f32 v[10:11], v[226:227], s[56:57], v[10:11] op_sel_hi:[1,0,1]
	v_pk_fma_f32 v[4:5], v[228:229], s[58:59], v[4:5] op_sel_hi:[1,0,1]
	v_pk_fma_f32 v[6:7], v[230:231], s[58:59], v[6:7] op_sel_hi:[1,0,1]
	v_pk_fma_f32 v[62:63], v[228:229], s[60:61], v[62:63] op_sel_hi:[1,0,1]
	v_pk_fma_f32 v[60:61], v[230:231], s[60:61], v[60:61] op_sel_hi:[1,0,1]
	v_pk_fma_f32 v[70:71], v[228:229], s[62:63], v[70:71] op_sel_hi:[1,0,1]
	v_pk_fma_f32 v[68:69], v[230:231], s[62:63], v[68:69] op_sel_hi:[1,0,1]
	v_pk_fma_f32 v[54:55], v[228:229], s[64:65], v[54:55] op_sel_hi:[1,0,1]
	v_pk_fma_f32 v[52:53], v[230:231], s[64:65], v[52:53] op_sel_hi:[1,0,1]
	global_load_dwordx4 v[216:219], v[232:233], off offset:1016
	global_load_dwordx4 v[220:223], v[234:235], off offset:1016
	s_waitcnt vmcnt(12)
	v_readlane_b32 s50, v81, 16
	v_readlane_b32 s52, v80, 16
	v_readlane_b32 s54, v79, 16
	v_readlane_b32 s56, v82, 16
	v_readlane_b32 s58, v78, 16
	v_readlane_b32 s60, v76, 16
	v_readlane_b32 s62, v19, 16
	v_readlane_b32 s64, v77, 16
	v_pk_fma_f32 v[74:75], v[168:169], s[50:51], v[74:75] op_sel_hi:[1,0,1]
	v_pk_fma_f32 v[14:15], v[170:171], s[50:51], v[14:15] op_sel_hi:[1,0,1]
	v_pk_fma_f32 v[66:67], v[168:169], s[52:53], v[66:67] op_sel_hi:[1,0,1]
	v_pk_fma_f32 v[64:65], v[170:171], s[52:53], v[64:65] op_sel_hi:[1,0,1]
	v_pk_fma_f32 v[58:59], v[168:169], s[54:55], v[58:59] op_sel_hi:[1,0,1]
	v_pk_fma_f32 v[56:57], v[170:171], s[54:55], v[56:57] op_sel_hi:[1,0,1]
	v_pk_fma_f32 v[8:9], v[168:169], s[56:57], v[8:9] op_sel_hi:[1,0,1]
	v_pk_fma_f32 v[10:11], v[170:171], s[56:57], v[10:11] op_sel_hi:[1,0,1]
	v_pk_fma_f32 v[4:5], v[172:173], s[58:59], v[4:5] op_sel_hi:[1,0,1]
	v_pk_fma_f32 v[6:7], v[174:175], s[58:59], v[6:7] op_sel_hi:[1,0,1]
	v_pk_fma_f32 v[62:63], v[172:173], s[60:61], v[62:63] op_sel_hi:[1,0,1]
	v_pk_fma_f32 v[60:61], v[174:175], s[60:61], v[60:61] op_sel_hi:[1,0,1]
	v_pk_fma_f32 v[70:71], v[172:173], s[62:63], v[70:71] op_sel_hi:[1,0,1]
	v_pk_fma_f32 v[68:69], v[174:175], s[62:63], v[68:69] op_sel_hi:[1,0,1]
	v_pk_fma_f32 v[54:55], v[172:173], s[64:65], v[54:55] op_sel_hi:[1,0,1]
	v_pk_fma_f32 v[52:53], v[174:175], s[64:65], v[52:53] op_sel_hi:[1,0,1]
	global_load_dwordx4 v[224:227], v[232:233], off offset:2040
	global_load_dwordx4 v[228:231], v[234:235], off offset:2040
	v_lshl_add_u64 v[232:233], v[232:233], 0, s[66:67]
	v_lshl_add_u64 v[234:235], v[234:235], 0, s[66:67]
	s_waitcnt vmcnt(12)
	v_readlane_b32 s50, v81, 17
	v_readlane_b32 s52, v80, 17
	v_readlane_b32 s54, v79, 17
	v_readlane_b32 s56, v82, 17
	v_readlane_b32 s58, v78, 17
	v_readlane_b32 s60, v76, 17
	v_readlane_b32 s62, v19, 17
	v_readlane_b32 s64, v77, 17
	v_pk_fma_f32 v[74:75], v[176:177], s[50:51], v[74:75] op_sel_hi:[1,0,1]
	v_pk_fma_f32 v[14:15], v[178:179], s[50:51], v[14:15] op_sel_hi:[1,0,1]
	v_pk_fma_f32 v[66:67], v[176:177], s[52:53], v[66:67] op_sel_hi:[1,0,1]
	v_pk_fma_f32 v[64:65], v[178:179], s[52:53], v[64:65] op_sel_hi:[1,0,1]
	v_pk_fma_f32 v[58:59], v[176:177], s[54:55], v[58:59] op_sel_hi:[1,0,1]
	v_pk_fma_f32 v[56:57], v[178:179], s[54:55], v[56:57] op_sel_hi:[1,0,1]
	v_pk_fma_f32 v[8:9], v[176:177], s[56:57], v[8:9] op_sel_hi:[1,0,1]
	v_pk_fma_f32 v[10:11], v[178:179], s[56:57], v[10:11] op_sel_hi:[1,0,1]
	v_pk_fma_f32 v[4:5], v[180:181], s[58:59], v[4:5] op_sel_hi:[1,0,1]
	v_pk_fma_f32 v[6:7], v[182:183], s[58:59], v[6:7] op_sel_hi:[1,0,1]
	v_pk_fma_f32 v[62:63], v[180:181], s[60:61], v[62:63] op_sel_hi:[1,0,1]
	v_pk_fma_f32 v[60:61], v[182:183], s[60:61], v[60:61] op_sel_hi:[1,0,1]
	v_pk_fma_f32 v[70:71], v[180:181], s[62:63], v[70:71] op_sel_hi:[1,0,1]
	v_pk_fma_f32 v[68:69], v[182:183], s[62:63], v[68:69] op_sel_hi:[1,0,1]
	v_pk_fma_f32 v[54:55], v[180:181], s[64:65], v[54:55] op_sel_hi:[1,0,1]
	v_pk_fma_f32 v[52:53], v[182:183], s[64:65], v[52:53] op_sel_hi:[1,0,1]
	global_load_dwordx4 v[168:171], v[232:233], off offset:-1032
	global_load_dwordx4 v[172:175], v[234:235], off offset:-1032
	s_waitcnt vmcnt(12)
	v_readlane_b32 s50, v81, 18
	v_readlane_b32 s52, v80, 18
	v_readlane_b32 s54, v79, 18
	v_readlane_b32 s56, v82, 18
	v_readlane_b32 s58, v78, 18
	v_readlane_b32 s60, v76, 18
	v_readlane_b32 s62, v19, 18
	v_readlane_b32 s64, v77, 18
	v_pk_fma_f32 v[74:75], v[184:185], s[50:51], v[74:75] op_sel_hi:[1,0,1]
	v_pk_fma_f32 v[14:15], v[186:187], s[50:51], v[14:15] op_sel_hi:[1,0,1]
	v_pk_fma_f32 v[66:67], v[184:185], s[52:53], v[66:67] op_sel_hi:[1,0,1]
	v_pk_fma_f32 v[64:65], v[186:187], s[52:53], v[64:65] op_sel_hi:[1,0,1]
	v_pk_fma_f32 v[58:59], v[184:185], s[54:55], v[58:59] op_sel_hi:[1,0,1]
	v_pk_fma_f32 v[56:57], v[186:187], s[54:55], v[56:57] op_sel_hi:[1,0,1]
	v_pk_fma_f32 v[8:9], v[184:185], s[56:57], v[8:9] op_sel_hi:[1,0,1]
	v_pk_fma_f32 v[10:11], v[186:187], s[56:57], v[10:11] op_sel_hi:[1,0,1]
	v_pk_fma_f32 v[4:5], v[188:189], s[58:59], v[4:5] op_sel_hi:[1,0,1]
	v_pk_fma_f32 v[6:7], v[190:191], s[58:59], v[6:7] op_sel_hi:[1,0,1]
	v_pk_fma_f32 v[62:63], v[188:189], s[60:61], v[62:63] op_sel_hi:[1,0,1]
	v_pk_fma_f32 v[60:61], v[190:191], s[60:61], v[60:61] op_sel_hi:[1,0,1]
	v_pk_fma_f32 v[70:71], v[188:189], s[62:63], v[70:71] op_sel_hi:[1,0,1]
	v_pk_fma_f32 v[68:69], v[190:191], s[62:63], v[68:69] op_sel_hi:[1,0,1]
	v_pk_fma_f32 v[54:55], v[188:189], s[64:65], v[54:55] op_sel_hi:[1,0,1]
	v_pk_fma_f32 v[52:53], v[190:191], s[64:65], v[52:53] op_sel_hi:[1,0,1]
	global_load_dwordx4 v[176:179], v[232:233], off offset:-8
	global_load_dwordx4 v[180:183], v[234:235], off offset:-8
	s_waitcnt vmcnt(12)
	v_readlane_b32 s50, v81, 19
	v_readlane_b32 s52, v80, 19
	v_readlane_b32 s54, v79, 19
	v_readlane_b32 s56, v82, 19
	v_readlane_b32 s58, v78, 19
	v_readlane_b32 s60, v76, 19
	v_readlane_b32 s62, v19, 19
	v_readlane_b32 s64, v77, 19
	v_pk_fma_f32 v[74:75], v[192:193], s[50:51], v[74:75] op_sel_hi:[1,0,1]
	v_pk_fma_f32 v[14:15], v[194:195], s[50:51], v[14:15] op_sel_hi:[1,0,1]
	v_pk_fma_f32 v[66:67], v[192:193], s[52:53], v[66:67] op_sel_hi:[1,0,1]
	v_pk_fma_f32 v[64:65], v[194:195], s[52:53], v[64:65] op_sel_hi:[1,0,1]
	v_pk_fma_f32 v[58:59], v[192:193], s[54:55], v[58:59] op_sel_hi:[1,0,1]
	v_pk_fma_f32 v[56:57], v[194:195], s[54:55], v[56:57] op_sel_hi:[1,0,1]
	v_pk_fma_f32 v[8:9], v[192:193], s[56:57], v[8:9] op_sel_hi:[1,0,1]
	v_pk_fma_f32 v[10:11], v[194:195], s[56:57], v[10:11] op_sel_hi:[1,0,1]
	v_pk_fma_f32 v[4:5], v[196:197], s[58:59], v[4:5] op_sel_hi:[1,0,1]
	v_pk_fma_f32 v[6:7], v[198:199], s[58:59], v[6:7] op_sel_hi:[1,0,1]
	v_pk_fma_f32 v[62:63], v[196:197], s[60:61], v[62:63] op_sel_hi:[1,0,1]
	v_pk_fma_f32 v[60:61], v[198:199], s[60:61], v[60:61] op_sel_hi:[1,0,1]
	v_pk_fma_f32 v[70:71], v[196:197], s[62:63], v[70:71] op_sel_hi:[1,0,1]
	v_pk_fma_f32 v[68:69], v[198:199], s[62:63], v[68:69] op_sel_hi:[1,0,1]
	v_pk_fma_f32 v[54:55], v[196:197], s[64:65], v[54:55] op_sel_hi:[1,0,1]
	v_pk_fma_f32 v[52:53], v[198:199], s[64:65], v[52:53] op_sel_hi:[1,0,1]
	global_load_dwordx4 v[184:187], v[232:233], off offset:1016
	global_load_dwordx4 v[188:191], v[234:235], off offset:1016
	s_waitcnt vmcnt(12)
	v_readlane_b32 s50, v81, 20
	v_readlane_b32 s52, v80, 20
	v_readlane_b32 s54, v79, 20
	v_readlane_b32 s56, v82, 20
	v_readlane_b32 s58, v78, 20
	v_readlane_b32 s60, v76, 20
	v_readlane_b32 s62, v19, 20
	v_readlane_b32 s64, v77, 20
	v_pk_fma_f32 v[74:75], v[200:201], s[50:51], v[74:75] op_sel_hi:[1,0,1]
	v_pk_fma_f32 v[14:15], v[202:203], s[50:51], v[14:15] op_sel_hi:[1,0,1]
	v_pk_fma_f32 v[66:67], v[200:201], s[52:53], v[66:67] op_sel_hi:[1,0,1]
	v_pk_fma_f32 v[64:65], v[202:203], s[52:53], v[64:65] op_sel_hi:[1,0,1]
	v_pk_fma_f32 v[58:59], v[200:201], s[54:55], v[58:59] op_sel_hi:[1,0,1]
	v_pk_fma_f32 v[56:57], v[202:203], s[54:55], v[56:57] op_sel_hi:[1,0,1]
	v_pk_fma_f32 v[8:9], v[200:201], s[56:57], v[8:9] op_sel_hi:[1,0,1]
	v_pk_fma_f32 v[10:11], v[202:203], s[56:57], v[10:11] op_sel_hi:[1,0,1]
	v_pk_fma_f32 v[4:5], v[204:205], s[58:59], v[4:5] op_sel_hi:[1,0,1]
	v_pk_fma_f32 v[6:7], v[206:207], s[58:59], v[6:7] op_sel_hi:[1,0,1]
	v_pk_fma_f32 v[62:63], v[204:205], s[60:61], v[62:63] op_sel_hi:[1,0,1]
	v_pk_fma_f32 v[60:61], v[206:207], s[60:61], v[60:61] op_sel_hi:[1,0,1]
	v_pk_fma_f32 v[70:71], v[204:205], s[62:63], v[70:71] op_sel_hi:[1,0,1]
	v_pk_fma_f32 v[68:69], v[206:207], s[62:63], v[68:69] op_sel_hi:[1,0,1]
	v_pk_fma_f32 v[54:55], v[204:205], s[64:65], v[54:55] op_sel_hi:[1,0,1]
	v_pk_fma_f32 v[52:53], v[206:207], s[64:65], v[52:53] op_sel_hi:[1,0,1]
	global_load_dwordx4 v[192:195], v[232:233], off offset:2040
	global_load_dwordx4 v[196:199], v[234:235], off offset:2040
	v_lshl_add_u64 v[232:233], v[232:233], 0, s[66:67]
	v_lshl_add_u64 v[234:235], v[234:235], 0, s[66:67]
	s_waitcnt vmcnt(12)
	v_readlane_b32 s50, v81, 21
	v_readlane_b32 s52, v80, 21
	v_readlane_b32 s54, v79, 21
	v_readlane_b32 s56, v82, 21
	v_readlane_b32 s58, v78, 21
	v_readlane_b32 s60, v76, 21
	v_readlane_b32 s62, v19, 21
	v_readlane_b32 s64, v77, 21
	v_pk_fma_f32 v[74:75], v[208:209], s[50:51], v[74:75] op_sel_hi:[1,0,1]
	v_pk_fma_f32 v[14:15], v[210:211], s[50:51], v[14:15] op_sel_hi:[1,0,1]
	v_pk_fma_f32 v[66:67], v[208:209], s[52:53], v[66:67] op_sel_hi:[1,0,1]
	v_pk_fma_f32 v[64:65], v[210:211], s[52:53], v[64:65] op_sel_hi:[1,0,1]
	v_pk_fma_f32 v[58:59], v[208:209], s[54:55], v[58:59] op_sel_hi:[1,0,1]
	v_pk_fma_f32 v[56:57], v[210:211], s[54:55], v[56:57] op_sel_hi:[1,0,1]
	v_pk_fma_f32 v[8:9], v[208:209], s[56:57], v[8:9] op_sel_hi:[1,0,1]
	v_pk_fma_f32 v[10:11], v[210:211], s[56:57], v[10:11] op_sel_hi:[1,0,1]
	v_pk_fma_f32 v[4:5], v[212:213], s[58:59], v[4:5] op_sel_hi:[1,0,1]
	v_pk_fma_f32 v[6:7], v[214:215], s[58:59], v[6:7] op_sel_hi:[1,0,1]
	v_pk_fma_f32 v[62:63], v[212:213], s[60:61], v[62:63] op_sel_hi:[1,0,1]
	v_pk_fma_f32 v[60:61], v[214:215], s[60:61], v[60:61] op_sel_hi:[1,0,1]
	v_pk_fma_f32 v[70:71], v[212:213], s[62:63], v[70:71] op_sel_hi:[1,0,1]
	v_pk_fma_f32 v[68:69], v[214:215], s[62:63], v[68:69] op_sel_hi:[1,0,1]
	v_pk_fma_f32 v[54:55], v[212:213], s[64:65], v[54:55] op_sel_hi:[1,0,1]
	v_pk_fma_f32 v[52:53], v[214:215], s[64:65], v[52:53] op_sel_hi:[1,0,1]
	global_load_dwordx4 v[200:203], v[232:233], off offset:-1032
	global_load_dwordx4 v[204:207], v[234:235], off offset:-1032
	s_waitcnt vmcnt(12)
	v_readlane_b32 s50, v81, 22
	v_readlane_b32 s52, v80, 22
	v_readlane_b32 s54, v79, 22
	v_readlane_b32 s56, v82, 22
	v_readlane_b32 s58, v78, 22
	v_readlane_b32 s60, v76, 22
	v_readlane_b32 s62, v19, 22
	v_readlane_b32 s64, v77, 22
	v_pk_fma_f32 v[74:75], v[216:217], s[50:51], v[74:75] op_sel_hi:[1,0,1]
	v_pk_fma_f32 v[14:15], v[218:219], s[50:51], v[14:15] op_sel_hi:[1,0,1]
	v_pk_fma_f32 v[66:67], v[216:217], s[52:53], v[66:67] op_sel_hi:[1,0,1]
	v_pk_fma_f32 v[64:65], v[218:219], s[52:53], v[64:65] op_sel_hi:[1,0,1]
	v_pk_fma_f32 v[58:59], v[216:217], s[54:55], v[58:59] op_sel_hi:[1,0,1]
	v_pk_fma_f32 v[56:57], v[218:219], s[54:55], v[56:57] op_sel_hi:[1,0,1]
	v_pk_fma_f32 v[8:9], v[216:217], s[56:57], v[8:9] op_sel_hi:[1,0,1]
	v_pk_fma_f32 v[10:11], v[218:219], s[56:57], v[10:11] op_sel_hi:[1,0,1]
	v_pk_fma_f32 v[4:5], v[220:221], s[58:59], v[4:5] op_sel_hi:[1,0,1]
	v_pk_fma_f32 v[6:7], v[222:223], s[58:59], v[6:7] op_sel_hi:[1,0,1]
	v_pk_fma_f32 v[62:63], v[220:221], s[60:61], v[62:63] op_sel_hi:[1,0,1]
	v_pk_fma_f32 v[60:61], v[222:223], s[60:61], v[60:61] op_sel_hi:[1,0,1]
	v_pk_fma_f32 v[70:71], v[220:221], s[62:63], v[70:71] op_sel_hi:[1,0,1]
	v_pk_fma_f32 v[68:69], v[222:223], s[62:63], v[68:69] op_sel_hi:[1,0,1]
	v_pk_fma_f32 v[54:55], v[220:221], s[64:65], v[54:55] op_sel_hi:[1,0,1]
	v_pk_fma_f32 v[52:53], v[222:223], s[64:65], v[52:53] op_sel_hi:[1,0,1]
	global_load_dwordx4 v[208:211], v[232:233], off offset:-8
	global_load_dwordx4 v[212:215], v[234:235], off offset:-8
	s_waitcnt vmcnt(12)
	v_readlane_b32 s50, v81, 23
	v_readlane_b32 s52, v80, 23
	v_readlane_b32 s54, v79, 23
	v_readlane_b32 s56, v82, 23
	v_readlane_b32 s58, v78, 23
	v_readlane_b32 s60, v76, 23
	v_readlane_b32 s62, v19, 23
	v_readlane_b32 s64, v77, 23
	v_pk_fma_f32 v[74:75], v[224:225], s[50:51], v[74:75] op_sel_hi:[1,0,1]
	v_pk_fma_f32 v[14:15], v[226:227], s[50:51], v[14:15] op_sel_hi:[1,0,1]
	v_pk_fma_f32 v[66:67], v[224:225], s[52:53], v[66:67] op_sel_hi:[1,0,1]
	v_pk_fma_f32 v[64:65], v[226:227], s[52:53], v[64:65] op_sel_hi:[1,0,1]
	v_pk_fma_f32 v[58:59], v[224:225], s[54:55], v[58:59] op_sel_hi:[1,0,1]
	v_pk_fma_f32 v[56:57], v[226:227], s[54:55], v[56:57] op_sel_hi:[1,0,1]
	v_pk_fma_f32 v[8:9], v[224:225], s[56:57], v[8:9] op_sel_hi:[1,0,1]
	v_pk_fma_f32 v[10:11], v[226:227], s[56:57], v[10:11] op_sel_hi:[1,0,1]
	v_pk_fma_f32 v[4:5], v[228:229], s[58:59], v[4:5] op_sel_hi:[1,0,1]
	v_pk_fma_f32 v[6:7], v[230:231], s[58:59], v[6:7] op_sel_hi:[1,0,1]
	v_pk_fma_f32 v[62:63], v[228:229], s[60:61], v[62:63] op_sel_hi:[1,0,1]
	v_pk_fma_f32 v[60:61], v[230:231], s[60:61], v[60:61] op_sel_hi:[1,0,1]
	v_pk_fma_f32 v[70:71], v[228:229], s[62:63], v[70:71] op_sel_hi:[1,0,1]
	v_pk_fma_f32 v[68:69], v[230:231], s[62:63], v[68:69] op_sel_hi:[1,0,1]
	v_pk_fma_f32 v[54:55], v[228:229], s[64:65], v[54:55] op_sel_hi:[1,0,1]
	v_pk_fma_f32 v[52:53], v[230:231], s[64:65], v[52:53] op_sel_hi:[1,0,1]
	global_load_dwordx4 v[216:219], v[232:233], off offset:1016
	global_load_dwordx4 v[220:223], v[234:235], off offset:1016
	s_waitcnt vmcnt(12)
	v_readlane_b32 s50, v81, 24
	v_readlane_b32 s52, v80, 24
	v_readlane_b32 s54, v79, 24
	v_readlane_b32 s56, v82, 24
	v_readlane_b32 s58, v78, 24
	v_readlane_b32 s60, v76, 24
	v_readlane_b32 s62, v19, 24
	v_readlane_b32 s64, v77, 24
	v_pk_fma_f32 v[74:75], v[168:169], s[50:51], v[74:75] op_sel_hi:[1,0,1]
	v_pk_fma_f32 v[14:15], v[170:171], s[50:51], v[14:15] op_sel_hi:[1,0,1]
	v_pk_fma_f32 v[66:67], v[168:169], s[52:53], v[66:67] op_sel_hi:[1,0,1]
	v_pk_fma_f32 v[64:65], v[170:171], s[52:53], v[64:65] op_sel_hi:[1,0,1]
	v_pk_fma_f32 v[58:59], v[168:169], s[54:55], v[58:59] op_sel_hi:[1,0,1]
	v_pk_fma_f32 v[56:57], v[170:171], s[54:55], v[56:57] op_sel_hi:[1,0,1]
	v_pk_fma_f32 v[8:9], v[168:169], s[56:57], v[8:9] op_sel_hi:[1,0,1]
	v_pk_fma_f32 v[10:11], v[170:171], s[56:57], v[10:11] op_sel_hi:[1,0,1]
	v_pk_fma_f32 v[4:5], v[172:173], s[58:59], v[4:5] op_sel_hi:[1,0,1]
	v_pk_fma_f32 v[6:7], v[174:175], s[58:59], v[6:7] op_sel_hi:[1,0,1]
	v_pk_fma_f32 v[62:63], v[172:173], s[60:61], v[62:63] op_sel_hi:[1,0,1]
	v_pk_fma_f32 v[60:61], v[174:175], s[60:61], v[60:61] op_sel_hi:[1,0,1]
	v_pk_fma_f32 v[70:71], v[172:173], s[62:63], v[70:71] op_sel_hi:[1,0,1]
	v_pk_fma_f32 v[68:69], v[174:175], s[62:63], v[68:69] op_sel_hi:[1,0,1]
	v_pk_fma_f32 v[54:55], v[172:173], s[64:65], v[54:55] op_sel_hi:[1,0,1]
	v_pk_fma_f32 v[52:53], v[174:175], s[64:65], v[52:53] op_sel_hi:[1,0,1]
	global_load_dwordx4 v[224:227], v[232:233], off offset:2040
	global_load_dwordx4 v[228:231], v[234:235], off offset:2040
	s_waitcnt vmcnt(12)
	v_readlane_b32 s50, v81, 25
	v_readlane_b32 s52, v80, 25
	v_readlane_b32 s54, v79, 25
	v_readlane_b32 s56, v82, 25
	v_readlane_b32 s58, v78, 25
	v_readlane_b32 s60, v76, 25
	v_readlane_b32 s62, v19, 25
	v_readlane_b32 s64, v77, 25
	v_pk_fma_f32 v[74:75], v[176:177], s[50:51], v[74:75] op_sel_hi:[1,0,1]
	v_pk_fma_f32 v[14:15], v[178:179], s[50:51], v[14:15] op_sel_hi:[1,0,1]
	v_pk_fma_f32 v[66:67], v[176:177], s[52:53], v[66:67] op_sel_hi:[1,0,1]
	v_pk_fma_f32 v[64:65], v[178:179], s[52:53], v[64:65] op_sel_hi:[1,0,1]
	v_pk_fma_f32 v[58:59], v[176:177], s[54:55], v[58:59] op_sel_hi:[1,0,1]
	v_pk_fma_f32 v[56:57], v[178:179], s[54:55], v[56:57] op_sel_hi:[1,0,1]
	v_pk_fma_f32 v[8:9], v[176:177], s[56:57], v[8:9] op_sel_hi:[1,0,1]
	v_pk_fma_f32 v[10:11], v[178:179], s[56:57], v[10:11] op_sel_hi:[1,0,1]
	v_pk_fma_f32 v[4:5], v[180:181], s[58:59], v[4:5] op_sel_hi:[1,0,1]
	v_pk_fma_f32 v[6:7], v[182:183], s[58:59], v[6:7] op_sel_hi:[1,0,1]
	v_pk_fma_f32 v[62:63], v[180:181], s[60:61], v[62:63] op_sel_hi:[1,0,1]
	v_pk_fma_f32 v[60:61], v[182:183], s[60:61], v[60:61] op_sel_hi:[1,0,1]
	v_pk_fma_f32 v[70:71], v[180:181], s[62:63], v[70:71] op_sel_hi:[1,0,1]
	v_pk_fma_f32 v[68:69], v[182:183], s[62:63], v[68:69] op_sel_hi:[1,0,1]
	v_pk_fma_f32 v[54:55], v[180:181], s[64:65], v[54:55] op_sel_hi:[1,0,1]
	v_pk_fma_f32 v[52:53], v[182:183], s[64:65], v[52:53] op_sel_hi:[1,0,1]
	s_waitcnt vmcnt(10)
	v_readlane_b32 s50, v81, 26
	v_readlane_b32 s52, v80, 26
	v_readlane_b32 s54, v79, 26
	v_readlane_b32 s56, v82, 26
	v_readlane_b32 s58, v78, 26
	v_readlane_b32 s60, v76, 26
	v_readlane_b32 s62, v19, 26
	v_readlane_b32 s64, v77, 26
	v_pk_fma_f32 v[74:75], v[184:185], s[50:51], v[74:75] op_sel_hi:[1,0,1]
	v_pk_fma_f32 v[14:15], v[186:187], s[50:51], v[14:15] op_sel_hi:[1,0,1]
	v_pk_fma_f32 v[66:67], v[184:185], s[52:53], v[66:67] op_sel_hi:[1,0,1]
	v_pk_fma_f32 v[64:65], v[186:187], s[52:53], v[64:65] op_sel_hi:[1,0,1]
	v_pk_fma_f32 v[58:59], v[184:185], s[54:55], v[58:59] op_sel_hi:[1,0,1]
	v_pk_fma_f32 v[56:57], v[186:187], s[54:55], v[56:57] op_sel_hi:[1,0,1]
	v_pk_fma_f32 v[8:9], v[184:185], s[56:57], v[8:9] op_sel_hi:[1,0,1]
	v_pk_fma_f32 v[10:11], v[186:187], s[56:57], v[10:11] op_sel_hi:[1,0,1]
	v_pk_fma_f32 v[4:5], v[188:189], s[58:59], v[4:5] op_sel_hi:[1,0,1]
	v_pk_fma_f32 v[6:7], v[190:191], s[58:59], v[6:7] op_sel_hi:[1,0,1]
	v_pk_fma_f32 v[62:63], v[188:189], s[60:61], v[62:63] op_sel_hi:[1,0,1]
	v_pk_fma_f32 v[60:61], v[190:191], s[60:61], v[60:61] op_sel_hi:[1,0,1]
	v_pk_fma_f32 v[70:71], v[188:189], s[62:63], v[70:71] op_sel_hi:[1,0,1]
	v_pk_fma_f32 v[68:69], v[190:191], s[62:63], v[68:69] op_sel_hi:[1,0,1]
	v_pk_fma_f32 v[54:55], v[188:189], s[64:65], v[54:55] op_sel_hi:[1,0,1]
	v_pk_fma_f32 v[52:53], v[190:191], s[64:65], v[52:53] op_sel_hi:[1,0,1]
	s_waitcnt vmcnt(8)
	v_readlane_b32 s50, v81, 27
	v_readlane_b32 s52, v80, 27
	v_readlane_b32 s54, v79, 27
	v_readlane_b32 s56, v82, 27
	v_readlane_b32 s58, v78, 27
	v_readlane_b32 s60, v76, 27
	v_readlane_b32 s62, v19, 27
	v_readlane_b32 s64, v77, 27
	v_pk_fma_f32 v[74:75], v[192:193], s[50:51], v[74:75] op_sel_hi:[1,0,1]
	v_pk_fma_f32 v[14:15], v[194:195], s[50:51], v[14:15] op_sel_hi:[1,0,1]
	v_pk_fma_f32 v[66:67], v[192:193], s[52:53], v[66:67] op_sel_hi:[1,0,1]
	v_pk_fma_f32 v[64:65], v[194:195], s[52:53], v[64:65] op_sel_hi:[1,0,1]
	v_pk_fma_f32 v[58:59], v[192:193], s[54:55], v[58:59] op_sel_hi:[1,0,1]
	v_pk_fma_f32 v[56:57], v[194:195], s[54:55], v[56:57] op_sel_hi:[1,0,1]
	v_pk_fma_f32 v[8:9], v[192:193], s[56:57], v[8:9] op_sel_hi:[1,0,1]
	v_pk_fma_f32 v[10:11], v[194:195], s[56:57], v[10:11] op_sel_hi:[1,0,1]
	v_pk_fma_f32 v[4:5], v[196:197], s[58:59], v[4:5] op_sel_hi:[1,0,1]
	v_pk_fma_f32 v[6:7], v[198:199], s[58:59], v[6:7] op_sel_hi:[1,0,1]
	v_pk_fma_f32 v[62:63], v[196:197], s[60:61], v[62:63] op_sel_hi:[1,0,1]
	v_pk_fma_f32 v[60:61], v[198:199], s[60:61], v[60:61] op_sel_hi:[1,0,1]
	v_pk_fma_f32 v[70:71], v[196:197], s[62:63], v[70:71] op_sel_hi:[1,0,1]
	v_pk_fma_f32 v[68:69], v[198:199], s[62:63], v[68:69] op_sel_hi:[1,0,1]
	v_pk_fma_f32 v[54:55], v[196:197], s[64:65], v[54:55] op_sel_hi:[1,0,1]
	v_pk_fma_f32 v[52:53], v[198:199], s[64:65], v[52:53] op_sel_hi:[1,0,1]
	s_waitcnt vmcnt(6)
	v_readlane_b32 s50, v81, 28
	v_readlane_b32 s52, v80, 28
	v_readlane_b32 s54, v79, 28
	v_readlane_b32 s56, v82, 28
	v_readlane_b32 s58, v78, 28
	v_readlane_b32 s60, v76, 28
	v_readlane_b32 s62, v19, 28
	v_readlane_b32 s64, v77, 28
	v_pk_fma_f32 v[74:75], v[200:201], s[50:51], v[74:75] op_sel_hi:[1,0,1]
	v_pk_fma_f32 v[14:15], v[202:203], s[50:51], v[14:15] op_sel_hi:[1,0,1]
	v_pk_fma_f32 v[66:67], v[200:201], s[52:53], v[66:67] op_sel_hi:[1,0,1]
	v_pk_fma_f32 v[64:65], v[202:203], s[52:53], v[64:65] op_sel_hi:[1,0,1]
	v_pk_fma_f32 v[58:59], v[200:201], s[54:55], v[58:59] op_sel_hi:[1,0,1]
	v_pk_fma_f32 v[56:57], v[202:203], s[54:55], v[56:57] op_sel_hi:[1,0,1]
	v_pk_fma_f32 v[8:9], v[200:201], s[56:57], v[8:9] op_sel_hi:[1,0,1]
	v_pk_fma_f32 v[10:11], v[202:203], s[56:57], v[10:11] op_sel_hi:[1,0,1]
	v_pk_fma_f32 v[4:5], v[204:205], s[58:59], v[4:5] op_sel_hi:[1,0,1]
	v_pk_fma_f32 v[6:7], v[206:207], s[58:59], v[6:7] op_sel_hi:[1,0,1]
	v_pk_fma_f32 v[62:63], v[204:205], s[60:61], v[62:63] op_sel_hi:[1,0,1]
	v_pk_fma_f32 v[60:61], v[206:207], s[60:61], v[60:61] op_sel_hi:[1,0,1]
	v_pk_fma_f32 v[70:71], v[204:205], s[62:63], v[70:71] op_sel_hi:[1,0,1]
	v_pk_fma_f32 v[68:69], v[206:207], s[62:63], v[68:69] op_sel_hi:[1,0,1]
	v_pk_fma_f32 v[54:55], v[204:205], s[64:65], v[54:55] op_sel_hi:[1,0,1]
	v_pk_fma_f32 v[52:53], v[206:207], s[64:65], v[52:53] op_sel_hi:[1,0,1]
	s_waitcnt vmcnt(4)
	v_readlane_b32 s50, v81, 29
	v_readlane_b32 s52, v80, 29
	v_readlane_b32 s54, v79, 29
	v_readlane_b32 s56, v82, 29
	v_readlane_b32 s58, v78, 29
	v_readlane_b32 s60, v76, 29
	v_readlane_b32 s62, v19, 29
	v_readlane_b32 s64, v77, 29
	v_pk_fma_f32 v[74:75], v[208:209], s[50:51], v[74:75] op_sel_hi:[1,0,1]
	v_pk_fma_f32 v[14:15], v[210:211], s[50:51], v[14:15] op_sel_hi:[1,0,1]
	v_pk_fma_f32 v[66:67], v[208:209], s[52:53], v[66:67] op_sel_hi:[1,0,1]
	v_pk_fma_f32 v[64:65], v[210:211], s[52:53], v[64:65] op_sel_hi:[1,0,1]
	v_pk_fma_f32 v[58:59], v[208:209], s[54:55], v[58:59] op_sel_hi:[1,0,1]
	v_pk_fma_f32 v[56:57], v[210:211], s[54:55], v[56:57] op_sel_hi:[1,0,1]
	v_pk_fma_f32 v[8:9], v[208:209], s[56:57], v[8:9] op_sel_hi:[1,0,1]
	v_pk_fma_f32 v[10:11], v[210:211], s[56:57], v[10:11] op_sel_hi:[1,0,1]
	v_pk_fma_f32 v[4:5], v[212:213], s[58:59], v[4:5] op_sel_hi:[1,0,1]
	v_pk_fma_f32 v[6:7], v[214:215], s[58:59], v[6:7] op_sel_hi:[1,0,1]
	v_pk_fma_f32 v[62:63], v[212:213], s[60:61], v[62:63] op_sel_hi:[1,0,1]
	v_pk_fma_f32 v[60:61], v[214:215], s[60:61], v[60:61] op_sel_hi:[1,0,1]
	v_pk_fma_f32 v[70:71], v[212:213], s[62:63], v[70:71] op_sel_hi:[1,0,1]
	v_pk_fma_f32 v[68:69], v[214:215], s[62:63], v[68:69] op_sel_hi:[1,0,1]
	v_pk_fma_f32 v[54:55], v[212:213], s[64:65], v[54:55] op_sel_hi:[1,0,1]
	v_pk_fma_f32 v[52:53], v[214:215], s[64:65], v[52:53] op_sel_hi:[1,0,1]
	s_waitcnt vmcnt(2)
	v_readlane_b32 s50, v81, 30
	v_readlane_b32 s52, v80, 30
	v_readlane_b32 s54, v79, 30
	v_readlane_b32 s56, v82, 30
	v_readlane_b32 s58, v78, 30
	v_readlane_b32 s60, v76, 30
	v_readlane_b32 s62, v19, 30
	v_readlane_b32 s64, v77, 30
	v_pk_fma_f32 v[74:75], v[216:217], s[50:51], v[74:75] op_sel_hi:[1,0,1]
	v_pk_fma_f32 v[14:15], v[218:219], s[50:51], v[14:15] op_sel_hi:[1,0,1]
	v_pk_fma_f32 v[66:67], v[216:217], s[52:53], v[66:67] op_sel_hi:[1,0,1]
	v_pk_fma_f32 v[64:65], v[218:219], s[52:53], v[64:65] op_sel_hi:[1,0,1]
	v_pk_fma_f32 v[58:59], v[216:217], s[54:55], v[58:59] op_sel_hi:[1,0,1]
	v_pk_fma_f32 v[56:57], v[218:219], s[54:55], v[56:57] op_sel_hi:[1,0,1]
	v_pk_fma_f32 v[8:9], v[216:217], s[56:57], v[8:9] op_sel_hi:[1,0,1]
	v_pk_fma_f32 v[10:11], v[218:219], s[56:57], v[10:11] op_sel_hi:[1,0,1]
	v_pk_fma_f32 v[4:5], v[220:221], s[58:59], v[4:5] op_sel_hi:[1,0,1]
	v_pk_fma_f32 v[6:7], v[222:223], s[58:59], v[6:7] op_sel_hi:[1,0,1]
	v_pk_fma_f32 v[62:63], v[220:221], s[60:61], v[62:63] op_sel_hi:[1,0,1]
	v_pk_fma_f32 v[60:61], v[222:223], s[60:61], v[60:61] op_sel_hi:[1,0,1]
	v_pk_fma_f32 v[70:71], v[220:221], s[62:63], v[70:71] op_sel_hi:[1,0,1]
	v_pk_fma_f32 v[68:69], v[222:223], s[62:63], v[68:69] op_sel_hi:[1,0,1]
	v_pk_fma_f32 v[54:55], v[220:221], s[64:65], v[54:55] op_sel_hi:[1,0,1]
	v_pk_fma_f32 v[52:53], v[222:223], s[64:65], v[52:53] op_sel_hi:[1,0,1]
	s_waitcnt vmcnt(0)
	v_readlane_b32 s50, v81, 31
	v_readlane_b32 s52, v80, 31
	v_readlane_b32 s54, v79, 31
	v_readlane_b32 s56, v82, 31
	v_readlane_b32 s58, v78, 31
	v_readlane_b32 s60, v76, 31
	v_readlane_b32 s62, v19, 31
	v_readlane_b32 s64, v77, 31
	v_pk_fma_f32 v[74:75], v[224:225], s[50:51], v[74:75] op_sel_hi:[1,0,1]
	v_pk_fma_f32 v[14:15], v[226:227], s[50:51], v[14:15] op_sel_hi:[1,0,1]
	v_pk_fma_f32 v[66:67], v[224:225], s[52:53], v[66:67] op_sel_hi:[1,0,1]
	v_pk_fma_f32 v[64:65], v[226:227], s[52:53], v[64:65] op_sel_hi:[1,0,1]
	v_pk_fma_f32 v[58:59], v[224:225], s[54:55], v[58:59] op_sel_hi:[1,0,1]
	v_pk_fma_f32 v[56:57], v[226:227], s[54:55], v[56:57] op_sel_hi:[1,0,1]
	v_pk_fma_f32 v[8:9], v[224:225], s[56:57], v[8:9] op_sel_hi:[1,0,1]
	v_pk_fma_f32 v[10:11], v[226:227], s[56:57], v[10:11] op_sel_hi:[1,0,1]
	v_pk_fma_f32 v[4:5], v[228:229], s[58:59], v[4:5] op_sel_hi:[1,0,1]
	v_pk_fma_f32 v[6:7], v[230:231], s[58:59], v[6:7] op_sel_hi:[1,0,1]
	v_pk_fma_f32 v[62:63], v[228:229], s[60:61], v[62:63] op_sel_hi:[1,0,1]
	v_pk_fma_f32 v[60:61], v[230:231], s[60:61], v[60:61] op_sel_hi:[1,0,1]
	v_pk_fma_f32 v[70:71], v[228:229], s[62:63], v[70:71] op_sel_hi:[1,0,1]
	v_pk_fma_f32 v[68:69], v[230:231], s[62:63], v[68:69] op_sel_hi:[1,0,1]
	v_pk_fma_f32 v[54:55], v[228:229], s[64:65], v[54:55] op_sel_hi:[1,0,1]
	v_pk_fma_f32 v[52:53], v[230:231], s[64:65], v[52:53] op_sel_hi:[1,0,1]
	v_mul_f32_e32 v12, 0xbfb8aa3b, v74
	v_exp_f32_e32 v12, v12
	v_mul_f32_e32 v14, 0xbfb8aa3b, v14
	v_exp_f32_e32 v14, v14
	v_mul_f32_e32 v15, 0xbfb8aa3b, v15
	v_add_f32_e32 v12, 1.0, v12
	v_div_scale_f32 v13, s[22:23], v12, v12, 1.0
	v_rcp_f32_e32 v72, v13
	v_add_f32_e32 v14, 1.0, v14
	v_exp_f32_e32 v15, v15
	v_mul_f32_e32 v70, 0xbfb8aa3b, v70
	v_fma_f32 v73, -v13, v72, 1.0
	v_fmac_f32_e32 v72, v73, v72
	v_div_scale_f32 v73, vcc, 1.0, v12, 1.0
	v_mul_f32_e32 v74, v73, v72
	v_fma_f32 v83, -v13, v74, v73
	v_fmac_f32_e32 v74, v83, v72
	v_fma_f32 v13, -v13, v74, v73
	v_div_fmas_f32 v13, v13, v72, v74
	v_div_fixup_f32 v12, v13, v12, 1.0
	v_mul_f32_e32 v13, 0xbfb8aa3b, v75
	v_exp_f32_e32 v13, v13
	v_add_f32_e32 v15, 1.0, v15
	v_mul_f32_e32 v12, 0xbf1b4598, v12
	v_mul_f32_e32 v12, 0x3fb8aa3b, v12
	v_add_f32_e32 v13, 1.0, v13
	v_div_scale_f32 v72, s[22:23], v13, v13, 1.0
	v_rcp_f32_e32 v73, v72
	v_mul_f32_e32 v71, 0xbfb8aa3b, v71
	v_exp_f32_e32 v12, v12
	v_exp_f32_e32 v70, v70
	v_fma_f32 v74, -v72, v73, 1.0
	v_fmac_f32_e32 v73, v74, v73
	v_div_scale_f32 v74, vcc, 1.0, v13, 1.0
	v_mul_f32_e32 v75, v74, v73
	v_fma_f32 v83, -v72, v75, v74
	v_fmac_f32_e32 v75, v83, v73
	v_fma_f32 v72, -v72, v75, v74
	v_div_fmas_f32 v72, v72, v73, v75
	v_div_fixup_f32 v13, v72, v13, 1.0
	v_div_scale_f32 v72, s[22:23], v14, v14, 1.0
	v_rcp_f32_e32 v73, v72
	v_mul_f32_e32 v13, 0xbf1b4598, v13
	v_mul_f32_e32 v13, 0x3fb8aa3b, v13
	v_exp_f32_e32 v13, v13
	v_fma_f32 v74, -v72, v73, 1.0
	v_fmac_f32_e32 v73, v74, v73
	v_div_scale_f32 v74, vcc, 1.0, v14, 1.0
	v_mul_f32_e32 v75, v74, v73
	v_fma_f32 v83, -v72, v75, v74
	v_fmac_f32_e32 v75, v83, v73
	v_fma_f32 v72, -v72, v75, v74
	v_div_fmas_f32 v72, v72, v73, v75
	v_div_fixup_f32 v14, v72, v14, 1.0
	v_div_scale_f32 v72, s[22:23], v15, v15, 1.0
	v_rcp_f32_e32 v73, v72
	v_mul_f32_e32 v14, 0xbf1b4598, v14
	v_mul_f32_e32 v14, 0x3fb8aa3b, v14
	v_exp_f32_e32 v14, v14
	v_fma_f32 v74, -v72, v73, 1.0
	v_fmac_f32_e32 v73, v74, v73
	v_div_scale_f32 v74, vcc, 1.0, v15, 1.0
	v_mul_f32_e32 v75, v74, v73
	v_fma_f32 v83, -v72, v75, v74
	v_fmac_f32_e32 v75, v83, v73
	v_fma_f32 v72, -v72, v75, v74
	v_div_fmas_f32 v72, v72, v73, v75
	v_div_fixup_f32 v15, v72, v15, 1.0
	v_mul_f32_e32 v15, 0xbf1b4598, v15
	v_mul_f32_e32 v15, 0x3fb8aa3b, v15
	v_exp_f32_e32 v15, v15
	v_exp_f32_e32 v71, v71
	v_mul_f32_e32 v68, 0xbfb8aa3b, v68
	v_mul_f32_e32 v69, 0xbfb8aa3b, v69
	global_store_dwordx4 v[50:51], v[12:15], off offset:1024
	v_exp_f32_e32 v68, v68
	v_exp_f32_e32 v69, v69
	v_pk_add_f32 v[12:13], v[70:71], 1.0 op_sel_hi:[1,0]
	v_mul_f32_e32 v62, 0xbfb8aa3b, v62
	v_div_scale_f32 v14, s[22:23], v13, v13, 1.0
	v_rcp_f32_e32 v15, v14
	v_mul_f32_e32 v63, 0xbfb8aa3b, v63
	v_exp_f32_e32 v62, v62
	v_exp_f32_e32 v63, v63
	v_fma_f32 v70, -v14, v15, 1.0
	v_fmac_f32_e32 v15, v70, v15
	v_div_scale_f32 v70, vcc, 1.0, v13, 1.0
	v_mul_f32_e32 v71, v70, v15
	v_fma_f32 v72, -v14, v71, v70
	v_fmac_f32_e32 v71, v72, v15
	v_fma_f32 v14, -v14, v71, v70
	v_div_fmas_f32 v14, v14, v15, v71
	v_div_fixup_f32 v13, v14, v13, 1.0
	v_div_scale_f32 v14, s[22:23], v12, v12, 1.0
	v_rcp_f32_e32 v15, v14
	v_mul_f32_e32 v60, 0xbfb8aa3b, v60
	v_mul_f32_e32 v61, 0xbfb8aa3b, v61
	v_exp_f32_e32 v60, v60
	v_fma_f32 v70, -v14, v15, 1.0
	v_fmac_f32_e32 v15, v70, v15
	v_div_scale_f32 v70, vcc, 1.0, v12, 1.0
	v_mul_f32_e32 v71, v70, v15
	v_fma_f32 v72, -v14, v71, v70
	v_fmac_f32_e32 v71, v72, v15
	v_fma_f32 v14, -v14, v71, v70
	v_div_fmas_f32 v14, v14, v15, v71
	v_div_fixup_f32 v12, v14, v12, 1.0
	v_pk_add_f32 v[14:15], v[68:69], 1.0 op_sel_hi:[1,0]
	v_exp_f32_e32 v61, v61
	v_div_scale_f32 v68, s[22:23], v15, v15, 1.0
	v_rcp_f32_e32 v69, v68
	v_mul_f32_e32 v54, 0xbfb8aa3b, v54
	v_mul_f32_e32 v55, 0xbfb8aa3b, v55
	v_exp_f32_e32 v54, v54
	v_fma_f32 v70, -v68, v69, 1.0
	v_fmac_f32_e32 v69, v70, v69
	v_div_scale_f32 v70, vcc, 1.0, v15, 1.0
	v_mul_f32_e32 v71, v70, v69
	v_fma_f32 v72, -v68, v71, v70
	v_fmac_f32_e32 v71, v72, v69
	v_fma_f32 v68, -v68, v71, v70
	v_div_fmas_f32 v68, v68, v69, v71
	v_div_fixup_f32 v15, v68, v15, 1.0
	v_div_scale_f32 v68, s[22:23], v14, v14, 1.0
	v_rcp_f32_e32 v69, v68
	v_exp_f32_e32 v55, v55
	v_mul_f32_e32 v52, 0xbfb8aa3b, v52
	v_mul_f32_e32 v53, 0xbfb8aa3b, v53
	v_fma_f32 v70, -v68, v69, 1.0
	v_fmac_f32_e32 v69, v70, v69
	v_div_scale_f32 v70, vcc, 1.0, v14, 1.0
	v_mul_f32_e32 v71, v70, v69
	v_fma_f32 v72, -v68, v71, v70
	v_fmac_f32_e32 v71, v72, v69
	v_fma_f32 v68, -v68, v71, v70
	v_div_fmas_f32 v68, v68, v69, v71
	v_div_fixup_f32 v14, v68, v14, 1.0
	global_store_dwordx4 v[50:51], v[12:15], off offset:2048
	v_exp_f32_e32 v52, v52
	v_exp_f32_e32 v53, v53
	v_mul_f32_e32 v12, 0xbfb8aa3b, v66
	v_exp_f32_e32 v12, v12
	v_mul_f32_e32 v8, 0xbfb8aa3b, v8
	v_exp_f32_e32 v8, v8
	v_mul_f32_e32 v9, 0xbfb8aa3b, v9
	v_add_f32_e32 v12, 1.0, v12
	v_div_scale_f32 v13, s[22:23], v12, v12, 1.0
	v_rcp_f32_e32 v14, v13
	v_add_f32_e32 v8, 1.0, v8
	v_exp_f32_e32 v9, v9
	v_mul_f32_e32 v10, 0xbfb8aa3b, v10
	v_fma_f32 v15, -v13, v14, 1.0
	v_fmac_f32_e32 v14, v15, v14
	v_div_scale_f32 v15, vcc, 1.0, v12, 1.0
	v_mul_f32_e32 v66, v15, v14
	v_fma_f32 v68, -v13, v66, v15
	v_fmac_f32_e32 v66, v68, v14
	v_fma_f32 v13, -v13, v66, v15
	v_div_fmas_f32 v13, v13, v14, v66
	v_div_fixup_f32 v12, v13, v12, 1.0
	v_mul_f32_e32 v13, 0xbfb8aa3b, v67
	v_exp_f32_e32 v13, v13
	v_mul_f32_e32 v12, 0xbf1b4598, v12
	v_mul_f32_e32 v12, 0x3fb8aa3b, v12
	v_exp_f32_e32 v12, v12
	v_add_f32_e32 v13, 1.0, v13
	v_div_scale_f32 v14, s[22:23], v13, v13, 1.0
	v_rcp_f32_e32 v15, v14
	v_add_f32_e32 v9, 1.0, v9
	v_exp_f32_e32 v10, v10
	v_mul_f32_e32 v11, 0xbfb8aa3b, v11
	v_fma_f32 v66, -v14, v15, 1.0
	v_fmac_f32_e32 v15, v66, v15
	v_div_scale_f32 v66, vcc, 1.0, v13, 1.0
	v_mul_f32_e32 v67, v66, v15
	v_fma_f32 v68, -v14, v67, v66
	v_fmac_f32_e32 v67, v68, v15
	v_fma_f32 v14, -v14, v67, v66
	v_div_fmas_f32 v14, v14, v15, v67
	v_div_fixup_f32 v13, v14, v13, 1.0
	v_mul_f32_e32 v14, 0xbfb8aa3b, v64
	v_exp_f32_e32 v14, v14
	v_mul_f32_e32 v13, 0xbf1b4598, v13
	v_mul_f32_e32 v13, 0x3fb8aa3b, v13
	v_exp_f32_e32 v13, v13
	v_add_f32_e32 v14, 1.0, v14
	v_div_scale_f32 v15, s[22:23], v14, v14, 1.0
	v_rcp_f32_e32 v64, v15
	v_add_f32_e32 v10, 1.0, v10
	v_exp_f32_e32 v11, v11
	v_mul_f32_e32 v4, 0xbfb8aa3b, v4
	v_fma_f32 v66, -v15, v64, 1.0
	v_fmac_f32_e32 v64, v66, v64
	v_div_scale_f32 v66, vcc, 1.0, v14, 1.0
	v_mul_f32_e32 v67, v66, v64
	v_fma_f32 v68, -v15, v67, v66
	v_fmac_f32_e32 v67, v68, v64
	v_fma_f32 v15, -v15, v67, v66
	v_div_fmas_f32 v15, v15, v64, v67
	v_div_fixup_f32 v14, v15, v14, 1.0
	v_mul_f32_e32 v15, 0xbfb8aa3b, v65
	v_exp_f32_e32 v15, v15
	v_mul_f32_e32 v14, 0xbf1b4598, v14
	v_mul_f32_e32 v14, 0x3fb8aa3b, v14
	v_exp_f32_e32 v14, v14
	v_add_f32_e32 v15, 1.0, v15
	v_div_scale_f32 v64, s[22:23], v15, v15, 1.0
	v_rcp_f32_e32 v65, v64
	v_add_f32_e32 v11, 1.0, v11
	v_mul_f32_e32 v5, 0xbfb8aa3b, v5
	v_exp_f32_e32 v4, v4
	v_fma_f32 v66, -v64, v65, 1.0
	v_fmac_f32_e32 v65, v66, v65
	v_div_scale_f32 v66, vcc, 1.0, v15, 1.0
	v_mul_f32_e32 v67, v66, v65
	v_fma_f32 v68, -v64, v67, v66
	v_fmac_f32_e32 v67, v68, v65
	v_fma_f32 v64, -v64, v67, v66
	v_div_fmas_f32 v64, v64, v65, v67
	v_div_fixup_f32 v15, v64, v15, 1.0
	v_mul_f32_e32 v15, 0xbf1b4598, v15
	v_mul_f32_e32 v15, 0x3fb8aa3b, v15
	v_exp_f32_e32 v15, v15
	v_exp_f32_e32 v5, v5
	v_mul_f32_e32 v6, 0xbfb8aa3b, v6
	v_mul_f32_e32 v7, 0xbfb8aa3b, v7
	global_store_dwordx4 v[46:47], v[12:15], off offset:1024
	v_pk_add_f32 v[4:5], v[4:5], 1.0 op_sel_hi:[1,0]
	v_exp_f32_e32 v6, v6
	v_pk_add_f32 v[12:13], v[62:63], 1.0 op_sel_hi:[1,0]
	v_exp_f32_e32 v7, v7
	v_div_scale_f32 v14, s[22:23], v13, v13, 1.0
	v_rcp_f32_e32 v15, v14
	v_pk_add_f32 v[6:7], v[6:7], 1.0 op_sel_hi:[1,0]
	s_mov_b32 s25, 33
	v_fma_f32 v62, -v14, v15, 1.0
	v_fmac_f32_e32 v15, v62, v15
	v_div_scale_f32 v62, vcc, 1.0, v13, 1.0
	v_mul_f32_e32 v63, v62, v15
	v_fma_f32 v64, -v14, v63, v62
	v_fmac_f32_e32 v63, v64, v15
	v_fma_f32 v14, -v14, v63, v62
	v_div_fmas_f32 v14, v14, v15, v63
	v_div_fixup_f32 v13, v14, v13, 1.0
	v_div_scale_f32 v14, s[22:23], v12, v12, 1.0
	v_rcp_f32_e32 v15, v14
	s_nop 0
	v_fma_f32 v62, -v14, v15, 1.0
	v_fmac_f32_e32 v15, v62, v15
	v_div_scale_f32 v62, vcc, 1.0, v12, 1.0
	v_mul_f32_e32 v63, v62, v15
	v_fma_f32 v64, -v14, v63, v62
	v_fmac_f32_e32 v63, v64, v15
	v_fma_f32 v14, -v14, v63, v62
	v_div_fmas_f32 v14, v14, v15, v63
	v_div_fixup_f32 v12, v14, v12, 1.0
	v_pk_add_f32 v[14:15], v[60:61], 1.0 op_sel_hi:[1,0]
	s_nop 0
	v_div_scale_f32 v60, s[22:23], v15, v15, 1.0
	v_rcp_f32_e32 v61, v60
	s_nop 0
	v_fma_f32 v62, -v60, v61, 1.0
	v_fmac_f32_e32 v61, v62, v61
	v_div_scale_f32 v62, vcc, 1.0, v15, 1.0
	v_mul_f32_e32 v63, v62, v61
	v_fma_f32 v64, -v60, v63, v62
	v_fmac_f32_e32 v63, v64, v61
	v_fma_f32 v60, -v60, v63, v62
	v_div_fmas_f32 v60, v60, v61, v63
	v_div_fixup_f32 v15, v60, v15, 1.0
	v_div_scale_f32 v60, s[22:23], v14, v14, 1.0
	v_rcp_f32_e32 v61, v60
	s_nop 0
	v_fma_f32 v62, -v60, v61, 1.0
	v_fmac_f32_e32 v61, v62, v61
	v_div_scale_f32 v62, vcc, 1.0, v14, 1.0
	v_mul_f32_e32 v63, v62, v61
	v_fma_f32 v64, -v60, v63, v62
	v_fmac_f32_e32 v63, v64, v61
	v_fma_f32 v60, -v60, v63, v62
	v_div_fmas_f32 v60, v60, v61, v63
	v_div_fixup_f32 v14, v60, v14, 1.0
	global_store_dwordx4 v[46:47], v[12:15], off offset:2048
	s_nop 1
	v_mul_f32_e32 v12, 0xbfb8aa3b, v58
	v_exp_f32_e32 v12, v12
	s_nop 0
	v_add_f32_e32 v12, 1.0, v12
	v_div_scale_f32 v13, s[22:23], v12, v12, 1.0
	v_rcp_f32_e32 v14, v13
	s_nop 0
	v_fma_f32 v15, -v13, v14, 1.0
	v_fmac_f32_e32 v14, v15, v14
	v_div_scale_f32 v15, vcc, 1.0, v12, 1.0
	v_mul_f32_e32 v58, v15, v14
	v_fma_f32 v60, -v13, v58, v15
	v_fmac_f32_e32 v58, v60, v14
	v_fma_f32 v13, -v13, v58, v15
	v_div_fmas_f32 v13, v13, v14, v58
	v_div_fixup_f32 v12, v13, v12, 1.0
	v_mul_f32_e32 v13, 0xbfb8aa3b, v59
	v_exp_f32_e32 v13, v13
	v_mul_f32_e32 v12, 0xbf1b4598, v12
	v_mul_f32_e32 v12, 0x3fb8aa3b, v12
	v_exp_f32_e32 v12, v12
	v_add_f32_e32 v13, 1.0, v13
	v_div_scale_f32 v14, s[22:23], v13, v13, 1.0
	v_rcp_f32_e32 v15, v14
	s_nop 0
	v_fma_f32 v58, -v14, v15, 1.0
	v_fmac_f32_e32 v15, v58, v15
	v_div_scale_f32 v58, vcc, 1.0, v13, 1.0
	v_mul_f32_e32 v59, v58, v15
	v_fma_f32 v60, -v14, v59, v58
	v_fmac_f32_e32 v59, v60, v15
	v_fma_f32 v14, -v14, v59, v58
	v_div_fmas_f32 v14, v14, v15, v59
	v_div_fixup_f32 v13, v14, v13, 1.0
	v_mul_f32_e32 v14, 0xbfb8aa3b, v56
	v_exp_f32_e32 v14, v14
	v_mul_f32_e32 v13, 0xbf1b4598, v13
	v_mul_f32_e32 v13, 0x3fb8aa3b, v13
	v_exp_f32_e32 v13, v13
	v_add_f32_e32 v14, 1.0, v14
	v_div_scale_f32 v15, s[22:23], v14, v14, 1.0
	v_rcp_f32_e32 v56, v15
	s_nop 0
	v_fma_f32 v58, -v15, v56, 1.0
	v_fmac_f32_e32 v56, v58, v56
	v_div_scale_f32 v58, vcc, 1.0, v14, 1.0
	v_mul_f32_e32 v59, v58, v56
	v_fma_f32 v60, -v15, v59, v58
	v_fmac_f32_e32 v59, v60, v56
	v_fma_f32 v15, -v15, v59, v58
	v_div_fmas_f32 v15, v15, v56, v59
	v_div_fixup_f32 v14, v15, v14, 1.0
	v_mul_f32_e32 v15, 0xbfb8aa3b, v57
	v_exp_f32_e32 v15, v15
	v_mul_f32_e32 v14, 0xbf1b4598, v14
	v_mul_f32_e32 v14, 0x3fb8aa3b, v14
	v_exp_f32_e32 v14, v14
	v_add_f32_e32 v15, 1.0, v15
	v_div_scale_f32 v56, s[22:23], v15, v15, 1.0
	v_rcp_f32_e32 v57, v56
	s_nop 0
	v_fma_f32 v58, -v56, v57, 1.0
	v_fmac_f32_e32 v57, v58, v57
	v_div_scale_f32 v58, vcc, 1.0, v15, 1.0
	v_mul_f32_e32 v59, v58, v57
	v_fma_f32 v60, -v56, v59, v58
	v_fmac_f32_e32 v59, v60, v57
	v_fma_f32 v56, -v56, v59, v58
	v_div_fmas_f32 v56, v56, v57, v59
	v_div_fixup_f32 v15, v56, v15, 1.0
	v_mul_f32_e32 v15, 0xbf1b4598, v15
	v_mul_f32_e32 v15, 0x3fb8aa3b, v15
	v_exp_f32_e32 v15, v15
	global_store_dwordx4 v[42:43], v[12:15], off offset:1024
	s_nop 1
	v_pk_add_f32 v[12:13], v[54:55], 1.0 op_sel_hi:[1,0]
	s_nop 0
	v_div_scale_f32 v14, s[22:23], v13, v13, 1.0
	v_rcp_f32_e32 v15, v14
	s_nop 0
	v_fma_f32 v54, -v14, v15, 1.0
	v_fmac_f32_e32 v15, v54, v15
	v_div_scale_f32 v54, vcc, 1.0, v13, 1.0
	v_mul_f32_e32 v55, v54, v15
	v_fma_f32 v56, -v14, v55, v54
	v_fmac_f32_e32 v55, v56, v15
	v_fma_f32 v14, -v14, v55, v54
	v_div_fmas_f32 v14, v14, v15, v55
	v_div_fixup_f32 v13, v14, v13, 1.0
	v_div_scale_f32 v14, s[22:23], v12, v12, 1.0
	v_rcp_f32_e32 v15, v14
	s_nop 0
	v_fma_f32 v54, -v14, v15, 1.0
	v_fmac_f32_e32 v15, v54, v15
	v_div_scale_f32 v54, vcc, 1.0, v12, 1.0
	v_mul_f32_e32 v55, v54, v15
	v_fma_f32 v56, -v14, v55, v54
	v_fmac_f32_e32 v55, v56, v15
	v_fma_f32 v14, -v14, v55, v54
	v_div_fmas_f32 v14, v14, v15, v55
	v_div_fixup_f32 v12, v14, v12, 1.0
	v_pk_add_f32 v[14:15], v[52:53], 1.0 op_sel_hi:[1,0]
	s_nop 0
	v_div_scale_f32 v52, s[22:23], v15, v15, 1.0
	v_rcp_f32_e32 v53, v52
	s_nop 0
	v_fma_f32 v54, -v52, v53, 1.0
	v_fmac_f32_e32 v53, v54, v53
	v_div_scale_f32 v54, vcc, 1.0, v15, 1.0
	v_mul_f32_e32 v55, v54, v53
	v_fma_f32 v56, -v52, v55, v54
	v_fmac_f32_e32 v55, v56, v53
	v_fma_f32 v52, -v52, v55, v54
	v_div_fmas_f32 v52, v52, v53, v55
	v_div_fixup_f32 v15, v52, v15, 1.0
	v_div_scale_f32 v52, s[22:23], v14, v14, 1.0
	v_rcp_f32_e32 v53, v52
	s_nop 0
	v_fma_f32 v54, -v52, v53, 1.0
	v_fmac_f32_e32 v53, v54, v53
	v_div_scale_f32 v54, vcc, 1.0, v14, 1.0
	v_mul_f32_e32 v55, v54, v53
	v_fma_f32 v56, -v52, v55, v54
	v_fmac_f32_e32 v55, v56, v53
	v_fma_f32 v52, -v52, v55, v54
	v_div_fmas_f32 v52, v52, v53, v55
	v_div_fixup_f32 v14, v52, v14, 1.0
	global_store_dwordx4 v[42:43], v[12:15], off offset:2048
	s_nop 1
	v_div_scale_f32 v12, s[22:23], v8, v8, 1.0
	v_rcp_f32_e32 v13, v12
	s_nop 0
	v_fma_f32 v14, -v12, v13, 1.0
	v_fmac_f32_e32 v13, v14, v13
	v_div_scale_f32 v14, vcc, 1.0, v8, 1.0
	v_mul_f32_e32 v15, v14, v13
	v_fma_f32 v52, -v12, v15, v14
	v_fmac_f32_e32 v15, v52, v13
	v_fma_f32 v12, -v12, v15, v14
	v_div_fmas_f32 v12, v12, v13, v15
	v_div_fixup_f32 v8, v12, v8, 1.0
	v_div_scale_f32 v12, s[22:23], v9, v9, 1.0
	v_rcp_f32_e32 v13, v12
	v_mul_f32_e32 v8, 0xbf1b4598, v8
	v_mul_f32_e32 v8, 0x3fb8aa3b, v8
	v_exp_f32_e32 v8, v8
	v_fma_f32 v14, -v12, v13, 1.0
	v_fmac_f32_e32 v13, v14, v13
	v_div_scale_f32 v14, vcc, 1.0, v9, 1.0
	v_mul_f32_e32 v15, v14, v13
	v_fma_f32 v52, -v12, v15, v14
	v_fmac_f32_e32 v15, v52, v13
	v_fma_f32 v12, -v12, v15, v14
	v_div_fmas_f32 v12, v12, v13, v15
	v_div_fixup_f32 v9, v12, v9, 1.0
	v_div_scale_f32 v12, s[22:23], v10, v10, 1.0
	v_rcp_f32_e32 v13, v12
	v_mul_f32_e32 v9, 0xbf1b4598, v9
	v_mul_f32_e32 v9, 0x3fb8aa3b, v9
	v_exp_f32_e32 v9, v9
	v_fma_f32 v14, -v12, v13, 1.0
	v_fmac_f32_e32 v13, v14, v13
	v_div_scale_f32 v14, vcc, 1.0, v10, 1.0
	v_mul_f32_e32 v15, v14, v13
	v_fma_f32 v52, -v12, v15, v14
	v_fmac_f32_e32 v15, v52, v13
	v_fma_f32 v12, -v12, v15, v14
	v_div_fmas_f32 v12, v12, v13, v15
	v_div_fixup_f32 v10, v12, v10, 1.0
	v_div_scale_f32 v12, s[22:23], v11, v11, 1.0
	v_rcp_f32_e32 v13, v12
	v_mul_f32_e32 v10, 0xbf1b4598, v10
	v_mul_f32_e32 v10, 0x3fb8aa3b, v10
	v_exp_f32_e32 v10, v10
	v_fma_f32 v14, -v12, v13, 1.0
	v_fmac_f32_e32 v13, v14, v13
	v_div_scale_f32 v14, vcc, 1.0, v11, 1.0
	v_mul_f32_e32 v15, v14, v13
	v_fma_f32 v52, -v12, v15, v14
	v_fmac_f32_e32 v15, v52, v13
	v_fma_f32 v12, -v12, v15, v14
	v_div_fmas_f32 v12, v12, v13, v15
	v_div_fixup_f32 v11, v12, v11, 1.0
	v_mul_f32_e32 v11, 0xbf1b4598, v11
	v_mul_f32_e32 v11, 0x3fb8aa3b, v11
	v_exp_f32_e32 v11, v11
	global_store_dwordx4 v[38:39], v[8:11], off offset:1024
	s_nop 1
	v_div_scale_f32 v8, s[22:23], v5, v5, 1.0
	v_rcp_f32_e32 v9, v8
	s_nop 0
	v_fma_f32 v10, -v8, v9, 1.0
	v_fmac_f32_e32 v9, v10, v9
	v_div_scale_f32 v10, vcc, 1.0, v5, 1.0
	v_mul_f32_e32 v11, v10, v9
	v_fma_f32 v12, -v8, v11, v10
	v_fmac_f32_e32 v11, v12, v9
	v_fma_f32 v8, -v8, v11, v10
	v_div_fmas_f32 v8, v8, v9, v11
	v_div_fixup_f32 v5, v8, v5, 1.0
	v_div_scale_f32 v8, s[22:23], v4, v4, 1.0
	v_rcp_f32_e32 v9, v8
	s_nop 0
	v_fma_f32 v10, -v8, v9, 1.0
	v_fmac_f32_e32 v9, v10, v9
	v_div_scale_f32 v10, vcc, 1.0, v4, 1.0
	v_mul_f32_e32 v11, v10, v9
	v_fma_f32 v12, -v8, v11, v10
	v_fmac_f32_e32 v11, v12, v9
	v_fma_f32 v8, -v8, v11, v10
	v_div_fmas_f32 v8, v8, v9, v11
	v_div_fixup_f32 v4, v8, v4, 1.0
	v_div_scale_f32 v8, s[22:23], v7, v7, 1.0
	v_rcp_f32_e32 v9, v8
	s_nop 0
	v_fma_f32 v10, -v8, v9, 1.0
	v_fmac_f32_e32 v9, v10, v9
	v_div_scale_f32 v10, vcc, 1.0, v7, 1.0
	v_mul_f32_e32 v11, v10, v9
	v_fma_f32 v12, -v8, v11, v10
	v_fmac_f32_e32 v11, v12, v9
	v_fma_f32 v8, -v8, v11, v10
	v_div_fmas_f32 v8, v8, v9, v11
	v_div_fixup_f32 v7, v8, v7, 1.0
	v_div_scale_f32 v8, s[22:23], v6, v6, 1.0
	v_rcp_f32_e32 v9, v8
	s_mov_b64 s[22:23], 0
	v_fma_f32 v10, -v8, v9, 1.0
	v_fmac_f32_e32 v9, v10, v9
	v_div_scale_f32 v10, vcc, 1.0, v6, 1.0
	v_mul_f32_e32 v11, v10, v9
	v_fma_f32 v12, -v8, v11, v10
	v_fmac_f32_e32 v11, v12, v9
	v_fma_f32 v8, -v8, v11, v10
	v_div_fmas_f32 v8, v8, v9, v11
	v_div_fixup_f32 v6, v8, v6, 1.0
	global_store_dwordx4 v[38:39], v[4:7], off offset:2048
	global_load_dwordx4 v[8:11], v[24:25], off
	s_nop 0
	global_load_dwordx4 v[4:7], v[26:27], off
	s_waitcnt vmcnt(1)
	v_mov_b32_e32 v54, v8
	v_mov_b32_e32 v55, v9
	v_mov_b32_e32 v52, v10
	v_mov_b32_e32 v53, v11
	v_mov_b32_e32 v62, v8
	v_mov_b32_e32 v63, v9
	v_mov_b32_e32 v60, v10
	v_mov_b32_e32 v61, v11
	v_mov_b32_e32 v70, v8
	v_mov_b32_e32 v71, v9
	v_mov_b32_e32 v68, v10
	v_mov_b32_e32 v69, v11
	s_waitcnt vmcnt(0)
	v_mov_b32_e32 v14, v4
	v_mov_b32_e32 v15, v5
	v_mov_b32_e32 v12, v6
	v_mov_b32_e32 v13, v7
	v_mov_b32_e32 v58, v4
	v_mov_b32_e32 v59, v5
	v_mov_b32_e32 v56, v6
	v_mov_b32_e32 v57, v7
	v_mov_b32_e32 v66, v4
	v_mov_b32_e32 v67, v5
	v_mov_b32_e32 v64, v6
	v_mov_b32_e32 v65, v7
.LBB0_545:
	s_mov_b32 s66, 0x1000
	s_mov_b32 s67, 0
	v_add_co_u32_e32 v232, vcc, s93, v32
	s_nop 1
	v_addc_co_u32_e32 v233, vcc, 0, v33, vcc
	v_add_co_u32_e32 v234, vcc, s93, v34
	s_nop 1
	v_addc_co_u32_e32 v235, vcc, 0, v35, vcc
	global_load_dwordx4 v[168:171], v[232:233], off offset:0
	global_load_dwordx4 v[172:175], v[234:235], off offset:0
	global_load_dwordx4 v[176:179], v[232:233], off offset:1024
	global_load_dwordx4 v[180:183], v[234:235], off offset:1024
	global_load_dwordx4 v[184:187], v[232:233], off offset:2048
	global_load_dwordx4 v[188:191], v[234:235], off offset:2048
	global_load_dwordx4 v[192:195], v[232:233], off offset:3072
	global_load_dwordx4 v[196:199], v[234:235], off offset:3072
	v_lshl_add_u64 v[232:233], v[232:233], 0, s[66:67]
	v_lshl_add_u64 v[234:235], v[234:235], 0, s[66:67]
	global_load_dwordx4 v[200:203], v[232:233], off offset:0
	global_load_dwordx4 v[204:207], v[234:235], off offset:0
	global_load_dwordx4 v[208:211], v[232:233], off offset:1024
	global_load_dwordx4 v[212:215], v[234:235], off offset:1024
	global_load_dwordx4 v[216:219], v[232:233], off offset:2048
	global_load_dwordx4 v[220:223], v[234:235], off offset:2048
	s_waitcnt vmcnt(12)
	v_readlane_b32 s50, v81, 32
	v_readlane_b32 s52, v80, 32
	v_readlane_b32 s54, v79, 32
	v_readlane_b32 s56, v82, 32
	v_readlane_b32 s58, v78, 32
	v_readlane_b32 s60, v19, 32
	v_readlane_b32 s62, v76, 32
	v_readlane_b32 s64, v77, 32
	v_pk_fma_f32 v[70:71], v[168:169], s[50:51], v[70:71] op_sel_hi:[1,0,1]
	v_pk_fma_f32 v[68:69], v[170:171], s[50:51], v[68:69] op_sel_hi:[1,0,1]
	v_pk_fma_f32 v[62:63], v[168:169], s[52:53], v[62:63] op_sel_hi:[1,0,1]
	v_pk_fma_f32 v[60:61], v[170:171], s[52:53], v[60:61] op_sel_hi:[1,0,1]
	v_pk_fma_f32 v[54:55], v[168:169], s[54:55], v[54:55] op_sel_hi:[1,0,1]
	v_pk_fma_f32 v[52:53], v[170:171], s[54:55], v[52:53] op_sel_hi:[1,0,1]
	v_pk_fma_f32 v[8:9], v[168:169], s[56:57], v[8:9] op_sel_hi:[1,0,1]
	v_pk_fma_f32 v[10:11], v[170:171], s[56:57], v[10:11] op_sel_hi:[1,0,1]
	v_pk_fma_f32 v[4:5], v[172:173], s[58:59], v[4:5] op_sel_hi:[1,0,1]
	v_pk_fma_f32 v[6:7], v[174:175], s[58:59], v[6:7] op_sel_hi:[1,0,1]
	v_pk_fma_f32 v[66:67], v[172:173], s[60:61], v[66:67] op_sel_hi:[1,0,1]
	v_pk_fma_f32 v[64:65], v[174:175], s[60:61], v[64:65] op_sel_hi:[1,0,1]
	v_pk_fma_f32 v[58:59], v[172:173], s[62:63], v[58:59] op_sel_hi:[1,0,1]
	v_pk_fma_f32 v[56:57], v[174:175], s[62:63], v[56:57] op_sel_hi:[1,0,1]
	v_pk_fma_f32 v[14:15], v[172:173], s[64:65], v[14:15] op_sel_hi:[1,0,1]
	v_pk_fma_f32 v[12:13], v[174:175], s[64:65], v[12:13] op_sel_hi:[1,0,1]
	global_load_dwordx4 v[224:227], v[232:233], off offset:3072
	global_load_dwordx4 v[228:231], v[234:235], off offset:3072
	v_lshl_add_u64 v[232:233], v[232:233], 0, s[66:67]
	v_lshl_add_u64 v[234:235], v[234:235], 0, s[66:67]
	s_waitcnt vmcnt(12)
	v_readlane_b32 s50, v81, 33
	v_readlane_b32 s52, v80, 33
	v_readlane_b32 s54, v79, 33
	v_readlane_b32 s56, v82, 33
	v_readlane_b32 s58, v78, 33
	v_readlane_b32 s60, v19, 33
	v_readlane_b32 s62, v76, 33
	v_readlane_b32 s64, v77, 33
	v_pk_fma_f32 v[70:71], v[176:177], s[50:51], v[70:71] op_sel_hi:[1,0,1]
	v_pk_fma_f32 v[68:69], v[178:179], s[50:51], v[68:69] op_sel_hi:[1,0,1]
	v_pk_fma_f32 v[62:63], v[176:177], s[52:53], v[62:63] op_sel_hi:[1,0,1]
	v_pk_fma_f32 v[60:61], v[178:179], s[52:53], v[60:61] op_sel_hi:[1,0,1]
	v_pk_fma_f32 v[54:55], v[176:177], s[54:55], v[54:55] op_sel_hi:[1,0,1]
	v_pk_fma_f32 v[52:53], v[178:179], s[54:55], v[52:53] op_sel_hi:[1,0,1]
	v_pk_fma_f32 v[8:9], v[176:177], s[56:57], v[8:9] op_sel_hi:[1,0,1]
	v_pk_fma_f32 v[10:11], v[178:179], s[56:57], v[10:11] op_sel_hi:[1,0,1]
	v_pk_fma_f32 v[4:5], v[180:181], s[58:59], v[4:5] op_sel_hi:[1,0,1]
	v_pk_fma_f32 v[6:7], v[182:183], s[58:59], v[6:7] op_sel_hi:[1,0,1]
	v_pk_fma_f32 v[66:67], v[180:181], s[60:61], v[66:67] op_sel_hi:[1,0,1]
	v_pk_fma_f32 v[64:65], v[182:183], s[60:61], v[64:65] op_sel_hi:[1,0,1]
	v_pk_fma_f32 v[58:59], v[180:181], s[62:63], v[58:59] op_sel_hi:[1,0,1]
	v_pk_fma_f32 v[56:57], v[182:183], s[62:63], v[56:57] op_sel_hi:[1,0,1]
	v_pk_fma_f32 v[14:15], v[180:181], s[64:65], v[14:15] op_sel_hi:[1,0,1]
	v_pk_fma_f32 v[12:13], v[182:183], s[64:65], v[12:13] op_sel_hi:[1,0,1]
	global_load_dwordx4 v[168:171], v[232:233], off offset:0
	global_load_dwordx4 v[172:175], v[234:235], off offset:0
	s_waitcnt vmcnt(12)
	v_readlane_b32 s50, v81, 34
	v_readlane_b32 s52, v80, 34
	v_readlane_b32 s54, v79, 34
	v_readlane_b32 s56, v82, 34
	v_readlane_b32 s58, v78, 34
	v_readlane_b32 s60, v19, 34
	v_readlane_b32 s62, v76, 34
	v_readlane_b32 s64, v77, 34
	v_pk_fma_f32 v[70:71], v[184:185], s[50:51], v[70:71] op_sel_hi:[1,0,1]
	v_pk_fma_f32 v[68:69], v[186:187], s[50:51], v[68:69] op_sel_hi:[1,0,1]
	v_pk_fma_f32 v[62:63], v[184:185], s[52:53], v[62:63] op_sel_hi:[1,0,1]
	v_pk_fma_f32 v[60:61], v[186:187], s[52:53], v[60:61] op_sel_hi:[1,0,1]
	v_pk_fma_f32 v[54:55], v[184:185], s[54:55], v[54:55] op_sel_hi:[1,0,1]
	v_pk_fma_f32 v[52:53], v[186:187], s[54:55], v[52:53] op_sel_hi:[1,0,1]
	v_pk_fma_f32 v[8:9], v[184:185], s[56:57], v[8:9] op_sel_hi:[1,0,1]
	v_pk_fma_f32 v[10:11], v[186:187], s[56:57], v[10:11] op_sel_hi:[1,0,1]
	v_pk_fma_f32 v[4:5], v[188:189], s[58:59], v[4:5] op_sel_hi:[1,0,1]
	v_pk_fma_f32 v[6:7], v[190:191], s[58:59], v[6:7] op_sel_hi:[1,0,1]
	v_pk_fma_f32 v[66:67], v[188:189], s[60:61], v[66:67] op_sel_hi:[1,0,1]
	v_pk_fma_f32 v[64:65], v[190:191], s[60:61], v[64:65] op_sel_hi:[1,0,1]
	v_pk_fma_f32 v[58:59], v[188:189], s[62:63], v[58:59] op_sel_hi:[1,0,1]
	v_pk_fma_f32 v[56:57], v[190:191], s[62:63], v[56:57] op_sel_hi:[1,0,1]
	v_pk_fma_f32 v[14:15], v[188:189], s[64:65], v[14:15] op_sel_hi:[1,0,1]
	v_pk_fma_f32 v[12:13], v[190:191], s[64:65], v[12:13] op_sel_hi:[1,0,1]
	global_load_dwordx4 v[176:179], v[232:233], off offset:1024
	global_load_dwordx4 v[180:183], v[234:235], off offset:1024
	s_waitcnt vmcnt(12)
	v_readlane_b32 s50, v81, 35
	v_readlane_b32 s52, v80, 35
	v_readlane_b32 s54, v79, 35
	v_readlane_b32 s56, v82, 35
	v_readlane_b32 s58, v78, 35
	v_readlane_b32 s60, v19, 35
	v_readlane_b32 s62, v76, 35
	v_readlane_b32 s64, v77, 35
	v_pk_fma_f32 v[70:71], v[192:193], s[50:51], v[70:71] op_sel_hi:[1,0,1]
	v_pk_fma_f32 v[68:69], v[194:195], s[50:51], v[68:69] op_sel_hi:[1,0,1]
	v_pk_fma_f32 v[62:63], v[192:193], s[52:53], v[62:63] op_sel_hi:[1,0,1]
	v_pk_fma_f32 v[60:61], v[194:195], s[52:53], v[60:61] op_sel_hi:[1,0,1]
	v_pk_fma_f32 v[54:55], v[192:193], s[54:55], v[54:55] op_sel_hi:[1,0,1]
	v_pk_fma_f32 v[52:53], v[194:195], s[54:55], v[52:53] op_sel_hi:[1,0,1]
	v_pk_fma_f32 v[8:9], v[192:193], s[56:57], v[8:9] op_sel_hi:[1,0,1]
	v_pk_fma_f32 v[10:11], v[194:195], s[56:57], v[10:11] op_sel_hi:[1,0,1]
	v_pk_fma_f32 v[4:5], v[196:197], s[58:59], v[4:5] op_sel_hi:[1,0,1]
	v_pk_fma_f32 v[6:7], v[198:199], s[58:59], v[6:7] op_sel_hi:[1,0,1]
	v_pk_fma_f32 v[66:67], v[196:197], s[60:61], v[66:67] op_sel_hi:[1,0,1]
	v_pk_fma_f32 v[64:65], v[198:199], s[60:61], v[64:65] op_sel_hi:[1,0,1]
	v_pk_fma_f32 v[58:59], v[196:197], s[62:63], v[58:59] op_sel_hi:[1,0,1]
	v_pk_fma_f32 v[56:57], v[198:199], s[62:63], v[56:57] op_sel_hi:[1,0,1]
	v_pk_fma_f32 v[14:15], v[196:197], s[64:65], v[14:15] op_sel_hi:[1,0,1]
	v_pk_fma_f32 v[12:13], v[198:199], s[64:65], v[12:13] op_sel_hi:[1,0,1]
	global_load_dwordx4 v[184:187], v[232:233], off offset:2048
	global_load_dwordx4 v[188:191], v[234:235], off offset:2048
	s_waitcnt vmcnt(12)
	v_readlane_b32 s50, v81, 36
	v_readlane_b32 s52, v80, 36
	v_readlane_b32 s54, v79, 36
	v_readlane_b32 s56, v82, 36
	v_readlane_b32 s58, v78, 36
	v_readlane_b32 s60, v19, 36
	v_readlane_b32 s62, v76, 36
	v_readlane_b32 s64, v77, 36
	v_pk_fma_f32 v[70:71], v[200:201], s[50:51], v[70:71] op_sel_hi:[1,0,1]
	v_pk_fma_f32 v[68:69], v[202:203], s[50:51], v[68:69] op_sel_hi:[1,0,1]
	v_pk_fma_f32 v[62:63], v[200:201], s[52:53], v[62:63] op_sel_hi:[1,0,1]
	v_pk_fma_f32 v[60:61], v[202:203], s[52:53], v[60:61] op_sel_hi:[1,0,1]
	v_pk_fma_f32 v[54:55], v[200:201], s[54:55], v[54:55] op_sel_hi:[1,0,1]
	v_pk_fma_f32 v[52:53], v[202:203], s[54:55], v[52:53] op_sel_hi:[1,0,1]
	v_pk_fma_f32 v[8:9], v[200:201], s[56:57], v[8:9] op_sel_hi:[1,0,1]
	v_pk_fma_f32 v[10:11], v[202:203], s[56:57], v[10:11] op_sel_hi:[1,0,1]
	v_pk_fma_f32 v[4:5], v[204:205], s[58:59], v[4:5] op_sel_hi:[1,0,1]
	v_pk_fma_f32 v[6:7], v[206:207], s[58:59], v[6:7] op_sel_hi:[1,0,1]
	v_pk_fma_f32 v[66:67], v[204:205], s[60:61], v[66:67] op_sel_hi:[1,0,1]
	v_pk_fma_f32 v[64:65], v[206:207], s[60:61], v[64:65] op_sel_hi:[1,0,1]
	v_pk_fma_f32 v[58:59], v[204:205], s[62:63], v[58:59] op_sel_hi:[1,0,1]
	v_pk_fma_f32 v[56:57], v[206:207], s[62:63], v[56:57] op_sel_hi:[1,0,1]
	v_pk_fma_f32 v[14:15], v[204:205], s[64:65], v[14:15] op_sel_hi:[1,0,1]
	v_pk_fma_f32 v[12:13], v[206:207], s[64:65], v[12:13] op_sel_hi:[1,0,1]
	global_load_dwordx4 v[192:195], v[232:233], off offset:3072
	global_load_dwordx4 v[196:199], v[234:235], off offset:3072
	v_lshl_add_u64 v[232:233], v[232:233], 0, s[66:67]
	v_lshl_add_u64 v[234:235], v[234:235], 0, s[66:67]
	s_waitcnt vmcnt(12)
	v_readlane_b32 s50, v81, 37
	v_readlane_b32 s52, v80, 37
	v_readlane_b32 s54, v79, 37
	v_readlane_b32 s56, v82, 37
	v_readlane_b32 s58, v78, 37
	v_readlane_b32 s60, v19, 37
	v_readlane_b32 s62, v76, 37
	v_readlane_b32 s64, v77, 37
	v_pk_fma_f32 v[70:71], v[208:209], s[50:51], v[70:71] op_sel_hi:[1,0,1]
	v_pk_fma_f32 v[68:69], v[210:211], s[50:51], v[68:69] op_sel_hi:[1,0,1]
	v_pk_fma_f32 v[62:63], v[208:209], s[52:53], v[62:63] op_sel_hi:[1,0,1]
	v_pk_fma_f32 v[60:61], v[210:211], s[52:53], v[60:61] op_sel_hi:[1,0,1]
	v_pk_fma_f32 v[54:55], v[208:209], s[54:55], v[54:55] op_sel_hi:[1,0,1]
	v_pk_fma_f32 v[52:53], v[210:211], s[54:55], v[52:53] op_sel_hi:[1,0,1]
	v_pk_fma_f32 v[8:9], v[208:209], s[56:57], v[8:9] op_sel_hi:[1,0,1]
	v_pk_fma_f32 v[10:11], v[210:211], s[56:57], v[10:11] op_sel_hi:[1,0,1]
	v_pk_fma_f32 v[4:5], v[212:213], s[58:59], v[4:5] op_sel_hi:[1,0,1]
	v_pk_fma_f32 v[6:7], v[214:215], s[58:59], v[6:7] op_sel_hi:[1,0,1]
	v_pk_fma_f32 v[66:67], v[212:213], s[60:61], v[66:67] op_sel_hi:[1,0,1]
	v_pk_fma_f32 v[64:65], v[214:215], s[60:61], v[64:65] op_sel_hi:[1,0,1]
	v_pk_fma_f32 v[58:59], v[212:213], s[62:63], v[58:59] op_sel_hi:[1,0,1]
	v_pk_fma_f32 v[56:57], v[214:215], s[62:63], v[56:57] op_sel_hi:[1,0,1]
	v_pk_fma_f32 v[14:15], v[212:213], s[64:65], v[14:15] op_sel_hi:[1,0,1]
	v_pk_fma_f32 v[12:13], v[214:215], s[64:65], v[12:13] op_sel_hi:[1,0,1]
	global_load_dwordx4 v[200:203], v[232:233], off offset:0
	global_load_dwordx4 v[204:207], v[234:235], off offset:0
	s_waitcnt vmcnt(12)
	v_readlane_b32 s50, v81, 38
	v_readlane_b32 s52, v80, 38
	v_readlane_b32 s54, v79, 38
	v_readlane_b32 s56, v82, 38
	v_readlane_b32 s58, v78, 38
	v_readlane_b32 s60, v19, 38
	v_readlane_b32 s62, v76, 38
	v_readlane_b32 s64, v77, 38
	v_pk_fma_f32 v[70:71], v[216:217], s[50:51], v[70:71] op_sel_hi:[1,0,1]
	v_pk_fma_f32 v[68:69], v[218:219], s[50:51], v[68:69] op_sel_hi:[1,0,1]
	v_pk_fma_f32 v[62:63], v[216:217], s[52:53], v[62:63] op_sel_hi:[1,0,1]
	v_pk_fma_f32 v[60:61], v[218:219], s[52:53], v[60:61] op_sel_hi:[1,0,1]
	v_pk_fma_f32 v[54:55], v[216:217], s[54:55], v[54:55] op_sel_hi:[1,0,1]
	v_pk_fma_f32 v[52:53], v[218:219], s[54:55], v[52:53] op_sel_hi:[1,0,1]
	v_pk_fma_f32 v[8:9], v[216:217], s[56:57], v[8:9] op_sel_hi:[1,0,1]
	v_pk_fma_f32 v[10:11], v[218:219], s[56:57], v[10:11] op_sel_hi:[1,0,1]
	v_pk_fma_f32 v[4:5], v[220:221], s[58:59], v[4:5] op_sel_hi:[1,0,1]
	v_pk_fma_f32 v[6:7], v[222:223], s[58:59], v[6:7] op_sel_hi:[1,0,1]
	v_pk_fma_f32 v[66:67], v[220:221], s[60:61], v[66:67] op_sel_hi:[1,0,1]
	v_pk_fma_f32 v[64:65], v[222:223], s[60:61], v[64:65] op_sel_hi:[1,0,1]
	v_pk_fma_f32 v[58:59], v[220:221], s[62:63], v[58:59] op_sel_hi:[1,0,1]
	v_pk_fma_f32 v[56:57], v[222:223], s[62:63], v[56:57] op_sel_hi:[1,0,1]
	v_pk_fma_f32 v[14:15], v[220:221], s[64:65], v[14:15] op_sel_hi:[1,0,1]
	v_pk_fma_f32 v[12:13], v[222:223], s[64:65], v[12:13] op_sel_hi:[1,0,1]
	global_load_dwordx4 v[208:211], v[232:233], off offset:1024
	global_load_dwordx4 v[212:215], v[234:235], off offset:1024
	s_waitcnt vmcnt(12)
	v_readlane_b32 s50, v81, 39
	v_readlane_b32 s52, v80, 39
	v_readlane_b32 s54, v79, 39
	v_readlane_b32 s56, v82, 39
	v_readlane_b32 s58, v78, 39
	v_readlane_b32 s60, v19, 39
	v_readlane_b32 s62, v76, 39
	v_readlane_b32 s64, v77, 39
	v_pk_fma_f32 v[70:71], v[224:225], s[50:51], v[70:71] op_sel_hi:[1,0,1]
	v_pk_fma_f32 v[68:69], v[226:227], s[50:51], v[68:69] op_sel_hi:[1,0,1]
	v_pk_fma_f32 v[62:63], v[224:225], s[52:53], v[62:63] op_sel_hi:[1,0,1]
	v_pk_fma_f32 v[60:61], v[226:227], s[52:53], v[60:61] op_sel_hi:[1,0,1]
	v_pk_fma_f32 v[54:55], v[224:225], s[54:55], v[54:55] op_sel_hi:[1,0,1]
	v_pk_fma_f32 v[52:53], v[226:227], s[54:55], v[52:53] op_sel_hi:[1,0,1]
	v_pk_fma_f32 v[8:9], v[224:225], s[56:57], v[8:9] op_sel_hi:[1,0,1]
	v_pk_fma_f32 v[10:11], v[226:227], s[56:57], v[10:11] op_sel_hi:[1,0,1]
	v_pk_fma_f32 v[4:5], v[228:229], s[58:59], v[4:5] op_sel_hi:[1,0,1]
	v_pk_fma_f32 v[6:7], v[230:231], s[58:59], v[6:7] op_sel_hi:[1,0,1]
	v_pk_fma_f32 v[66:67], v[228:229], s[60:61], v[66:67] op_sel_hi:[1,0,1]
	v_pk_fma_f32 v[64:65], v[230:231], s[60:61], v[64:65] op_sel_hi:[1,0,1]
	v_pk_fma_f32 v[58:59], v[228:229], s[62:63], v[58:59] op_sel_hi:[1,0,1]
	v_pk_fma_f32 v[56:57], v[230:231], s[62:63], v[56:57] op_sel_hi:[1,0,1]
	v_pk_fma_f32 v[14:15], v[228:229], s[64:65], v[14:15] op_sel_hi:[1,0,1]
	v_pk_fma_f32 v[12:13], v[230:231], s[64:65], v[12:13] op_sel_hi:[1,0,1]
	global_load_dwordx4 v[216:219], v[232:233], off offset:2048
	global_load_dwordx4 v[220:223], v[234:235], off offset:2048
	s_waitcnt vmcnt(12)
	v_readlane_b32 s50, v81, 40
	v_readlane_b32 s52, v80, 40
	v_readlane_b32 s54, v79, 40
	v_readlane_b32 s56, v82, 40
	v_readlane_b32 s58, v78, 40
	v_readlane_b32 s60, v19, 40
	v_readlane_b32 s62, v76, 40
	v_readlane_b32 s64, v77, 40
	v_pk_fma_f32 v[70:71], v[168:169], s[50:51], v[70:71] op_sel_hi:[1,0,1]
	v_pk_fma_f32 v[68:69], v[170:171], s[50:51], v[68:69] op_sel_hi:[1,0,1]
	v_pk_fma_f32 v[62:63], v[168:169], s[52:53], v[62:63] op_sel_hi:[1,0,1]
	v_pk_fma_f32 v[60:61], v[170:171], s[52:53], v[60:61] op_sel_hi:[1,0,1]
	v_pk_fma_f32 v[54:55], v[168:169], s[54:55], v[54:55] op_sel_hi:[1,0,1]
	v_pk_fma_f32 v[52:53], v[170:171], s[54:55], v[52:53] op_sel_hi:[1,0,1]
	v_pk_fma_f32 v[8:9], v[168:169], s[56:57], v[8:9] op_sel_hi:[1,0,1]
	v_pk_fma_f32 v[10:11], v[170:171], s[56:57], v[10:11] op_sel_hi:[1,0,1]
	v_pk_fma_f32 v[4:5], v[172:173], s[58:59], v[4:5] op_sel_hi:[1,0,1]
	v_pk_fma_f32 v[6:7], v[174:175], s[58:59], v[6:7] op_sel_hi:[1,0,1]
	v_pk_fma_f32 v[66:67], v[172:173], s[60:61], v[66:67] op_sel_hi:[1,0,1]
	v_pk_fma_f32 v[64:65], v[174:175], s[60:61], v[64:65] op_sel_hi:[1,0,1]
	v_pk_fma_f32 v[58:59], v[172:173], s[62:63], v[58:59] op_sel_hi:[1,0,1]
	v_pk_fma_f32 v[56:57], v[174:175], s[62:63], v[56:57] op_sel_hi:[1,0,1]
	v_pk_fma_f32 v[14:15], v[172:173], s[64:65], v[14:15] op_sel_hi:[1,0,1]
	v_pk_fma_f32 v[12:13], v[174:175], s[64:65], v[12:13] op_sel_hi:[1,0,1]
	global_load_dwordx4 v[224:227], v[232:233], off offset:3072
	global_load_dwordx4 v[228:231], v[234:235], off offset:3072
	v_lshl_add_u64 v[232:233], v[232:233], 0, s[66:67]
	v_lshl_add_u64 v[234:235], v[234:235], 0, s[66:67]
	s_waitcnt vmcnt(12)
	v_readlane_b32 s50, v81, 41
	v_readlane_b32 s52, v80, 41
	v_readlane_b32 s54, v79, 41
	v_readlane_b32 s56, v82, 41
	v_readlane_b32 s58, v78, 41
	v_readlane_b32 s60, v19, 41
	v_readlane_b32 s62, v76, 41
	v_readlane_b32 s64, v77, 41
	v_pk_fma_f32 v[70:71], v[176:177], s[50:51], v[70:71] op_sel_hi:[1,0,1]
	v_pk_fma_f32 v[68:69], v[178:179], s[50:51], v[68:69] op_sel_hi:[1,0,1]
	v_pk_fma_f32 v[62:63], v[176:177], s[52:53], v[62:63] op_sel_hi:[1,0,1]
	v_pk_fma_f32 v[60:61], v[178:179], s[52:53], v[60:61] op_sel_hi:[1,0,1]
	v_pk_fma_f32 v[54:55], v[176:177], s[54:55], v[54:55] op_sel_hi:[1,0,1]
	v_pk_fma_f32 v[52:53], v[178:179], s[54:55], v[52:53] op_sel_hi:[1,0,1]
	v_pk_fma_f32 v[8:9], v[176:177], s[56:57], v[8:9] op_sel_hi:[1,0,1]
	v_pk_fma_f32 v[10:11], v[178:179], s[56:57], v[10:11] op_sel_hi:[1,0,1]
	v_pk_fma_f32 v[4:5], v[180:181], s[58:59], v[4:5] op_sel_hi:[1,0,1]
	v_pk_fma_f32 v[6:7], v[182:183], s[58:59], v[6:7] op_sel_hi:[1,0,1]
	v_pk_fma_f32 v[66:67], v[180:181], s[60:61], v[66:67] op_sel_hi:[1,0,1]
	v_pk_fma_f32 v[64:65], v[182:183], s[60:61], v[64:65] op_sel_hi:[1,0,1]
	v_pk_fma_f32 v[58:59], v[180:181], s[62:63], v[58:59] op_sel_hi:[1,0,1]
	v_pk_fma_f32 v[56:57], v[182:183], s[62:63], v[56:57] op_sel_hi:[1,0,1]
	v_pk_fma_f32 v[14:15], v[180:181], s[64:65], v[14:15] op_sel_hi:[1,0,1]
	v_pk_fma_f32 v[12:13], v[182:183], s[64:65], v[12:13] op_sel_hi:[1,0,1]
	global_load_dwordx4 v[168:171], v[232:233], off offset:0
	global_load_dwordx4 v[172:175], v[234:235], off offset:0
	s_waitcnt vmcnt(12)
	v_readlane_b32 s50, v81, 42
	v_readlane_b32 s52, v80, 42
	v_readlane_b32 s54, v79, 42
	v_readlane_b32 s56, v82, 42
	v_readlane_b32 s58, v78, 42
	v_readlane_b32 s60, v19, 42
	v_readlane_b32 s62, v76, 42
	v_readlane_b32 s64, v77, 42
	v_pk_fma_f32 v[70:71], v[184:185], s[50:51], v[70:71] op_sel_hi:[1,0,1]
	v_pk_fma_f32 v[68:69], v[186:187], s[50:51], v[68:69] op_sel_hi:[1,0,1]
	v_pk_fma_f32 v[62:63], v[184:185], s[52:53], v[62:63] op_sel_hi:[1,0,1]
	v_pk_fma_f32 v[60:61], v[186:187], s[52:53], v[60:61] op_sel_hi:[1,0,1]
	v_pk_fma_f32 v[54:55], v[184:185], s[54:55], v[54:55] op_sel_hi:[1,0,1]
	v_pk_fma_f32 v[52:53], v[186:187], s[54:55], v[52:53] op_sel_hi:[1,0,1]
	v_pk_fma_f32 v[8:9], v[184:185], s[56:57], v[8:9] op_sel_hi:[1,0,1]
	v_pk_fma_f32 v[10:11], v[186:187], s[56:57], v[10:11] op_sel_hi:[1,0,1]
	v_pk_fma_f32 v[4:5], v[188:189], s[58:59], v[4:5] op_sel_hi:[1,0,1]
	v_pk_fma_f32 v[6:7], v[190:191], s[58:59], v[6:7] op_sel_hi:[1,0,1]
	v_pk_fma_f32 v[66:67], v[188:189], s[60:61], v[66:67] op_sel_hi:[1,0,1]
	v_pk_fma_f32 v[64:65], v[190:191], s[60:61], v[64:65] op_sel_hi:[1,0,1]
	v_pk_fma_f32 v[58:59], v[188:189], s[62:63], v[58:59] op_sel_hi:[1,0,1]
	v_pk_fma_f32 v[56:57], v[190:191], s[62:63], v[56:57] op_sel_hi:[1,0,1]
	v_pk_fma_f32 v[14:15], v[188:189], s[64:65], v[14:15] op_sel_hi:[1,0,1]
	v_pk_fma_f32 v[12:13], v[190:191], s[64:65], v[12:13] op_sel_hi:[1,0,1]
	global_load_dwordx4 v[176:179], v[232:233], off offset:1024
	global_load_dwordx4 v[180:183], v[234:235], off offset:1024
	s_waitcnt vmcnt(12)
	v_readlane_b32 s50, v81, 43
	v_readlane_b32 s52, v80, 43
	v_readlane_b32 s54, v79, 43
	v_readlane_b32 s56, v82, 43
	v_readlane_b32 s58, v78, 43
	v_readlane_b32 s60, v19, 43
	v_readlane_b32 s62, v76, 43
	v_readlane_b32 s64, v77, 43
	v_pk_fma_f32 v[70:71], v[192:193], s[50:51], v[70:71] op_sel_hi:[1,0,1]
	v_pk_fma_f32 v[68:69], v[194:195], s[50:51], v[68:69] op_sel_hi:[1,0,1]
	v_pk_fma_f32 v[62:63], v[192:193], s[52:53], v[62:63] op_sel_hi:[1,0,1]
	v_pk_fma_f32 v[60:61], v[194:195], s[52:53], v[60:61] op_sel_hi:[1,0,1]
	v_pk_fma_f32 v[54:55], v[192:193], s[54:55], v[54:55] op_sel_hi:[1,0,1]
	v_pk_fma_f32 v[52:53], v[194:195], s[54:55], v[52:53] op_sel_hi:[1,0,1]
	v_pk_fma_f32 v[8:9], v[192:193], s[56:57], v[8:9] op_sel_hi:[1,0,1]
	v_pk_fma_f32 v[10:11], v[194:195], s[56:57], v[10:11] op_sel_hi:[1,0,1]
	v_pk_fma_f32 v[4:5], v[196:197], s[58:59], v[4:5] op_sel_hi:[1,0,1]
	v_pk_fma_f32 v[6:7], v[198:199], s[58:59], v[6:7] op_sel_hi:[1,0,1]
	v_pk_fma_f32 v[66:67], v[196:197], s[60:61], v[66:67] op_sel_hi:[1,0,1]
	v_pk_fma_f32 v[64:65], v[198:199], s[60:61], v[64:65] op_sel_hi:[1,0,1]
	v_pk_fma_f32 v[58:59], v[196:197], s[62:63], v[58:59] op_sel_hi:[1,0,1]
	v_pk_fma_f32 v[56:57], v[198:199], s[62:63], v[56:57] op_sel_hi:[1,0,1]
	v_pk_fma_f32 v[14:15], v[196:197], s[64:65], v[14:15] op_sel_hi:[1,0,1]
	v_pk_fma_f32 v[12:13], v[198:199], s[64:65], v[12:13] op_sel_hi:[1,0,1]
	global_load_dwordx4 v[184:187], v[232:233], off offset:2048
	global_load_dwordx4 v[188:191], v[234:235], off offset:2048
	s_waitcnt vmcnt(12)
	v_readlane_b32 s50, v81, 44
	v_readlane_b32 s52, v80, 44
	v_readlane_b32 s54, v79, 44
	v_readlane_b32 s56, v82, 44
	v_readlane_b32 s58, v78, 44
	v_readlane_b32 s60, v19, 44
	v_readlane_b32 s62, v76, 44
	v_readlane_b32 s64, v77, 44
	v_pk_fma_f32 v[70:71], v[200:201], s[50:51], v[70:71] op_sel_hi:[1,0,1]
	v_pk_fma_f32 v[68:69], v[202:203], s[50:51], v[68:69] op_sel_hi:[1,0,1]
	v_pk_fma_f32 v[62:63], v[200:201], s[52:53], v[62:63] op_sel_hi:[1,0,1]
	v_pk_fma_f32 v[60:61], v[202:203], s[52:53], v[60:61] op_sel_hi:[1,0,1]
	v_pk_fma_f32 v[54:55], v[200:201], s[54:55], v[54:55] op_sel_hi:[1,0,1]
	v_pk_fma_f32 v[52:53], v[202:203], s[54:55], v[52:53] op_sel_hi:[1,0,1]
	v_pk_fma_f32 v[8:9], v[200:201], s[56:57], v[8:9] op_sel_hi:[1,0,1]
	v_pk_fma_f32 v[10:11], v[202:203], s[56:57], v[10:11] op_sel_hi:[1,0,1]
	v_pk_fma_f32 v[4:5], v[204:205], s[58:59], v[4:5] op_sel_hi:[1,0,1]
	v_pk_fma_f32 v[6:7], v[206:207], s[58:59], v[6:7] op_sel_hi:[1,0,1]
	v_pk_fma_f32 v[66:67], v[204:205], s[60:61], v[66:67] op_sel_hi:[1,0,1]
	v_pk_fma_f32 v[64:65], v[206:207], s[60:61], v[64:65] op_sel_hi:[1,0,1]
	v_pk_fma_f32 v[58:59], v[204:205], s[62:63], v[58:59] op_sel_hi:[1,0,1]
	v_pk_fma_f32 v[56:57], v[206:207], s[62:63], v[56:57] op_sel_hi:[1,0,1]
	v_pk_fma_f32 v[14:15], v[204:205], s[64:65], v[14:15] op_sel_hi:[1,0,1]
	v_pk_fma_f32 v[12:13], v[206:207], s[64:65], v[12:13] op_sel_hi:[1,0,1]
	global_load_dwordx4 v[192:195], v[232:233], off offset:3072
	global_load_dwordx4 v[196:199], v[234:235], off offset:3072
	v_lshl_add_u64 v[232:233], v[232:233], 0, s[66:67]
	v_lshl_add_u64 v[234:235], v[234:235], 0, s[66:67]
	s_waitcnt vmcnt(12)
	v_readlane_b32 s50, v81, 45
	v_readlane_b32 s52, v80, 45
	v_readlane_b32 s54, v79, 45
	v_readlane_b32 s56, v82, 45
	v_readlane_b32 s58, v78, 45
	v_readlane_b32 s60, v19, 45
	v_readlane_b32 s62, v76, 45
	v_readlane_b32 s64, v77, 45
	v_pk_fma_f32 v[70:71], v[208:209], s[50:51], v[70:71] op_sel_hi:[1,0,1]
	v_pk_fma_f32 v[68:69], v[210:211], s[50:51], v[68:69] op_sel_hi:[1,0,1]
	v_pk_fma_f32 v[62:63], v[208:209], s[52:53], v[62:63] op_sel_hi:[1,0,1]
	v_pk_fma_f32 v[60:61], v[210:211], s[52:53], v[60:61] op_sel_hi:[1,0,1]
	v_pk_fma_f32 v[54:55], v[208:209], s[54:55], v[54:55] op_sel_hi:[1,0,1]
	v_pk_fma_f32 v[52:53], v[210:211], s[54:55], v[52:53] op_sel_hi:[1,0,1]
	v_pk_fma_f32 v[8:9], v[208:209], s[56:57], v[8:9] op_sel_hi:[1,0,1]
	v_pk_fma_f32 v[10:11], v[210:211], s[56:57], v[10:11] op_sel_hi:[1,0,1]
	v_pk_fma_f32 v[4:5], v[212:213], s[58:59], v[4:5] op_sel_hi:[1,0,1]
	v_pk_fma_f32 v[6:7], v[214:215], s[58:59], v[6:7] op_sel_hi:[1,0,1]
	v_pk_fma_f32 v[66:67], v[212:213], s[60:61], v[66:67] op_sel_hi:[1,0,1]
	v_pk_fma_f32 v[64:65], v[214:215], s[60:61], v[64:65] op_sel_hi:[1,0,1]
	v_pk_fma_f32 v[58:59], v[212:213], s[62:63], v[58:59] op_sel_hi:[1,0,1]
	v_pk_fma_f32 v[56:57], v[214:215], s[62:63], v[56:57] op_sel_hi:[1,0,1]
	v_pk_fma_f32 v[14:15], v[212:213], s[64:65], v[14:15] op_sel_hi:[1,0,1]
	v_pk_fma_f32 v[12:13], v[214:215], s[64:65], v[12:13] op_sel_hi:[1,0,1]
	global_load_dwordx4 v[200:203], v[232:233], off offset:0
	global_load_dwordx4 v[204:207], v[234:235], off offset:0
	s_waitcnt vmcnt(12)
	v_readlane_b32 s50, v81, 46
	v_readlane_b32 s52, v80, 46
	v_readlane_b32 s54, v79, 46
	v_readlane_b32 s56, v82, 46
	v_readlane_b32 s58, v78, 46
	v_readlane_b32 s60, v19, 46
	v_readlane_b32 s62, v76, 46
	v_readlane_b32 s64, v77, 46
	v_pk_fma_f32 v[70:71], v[216:217], s[50:51], v[70:71] op_sel_hi:[1,0,1]
	v_pk_fma_f32 v[68:69], v[218:219], s[50:51], v[68:69] op_sel_hi:[1,0,1]
	v_pk_fma_f32 v[62:63], v[216:217], s[52:53], v[62:63] op_sel_hi:[1,0,1]
	v_pk_fma_f32 v[60:61], v[218:219], s[52:53], v[60:61] op_sel_hi:[1,0,1]
	v_pk_fma_f32 v[54:55], v[216:217], s[54:55], v[54:55] op_sel_hi:[1,0,1]
	v_pk_fma_f32 v[52:53], v[218:219], s[54:55], v[52:53] op_sel_hi:[1,0,1]
	v_pk_fma_f32 v[8:9], v[216:217], s[56:57], v[8:9] op_sel_hi:[1,0,1]
	v_pk_fma_f32 v[10:11], v[218:219], s[56:57], v[10:11] op_sel_hi:[1,0,1]
	v_pk_fma_f32 v[4:5], v[220:221], s[58:59], v[4:5] op_sel_hi:[1,0,1]
	v_pk_fma_f32 v[6:7], v[222:223], s[58:59], v[6:7] op_sel_hi:[1,0,1]
	v_pk_fma_f32 v[66:67], v[220:221], s[60:61], v[66:67] op_sel_hi:[1,0,1]
	v_pk_fma_f32 v[64:65], v[222:223], s[60:61], v[64:65] op_sel_hi:[1,0,1]
	v_pk_fma_f32 v[58:59], v[220:221], s[62:63], v[58:59] op_sel_hi:[1,0,1]
	v_pk_fma_f32 v[56:57], v[222:223], s[62:63], v[56:57] op_sel_hi:[1,0,1]
	v_pk_fma_f32 v[14:15], v[220:221], s[64:65], v[14:15] op_sel_hi:[1,0,1]
	v_pk_fma_f32 v[12:13], v[222:223], s[64:65], v[12:13] op_sel_hi:[1,0,1]
	global_load_dwordx4 v[208:211], v[232:233], off offset:1024
	global_load_dwordx4 v[212:215], v[234:235], off offset:1024
	s_waitcnt vmcnt(12)
	v_readlane_b32 s50, v81, 47
	v_readlane_b32 s52, v80, 47
	v_readlane_b32 s54, v79, 47
	v_readlane_b32 s56, v82, 47
	v_readlane_b32 s58, v78, 47
	v_readlane_b32 s60, v19, 47
	v_readlane_b32 s62, v76, 47
	v_readlane_b32 s64, v77, 47
	v_pk_fma_f32 v[70:71], v[224:225], s[50:51], v[70:71] op_sel_hi:[1,0,1]
	v_pk_fma_f32 v[68:69], v[226:227], s[50:51], v[68:69] op_sel_hi:[1,0,1]
	v_pk_fma_f32 v[62:63], v[224:225], s[52:53], v[62:63] op_sel_hi:[1,0,1]
	v_pk_fma_f32 v[60:61], v[226:227], s[52:53], v[60:61] op_sel_hi:[1,0,1]
	v_pk_fma_f32 v[54:55], v[224:225], s[54:55], v[54:55] op_sel_hi:[1,0,1]
	v_pk_fma_f32 v[52:53], v[226:227], s[54:55], v[52:53] op_sel_hi:[1,0,1]
	v_pk_fma_f32 v[8:9], v[224:225], s[56:57], v[8:9] op_sel_hi:[1,0,1]
	v_pk_fma_f32 v[10:11], v[226:227], s[56:57], v[10:11] op_sel_hi:[1,0,1]
	v_pk_fma_f32 v[4:5], v[228:229], s[58:59], v[4:5] op_sel_hi:[1,0,1]
	v_pk_fma_f32 v[6:7], v[230:231], s[58:59], v[6:7] op_sel_hi:[1,0,1]
	v_pk_fma_f32 v[66:67], v[228:229], s[60:61], v[66:67] op_sel_hi:[1,0,1]
	v_pk_fma_f32 v[64:65], v[230:231], s[60:61], v[64:65] op_sel_hi:[1,0,1]
	v_pk_fma_f32 v[58:59], v[228:229], s[62:63], v[58:59] op_sel_hi:[1,0,1]
	v_pk_fma_f32 v[56:57], v[230:231], s[62:63], v[56:57] op_sel_hi:[1,0,1]
	v_pk_fma_f32 v[14:15], v[228:229], s[64:65], v[14:15] op_sel_hi:[1,0,1]
	v_pk_fma_f32 v[12:13], v[230:231], s[64:65], v[12:13] op_sel_hi:[1,0,1]
	global_load_dwordx4 v[216:219], v[232:233], off offset:2048
	global_load_dwordx4 v[220:223], v[234:235], off offset:2048
	s_waitcnt vmcnt(12)
	v_readlane_b32 s50, v81, 48
	v_readlane_b32 s52, v80, 48
	v_readlane_b32 s54, v79, 48
	v_readlane_b32 s56, v82, 48
	v_readlane_b32 s58, v78, 48
	v_readlane_b32 s60, v19, 48
	v_readlane_b32 s62, v76, 48
	v_readlane_b32 s64, v77, 48
	v_pk_fma_f32 v[70:71], v[168:169], s[50:51], v[70:71] op_sel_hi:[1,0,1]
	v_pk_fma_f32 v[68:69], v[170:171], s[50:51], v[68:69] op_sel_hi:[1,0,1]
	v_pk_fma_f32 v[62:63], v[168:169], s[52:53], v[62:63] op_sel_hi:[1,0,1]
	v_pk_fma_f32 v[60:61], v[170:171], s[52:53], v[60:61] op_sel_hi:[1,0,1]
	v_pk_fma_f32 v[54:55], v[168:169], s[54:55], v[54:55] op_sel_hi:[1,0,1]
	v_pk_fma_f32 v[52:53], v[170:171], s[54:55], v[52:53] op_sel_hi:[1,0,1]
	v_pk_fma_f32 v[8:9], v[168:169], s[56:57], v[8:9] op_sel_hi:[1,0,1]
	v_pk_fma_f32 v[10:11], v[170:171], s[56:57], v[10:11] op_sel_hi:[1,0,1]
	v_pk_fma_f32 v[4:5], v[172:173], s[58:59], v[4:5] op_sel_hi:[1,0,1]
	v_pk_fma_f32 v[6:7], v[174:175], s[58:59], v[6:7] op_sel_hi:[1,0,1]
	v_pk_fma_f32 v[66:67], v[172:173], s[60:61], v[66:67] op_sel_hi:[1,0,1]
	v_pk_fma_f32 v[64:65], v[174:175], s[60:61], v[64:65] op_sel_hi:[1,0,1]
	v_pk_fma_f32 v[58:59], v[172:173], s[62:63], v[58:59] op_sel_hi:[1,0,1]
	v_pk_fma_f32 v[56:57], v[174:175], s[62:63], v[56:57] op_sel_hi:[1,0,1]
	v_pk_fma_f32 v[14:15], v[172:173], s[64:65], v[14:15] op_sel_hi:[1,0,1]
	v_pk_fma_f32 v[12:13], v[174:175], s[64:65], v[12:13] op_sel_hi:[1,0,1]
	global_load_dwordx4 v[224:227], v[232:233], off offset:3072
	global_load_dwordx4 v[228:231], v[234:235], off offset:3072
	v_lshl_add_u64 v[232:233], v[232:233], 0, s[66:67]
	v_lshl_add_u64 v[234:235], v[234:235], 0, s[66:67]
	s_waitcnt vmcnt(12)
	v_readlane_b32 s50, v81, 49
	v_readlane_b32 s52, v80, 49
	v_readlane_b32 s54, v79, 49
	v_readlane_b32 s56, v82, 49
	v_readlane_b32 s58, v78, 49
	v_readlane_b32 s60, v19, 49
	v_readlane_b32 s62, v76, 49
	v_readlane_b32 s64, v77, 49
	v_pk_fma_f32 v[70:71], v[176:177], s[50:51], v[70:71] op_sel_hi:[1,0,1]
	v_pk_fma_f32 v[68:69], v[178:179], s[50:51], v[68:69] op_sel_hi:[1,0,1]
	v_pk_fma_f32 v[62:63], v[176:177], s[52:53], v[62:63] op_sel_hi:[1,0,1]
	v_pk_fma_f32 v[60:61], v[178:179], s[52:53], v[60:61] op_sel_hi:[1,0,1]
	v_pk_fma_f32 v[54:55], v[176:177], s[54:55], v[54:55] op_sel_hi:[1,0,1]
	v_pk_fma_f32 v[52:53], v[178:179], s[54:55], v[52:53] op_sel_hi:[1,0,1]
	v_pk_fma_f32 v[8:9], v[176:177], s[56:57], v[8:9] op_sel_hi:[1,0,1]
	v_pk_fma_f32 v[10:11], v[178:179], s[56:57], v[10:11] op_sel_hi:[1,0,1]
	v_pk_fma_f32 v[4:5], v[180:181], s[58:59], v[4:5] op_sel_hi:[1,0,1]
	v_pk_fma_f32 v[6:7], v[182:183], s[58:59], v[6:7] op_sel_hi:[1,0,1]
	v_pk_fma_f32 v[66:67], v[180:181], s[60:61], v[66:67] op_sel_hi:[1,0,1]
	v_pk_fma_f32 v[64:65], v[182:183], s[60:61], v[64:65] op_sel_hi:[1,0,1]
	v_pk_fma_f32 v[58:59], v[180:181], s[62:63], v[58:59] op_sel_hi:[1,0,1]
	v_pk_fma_f32 v[56:57], v[182:183], s[62:63], v[56:57] op_sel_hi:[1,0,1]
	v_pk_fma_f32 v[14:15], v[180:181], s[64:65], v[14:15] op_sel_hi:[1,0,1]
	v_pk_fma_f32 v[12:13], v[182:183], s[64:65], v[12:13] op_sel_hi:[1,0,1]
	global_load_dwordx4 v[168:171], v[232:233], off offset:0
	global_load_dwordx4 v[172:175], v[234:235], off offset:0
	s_waitcnt vmcnt(12)
	v_readlane_b32 s50, v81, 50
	v_readlane_b32 s52, v80, 50
	v_readlane_b32 s54, v79, 50
	v_readlane_b32 s56, v82, 50
	v_readlane_b32 s58, v78, 50
	v_readlane_b32 s60, v19, 50
	v_readlane_b32 s62, v76, 50
	v_readlane_b32 s64, v77, 50
	v_pk_fma_f32 v[70:71], v[184:185], s[50:51], v[70:71] op_sel_hi:[1,0,1]
	v_pk_fma_f32 v[68:69], v[186:187], s[50:51], v[68:69] op_sel_hi:[1,0,1]
	v_pk_fma_f32 v[62:63], v[184:185], s[52:53], v[62:63] op_sel_hi:[1,0,1]
	v_pk_fma_f32 v[60:61], v[186:187], s[52:53], v[60:61] op_sel_hi:[1,0,1]
	v_pk_fma_f32 v[54:55], v[184:185], s[54:55], v[54:55] op_sel_hi:[1,0,1]
	v_pk_fma_f32 v[52:53], v[186:187], s[54:55], v[52:53] op_sel_hi:[1,0,1]
	v_pk_fma_f32 v[8:9], v[184:185], s[56:57], v[8:9] op_sel_hi:[1,0,1]
	v_pk_fma_f32 v[10:11], v[186:187], s[56:57], v[10:11] op_sel_hi:[1,0,1]
	v_pk_fma_f32 v[4:5], v[188:189], s[58:59], v[4:5] op_sel_hi:[1,0,1]
	v_pk_fma_f32 v[6:7], v[190:191], s[58:59], v[6:7] op_sel_hi:[1,0,1]
	v_pk_fma_f32 v[66:67], v[188:189], s[60:61], v[66:67] op_sel_hi:[1,0,1]
	v_pk_fma_f32 v[64:65], v[190:191], s[60:61], v[64:65] op_sel_hi:[1,0,1]
	v_pk_fma_f32 v[58:59], v[188:189], s[62:63], v[58:59] op_sel_hi:[1,0,1]
	v_pk_fma_f32 v[56:57], v[190:191], s[62:63], v[56:57] op_sel_hi:[1,0,1]
	v_pk_fma_f32 v[14:15], v[188:189], s[64:65], v[14:15] op_sel_hi:[1,0,1]
	v_pk_fma_f32 v[12:13], v[190:191], s[64:65], v[12:13] op_sel_hi:[1,0,1]
	global_load_dwordx4 v[176:179], v[232:233], off offset:1024
	global_load_dwordx4 v[180:183], v[234:235], off offset:1024
	s_waitcnt vmcnt(12)
	v_readlane_b32 s50, v81, 51
	v_readlane_b32 s52, v80, 51
	v_readlane_b32 s54, v79, 51
	v_readlane_b32 s56, v82, 51
	v_readlane_b32 s58, v78, 51
	v_readlane_b32 s60, v19, 51
	v_readlane_b32 s62, v76, 51
	v_readlane_b32 s64, v77, 51
	v_pk_fma_f32 v[70:71], v[192:193], s[50:51], v[70:71] op_sel_hi:[1,0,1]
	v_pk_fma_f32 v[68:69], v[194:195], s[50:51], v[68:69] op_sel_hi:[1,0,1]
	v_pk_fma_f32 v[62:63], v[192:193], s[52:53], v[62:63] op_sel_hi:[1,0,1]
	v_pk_fma_f32 v[60:61], v[194:195], s[52:53], v[60:61] op_sel_hi:[1,0,1]
	v_pk_fma_f32 v[54:55], v[192:193], s[54:55], v[54:55] op_sel_hi:[1,0,1]
	v_pk_fma_f32 v[52:53], v[194:195], s[54:55], v[52:53] op_sel_hi:[1,0,1]
	v_pk_fma_f32 v[8:9], v[192:193], s[56:57], v[8:9] op_sel_hi:[1,0,1]
	v_pk_fma_f32 v[10:11], v[194:195], s[56:57], v[10:11] op_sel_hi:[1,0,1]
	v_pk_fma_f32 v[4:5], v[196:197], s[58:59], v[4:5] op_sel_hi:[1,0,1]
	v_pk_fma_f32 v[6:7], v[198:199], s[58:59], v[6:7] op_sel_hi:[1,0,1]
	v_pk_fma_f32 v[66:67], v[196:197], s[60:61], v[66:67] op_sel_hi:[1,0,1]
	v_pk_fma_f32 v[64:65], v[198:199], s[60:61], v[64:65] op_sel_hi:[1,0,1]
	v_pk_fma_f32 v[58:59], v[196:197], s[62:63], v[58:59] op_sel_hi:[1,0,1]
	v_pk_fma_f32 v[56:57], v[198:199], s[62:63], v[56:57] op_sel_hi:[1,0,1]
	v_pk_fma_f32 v[14:15], v[196:197], s[64:65], v[14:15] op_sel_hi:[1,0,1]
	v_pk_fma_f32 v[12:13], v[198:199], s[64:65], v[12:13] op_sel_hi:[1,0,1]
	global_load_dwordx4 v[184:187], v[232:233], off offset:2048
	global_load_dwordx4 v[188:191], v[234:235], off offset:2048
	s_waitcnt vmcnt(12)
	v_readlane_b32 s50, v81, 52
	v_readlane_b32 s52, v80, 52
	v_readlane_b32 s54, v79, 52
	v_readlane_b32 s56, v82, 52
	v_readlane_b32 s58, v78, 52
	v_readlane_b32 s60, v19, 52
	v_readlane_b32 s62, v76, 52
	v_readlane_b32 s64, v77, 52
	v_pk_fma_f32 v[70:71], v[200:201], s[50:51], v[70:71] op_sel_hi:[1,0,1]
	v_pk_fma_f32 v[68:69], v[202:203], s[50:51], v[68:69] op_sel_hi:[1,0,1]
	v_pk_fma_f32 v[62:63], v[200:201], s[52:53], v[62:63] op_sel_hi:[1,0,1]
	v_pk_fma_f32 v[60:61], v[202:203], s[52:53], v[60:61] op_sel_hi:[1,0,1]
	v_pk_fma_f32 v[54:55], v[200:201], s[54:55], v[54:55] op_sel_hi:[1,0,1]
	v_pk_fma_f32 v[52:53], v[202:203], s[54:55], v[52:53] op_sel_hi:[1,0,1]
	v_pk_fma_f32 v[8:9], v[200:201], s[56:57], v[8:9] op_sel_hi:[1,0,1]
	v_pk_fma_f32 v[10:11], v[202:203], s[56:57], v[10:11] op_sel_hi:[1,0,1]
	v_pk_fma_f32 v[4:5], v[204:205], s[58:59], v[4:5] op_sel_hi:[1,0,1]
	v_pk_fma_f32 v[6:7], v[206:207], s[58:59], v[6:7] op_sel_hi:[1,0,1]
	v_pk_fma_f32 v[66:67], v[204:205], s[60:61], v[66:67] op_sel_hi:[1,0,1]
	v_pk_fma_f32 v[64:65], v[206:207], s[60:61], v[64:65] op_sel_hi:[1,0,1]
	v_pk_fma_f32 v[58:59], v[204:205], s[62:63], v[58:59] op_sel_hi:[1,0,1]
	v_pk_fma_f32 v[56:57], v[206:207], s[62:63], v[56:57] op_sel_hi:[1,0,1]
	v_pk_fma_f32 v[14:15], v[204:205], s[64:65], v[14:15] op_sel_hi:[1,0,1]
	v_pk_fma_f32 v[12:13], v[206:207], s[64:65], v[12:13] op_sel_hi:[1,0,1]
	global_load_dwordx4 v[192:195], v[232:233], off offset:3072
	global_load_dwordx4 v[196:199], v[234:235], off offset:3072
	v_lshl_add_u64 v[232:233], v[232:233], 0, s[66:67]
	v_lshl_add_u64 v[234:235], v[234:235], 0, s[66:67]
	s_waitcnt vmcnt(12)
	v_readlane_b32 s50, v81, 53
	v_readlane_b32 s52, v80, 53
	v_readlane_b32 s54, v79, 53
	v_readlane_b32 s56, v82, 53
	v_readlane_b32 s58, v78, 53
	v_readlane_b32 s60, v19, 53
	v_readlane_b32 s62, v76, 53
	v_readlane_b32 s64, v77, 53
	v_pk_fma_f32 v[70:71], v[208:209], s[50:51], v[70:71] op_sel_hi:[1,0,1]
	v_pk_fma_f32 v[68:69], v[210:211], s[50:51], v[68:69] op_sel_hi:[1,0,1]
	v_pk_fma_f32 v[62:63], v[208:209], s[52:53], v[62:63] op_sel_hi:[1,0,1]
	v_pk_fma_f32 v[60:61], v[210:211], s[52:53], v[60:61] op_sel_hi:[1,0,1]
	v_pk_fma_f32 v[54:55], v[208:209], s[54:55], v[54:55] op_sel_hi:[1,0,1]
	v_pk_fma_f32 v[52:53], v[210:211], s[54:55], v[52:53] op_sel_hi:[1,0,1]
	v_pk_fma_f32 v[8:9], v[208:209], s[56:57], v[8:9] op_sel_hi:[1,0,1]
	v_pk_fma_f32 v[10:11], v[210:211], s[56:57], v[10:11] op_sel_hi:[1,0,1]
	v_pk_fma_f32 v[4:5], v[212:213], s[58:59], v[4:5] op_sel_hi:[1,0,1]
	v_pk_fma_f32 v[6:7], v[214:215], s[58:59], v[6:7] op_sel_hi:[1,0,1]
	v_pk_fma_f32 v[66:67], v[212:213], s[60:61], v[66:67] op_sel_hi:[1,0,1]
	v_pk_fma_f32 v[64:65], v[214:215], s[60:61], v[64:65] op_sel_hi:[1,0,1]
	v_pk_fma_f32 v[58:59], v[212:213], s[62:63], v[58:59] op_sel_hi:[1,0,1]
	v_pk_fma_f32 v[56:57], v[214:215], s[62:63], v[56:57] op_sel_hi:[1,0,1]
	v_pk_fma_f32 v[14:15], v[212:213], s[64:65], v[14:15] op_sel_hi:[1,0,1]
	v_pk_fma_f32 v[12:13], v[214:215], s[64:65], v[12:13] op_sel_hi:[1,0,1]
	global_load_dwordx4 v[200:203], v[232:233], off offset:0
	global_load_dwordx4 v[204:207], v[234:235], off offset:0
	s_waitcnt vmcnt(12)
	v_readlane_b32 s50, v81, 54
	v_readlane_b32 s52, v80, 54
	v_readlane_b32 s54, v79, 54
	v_readlane_b32 s56, v82, 54
	v_readlane_b32 s58, v78, 54
	v_readlane_b32 s60, v19, 54
	v_readlane_b32 s62, v76, 54
	v_readlane_b32 s64, v77, 54
	v_pk_fma_f32 v[70:71], v[216:217], s[50:51], v[70:71] op_sel_hi:[1,0,1]
	v_pk_fma_f32 v[68:69], v[218:219], s[50:51], v[68:69] op_sel_hi:[1,0,1]
	v_pk_fma_f32 v[62:63], v[216:217], s[52:53], v[62:63] op_sel_hi:[1,0,1]
	v_pk_fma_f32 v[60:61], v[218:219], s[52:53], v[60:61] op_sel_hi:[1,0,1]
	v_pk_fma_f32 v[54:55], v[216:217], s[54:55], v[54:55] op_sel_hi:[1,0,1]
	v_pk_fma_f32 v[52:53], v[218:219], s[54:55], v[52:53] op_sel_hi:[1,0,1]
	v_pk_fma_f32 v[8:9], v[216:217], s[56:57], v[8:9] op_sel_hi:[1,0,1]
	v_pk_fma_f32 v[10:11], v[218:219], s[56:57], v[10:11] op_sel_hi:[1,0,1]
	v_pk_fma_f32 v[4:5], v[220:221], s[58:59], v[4:5] op_sel_hi:[1,0,1]
	v_pk_fma_f32 v[6:7], v[222:223], s[58:59], v[6:7] op_sel_hi:[1,0,1]
	v_pk_fma_f32 v[66:67], v[220:221], s[60:61], v[66:67] op_sel_hi:[1,0,1]
	v_pk_fma_f32 v[64:65], v[222:223], s[60:61], v[64:65] op_sel_hi:[1,0,1]
	v_pk_fma_f32 v[58:59], v[220:221], s[62:63], v[58:59] op_sel_hi:[1,0,1]
	v_pk_fma_f32 v[56:57], v[222:223], s[62:63], v[56:57] op_sel_hi:[1,0,1]
	v_pk_fma_f32 v[14:15], v[220:221], s[64:65], v[14:15] op_sel_hi:[1,0,1]
	v_pk_fma_f32 v[12:13], v[222:223], s[64:65], v[12:13] op_sel_hi:[1,0,1]
	global_load_dwordx4 v[208:211], v[232:233], off offset:1024
	global_load_dwordx4 v[212:215], v[234:235], off offset:1024
	s_waitcnt vmcnt(12)
	v_readlane_b32 s50, v81, 55
	v_readlane_b32 s52, v80, 55
	v_readlane_b32 s54, v79, 55
	v_readlane_b32 s56, v82, 55
	v_readlane_b32 s58, v78, 55
	v_readlane_b32 s60, v19, 55
	v_readlane_b32 s62, v76, 55
	v_readlane_b32 s64, v77, 55
	v_pk_fma_f32 v[70:71], v[224:225], s[50:51], v[70:71] op_sel_hi:[1,0,1]
	v_pk_fma_f32 v[68:69], v[226:227], s[50:51], v[68:69] op_sel_hi:[1,0,1]
	v_pk_fma_f32 v[62:63], v[224:225], s[52:53], v[62:63] op_sel_hi:[1,0,1]
	v_pk_fma_f32 v[60:61], v[226:227], s[52:53], v[60:61] op_sel_hi:[1,0,1]
	v_pk_fma_f32 v[54:55], v[224:225], s[54:55], v[54:55] op_sel_hi:[1,0,1]
	v_pk_fma_f32 v[52:53], v[226:227], s[54:55], v[52:53] op_sel_hi:[1,0,1]
	v_pk_fma_f32 v[8:9], v[224:225], s[56:57], v[8:9] op_sel_hi:[1,0,1]
	v_pk_fma_f32 v[10:11], v[226:227], s[56:57], v[10:11] op_sel_hi:[1,0,1]
	v_pk_fma_f32 v[4:5], v[228:229], s[58:59], v[4:5] op_sel_hi:[1,0,1]
	v_pk_fma_f32 v[6:7], v[230:231], s[58:59], v[6:7] op_sel_hi:[1,0,1]
	v_pk_fma_f32 v[66:67], v[228:229], s[60:61], v[66:67] op_sel_hi:[1,0,1]
	v_pk_fma_f32 v[64:65], v[230:231], s[60:61], v[64:65] op_sel_hi:[1,0,1]
	v_pk_fma_f32 v[58:59], v[228:229], s[62:63], v[58:59] op_sel_hi:[1,0,1]
	v_pk_fma_f32 v[56:57], v[230:231], s[62:63], v[56:57] op_sel_hi:[1,0,1]
	v_pk_fma_f32 v[14:15], v[228:229], s[64:65], v[14:15] op_sel_hi:[1,0,1]
	v_pk_fma_f32 v[12:13], v[230:231], s[64:65], v[12:13] op_sel_hi:[1,0,1]
	global_load_dwordx4 v[216:219], v[232:233], off offset:2048
	global_load_dwordx4 v[220:223], v[234:235], off offset:2048
	s_waitcnt vmcnt(12)
	v_readlane_b32 s50, v81, 56
	v_readlane_b32 s52, v80, 56
	v_readlane_b32 s54, v79, 56
	v_readlane_b32 s56, v82, 56
	v_readlane_b32 s58, v78, 56
	v_readlane_b32 s60, v19, 56
	v_readlane_b32 s62, v76, 56
	v_readlane_b32 s64, v77, 56
	v_pk_fma_f32 v[70:71], v[168:169], s[50:51], v[70:71] op_sel_hi:[1,0,1]
	v_pk_fma_f32 v[68:69], v[170:171], s[50:51], v[68:69] op_sel_hi:[1,0,1]
	v_pk_fma_f32 v[62:63], v[168:169], s[52:53], v[62:63] op_sel_hi:[1,0,1]
	v_pk_fma_f32 v[60:61], v[170:171], s[52:53], v[60:61] op_sel_hi:[1,0,1]
	v_pk_fma_f32 v[54:55], v[168:169], s[54:55], v[54:55] op_sel_hi:[1,0,1]
	v_pk_fma_f32 v[52:53], v[170:171], s[54:55], v[52:53] op_sel_hi:[1,0,1]
	v_pk_fma_f32 v[8:9], v[168:169], s[56:57], v[8:9] op_sel_hi:[1,0,1]
	v_pk_fma_f32 v[10:11], v[170:171], s[56:57], v[10:11] op_sel_hi:[1,0,1]
	v_pk_fma_f32 v[4:5], v[172:173], s[58:59], v[4:5] op_sel_hi:[1,0,1]
	v_pk_fma_f32 v[6:7], v[174:175], s[58:59], v[6:7] op_sel_hi:[1,0,1]
	v_pk_fma_f32 v[66:67], v[172:173], s[60:61], v[66:67] op_sel_hi:[1,0,1]
	v_pk_fma_f32 v[64:65], v[174:175], s[60:61], v[64:65] op_sel_hi:[1,0,1]
	v_pk_fma_f32 v[58:59], v[172:173], s[62:63], v[58:59] op_sel_hi:[1,0,1]
	v_pk_fma_f32 v[56:57], v[174:175], s[62:63], v[56:57] op_sel_hi:[1,0,1]
	v_pk_fma_f32 v[14:15], v[172:173], s[64:65], v[14:15] op_sel_hi:[1,0,1]
	v_pk_fma_f32 v[12:13], v[174:175], s[64:65], v[12:13] op_sel_hi:[1,0,1]
	global_load_dwordx4 v[224:227], v[232:233], off offset:3072
	global_load_dwordx4 v[228:231], v[234:235], off offset:3072
	s_waitcnt vmcnt(12)
	v_readlane_b32 s50, v81, 57
	v_readlane_b32 s52, v80, 57
	v_readlane_b32 s54, v79, 57
	v_readlane_b32 s56, v82, 57
	v_readlane_b32 s58, v78, 57
	v_readlane_b32 s60, v19, 57
	v_readlane_b32 s62, v76, 57
	v_readlane_b32 s64, v77, 57
	v_pk_fma_f32 v[70:71], v[176:177], s[50:51], v[70:71] op_sel_hi:[1,0,1]
	v_pk_fma_f32 v[68:69], v[178:179], s[50:51], v[68:69] op_sel_hi:[1,0,1]
	v_pk_fma_f32 v[62:63], v[176:177], s[52:53], v[62:63] op_sel_hi:[1,0,1]
	v_pk_fma_f32 v[60:61], v[178:179], s[52:53], v[60:61] op_sel_hi:[1,0,1]
	v_pk_fma_f32 v[54:55], v[176:177], s[54:55], v[54:55] op_sel_hi:[1,0,1]
	v_pk_fma_f32 v[52:53], v[178:179], s[54:55], v[52:53] op_sel_hi:[1,0,1]
	v_pk_fma_f32 v[8:9], v[176:177], s[56:57], v[8:9] op_sel_hi:[1,0,1]
	v_pk_fma_f32 v[10:11], v[178:179], s[56:57], v[10:11] op_sel_hi:[1,0,1]
	v_pk_fma_f32 v[4:5], v[180:181], s[58:59], v[4:5] op_sel_hi:[1,0,1]
	v_pk_fma_f32 v[6:7], v[182:183], s[58:59], v[6:7] op_sel_hi:[1,0,1]
	v_pk_fma_f32 v[66:67], v[180:181], s[60:61], v[66:67] op_sel_hi:[1,0,1]
	v_pk_fma_f32 v[64:65], v[182:183], s[60:61], v[64:65] op_sel_hi:[1,0,1]
	v_pk_fma_f32 v[58:59], v[180:181], s[62:63], v[58:59] op_sel_hi:[1,0,1]
	v_pk_fma_f32 v[56:57], v[182:183], s[62:63], v[56:57] op_sel_hi:[1,0,1]
	v_pk_fma_f32 v[14:15], v[180:181], s[64:65], v[14:15] op_sel_hi:[1,0,1]
	v_pk_fma_f32 v[12:13], v[182:183], s[64:65], v[12:13] op_sel_hi:[1,0,1]
	s_waitcnt vmcnt(10)
	v_readlane_b32 s50, v81, 58
	v_readlane_b32 s52, v80, 58
	v_readlane_b32 s54, v79, 58
	v_readlane_b32 s56, v82, 58
	v_readlane_b32 s58, v78, 58
	v_readlane_b32 s60, v19, 58
	v_readlane_b32 s62, v76, 58
	v_readlane_b32 s64, v77, 58
	v_pk_fma_f32 v[70:71], v[184:185], s[50:51], v[70:71] op_sel_hi:[1,0,1]
	v_pk_fma_f32 v[68:69], v[186:187], s[50:51], v[68:69] op_sel_hi:[1,0,1]
	v_pk_fma_f32 v[62:63], v[184:185], s[52:53], v[62:63] op_sel_hi:[1,0,1]
	v_pk_fma_f32 v[60:61], v[186:187], s[52:53], v[60:61] op_sel_hi:[1,0,1]
	v_pk_fma_f32 v[54:55], v[184:185], s[54:55], v[54:55] op_sel_hi:[1,0,1]
	v_pk_fma_f32 v[52:53], v[186:187], s[54:55], v[52:53] op_sel_hi:[1,0,1]
	v_pk_fma_f32 v[8:9], v[184:185], s[56:57], v[8:9] op_sel_hi:[1,0,1]
	v_pk_fma_f32 v[10:11], v[186:187], s[56:57], v[10:11] op_sel_hi:[1,0,1]
	v_pk_fma_f32 v[4:5], v[188:189], s[58:59], v[4:5] op_sel_hi:[1,0,1]
	v_pk_fma_f32 v[6:7], v[190:191], s[58:59], v[6:7] op_sel_hi:[1,0,1]
	v_pk_fma_f32 v[66:67], v[188:189], s[60:61], v[66:67] op_sel_hi:[1,0,1]
	v_pk_fma_f32 v[64:65], v[190:191], s[60:61], v[64:65] op_sel_hi:[1,0,1]
	v_pk_fma_f32 v[58:59], v[188:189], s[62:63], v[58:59] op_sel_hi:[1,0,1]
	v_pk_fma_f32 v[56:57], v[190:191], s[62:63], v[56:57] op_sel_hi:[1,0,1]
	v_pk_fma_f32 v[14:15], v[188:189], s[64:65], v[14:15] op_sel_hi:[1,0,1]
	v_pk_fma_f32 v[12:13], v[190:191], s[64:65], v[12:13] op_sel_hi:[1,0,1]
	s_waitcnt vmcnt(8)
	v_readlane_b32 s50, v81, 59
	v_readlane_b32 s52, v80, 59
	v_readlane_b32 s54, v79, 59
	v_readlane_b32 s56, v82, 59
	v_readlane_b32 s58, v78, 59
	v_readlane_b32 s60, v19, 59
	v_readlane_b32 s62, v76, 59
	v_readlane_b32 s64, v77, 59
	v_pk_fma_f32 v[70:71], v[192:193], s[50:51], v[70:71] op_sel_hi:[1,0,1]
	v_pk_fma_f32 v[68:69], v[194:195], s[50:51], v[68:69] op_sel_hi:[1,0,1]
	v_pk_fma_f32 v[62:63], v[192:193], s[52:53], v[62:63] op_sel_hi:[1,0,1]
	v_pk_fma_f32 v[60:61], v[194:195], s[52:53], v[60:61] op_sel_hi:[1,0,1]
	v_pk_fma_f32 v[54:55], v[192:193], s[54:55], v[54:55] op_sel_hi:[1,0,1]
	v_pk_fma_f32 v[52:53], v[194:195], s[54:55], v[52:53] op_sel_hi:[1,0,1]
	v_pk_fma_f32 v[8:9], v[192:193], s[56:57], v[8:9] op_sel_hi:[1,0,1]
	v_pk_fma_f32 v[10:11], v[194:195], s[56:57], v[10:11] op_sel_hi:[1,0,1]
	v_pk_fma_f32 v[4:5], v[196:197], s[58:59], v[4:5] op_sel_hi:[1,0,1]
	v_pk_fma_f32 v[6:7], v[198:199], s[58:59], v[6:7] op_sel_hi:[1,0,1]
	v_pk_fma_f32 v[66:67], v[196:197], s[60:61], v[66:67] op_sel_hi:[1,0,1]
	v_pk_fma_f32 v[64:65], v[198:199], s[60:61], v[64:65] op_sel_hi:[1,0,1]
	v_pk_fma_f32 v[58:59], v[196:197], s[62:63], v[58:59] op_sel_hi:[1,0,1]
	v_pk_fma_f32 v[56:57], v[198:199], s[62:63], v[56:57] op_sel_hi:[1,0,1]
	v_pk_fma_f32 v[14:15], v[196:197], s[64:65], v[14:15] op_sel_hi:[1,0,1]
	v_pk_fma_f32 v[12:13], v[198:199], s[64:65], v[12:13] op_sel_hi:[1,0,1]
	s_waitcnt vmcnt(6)
	v_readlane_b32 s50, v81, 60
	v_readlane_b32 s52, v80, 60
	v_readlane_b32 s54, v79, 60
	v_readlane_b32 s56, v82, 60
	v_readlane_b32 s58, v78, 60
	v_readlane_b32 s60, v19, 60
	v_readlane_b32 s62, v76, 60
	v_readlane_b32 s64, v77, 60
	v_pk_fma_f32 v[70:71], v[200:201], s[50:51], v[70:71] op_sel_hi:[1,0,1]
	v_pk_fma_f32 v[68:69], v[202:203], s[50:51], v[68:69] op_sel_hi:[1,0,1]
	v_pk_fma_f32 v[62:63], v[200:201], s[52:53], v[62:63] op_sel_hi:[1,0,1]
	v_pk_fma_f32 v[60:61], v[202:203], s[52:53], v[60:61] op_sel_hi:[1,0,1]
	v_pk_fma_f32 v[54:55], v[200:201], s[54:55], v[54:55] op_sel_hi:[1,0,1]
	v_pk_fma_f32 v[52:53], v[202:203], s[54:55], v[52:53] op_sel_hi:[1,0,1]
	v_pk_fma_f32 v[8:9], v[200:201], s[56:57], v[8:9] op_sel_hi:[1,0,1]
	v_pk_fma_f32 v[10:11], v[202:203], s[56:57], v[10:11] op_sel_hi:[1,0,1]
	v_pk_fma_f32 v[4:5], v[204:205], s[58:59], v[4:5] op_sel_hi:[1,0,1]
	v_pk_fma_f32 v[6:7], v[206:207], s[58:59], v[6:7] op_sel_hi:[1,0,1]
	v_pk_fma_f32 v[66:67], v[204:205], s[60:61], v[66:67] op_sel_hi:[1,0,1]
	v_pk_fma_f32 v[64:65], v[206:207], s[60:61], v[64:65] op_sel_hi:[1,0,1]
	v_pk_fma_f32 v[58:59], v[204:205], s[62:63], v[58:59] op_sel_hi:[1,0,1]
	v_pk_fma_f32 v[56:57], v[206:207], s[62:63], v[56:57] op_sel_hi:[1,0,1]
	v_pk_fma_f32 v[14:15], v[204:205], s[64:65], v[14:15] op_sel_hi:[1,0,1]
	v_pk_fma_f32 v[12:13], v[206:207], s[64:65], v[12:13] op_sel_hi:[1,0,1]
	s_waitcnt vmcnt(4)
	v_readlane_b32 s50, v81, 61
	v_readlane_b32 s52, v80, 61
	v_readlane_b32 s54, v79, 61
	v_readlane_b32 s56, v82, 61
	v_readlane_b32 s58, v78, 61
	v_readlane_b32 s60, v19, 61
	v_readlane_b32 s62, v76, 61
	v_readlane_b32 s64, v77, 61
	v_pk_fma_f32 v[70:71], v[208:209], s[50:51], v[70:71] op_sel_hi:[1,0,1]
	v_pk_fma_f32 v[68:69], v[210:211], s[50:51], v[68:69] op_sel_hi:[1,0,1]
	v_pk_fma_f32 v[62:63], v[208:209], s[52:53], v[62:63] op_sel_hi:[1,0,1]
	v_pk_fma_f32 v[60:61], v[210:211], s[52:53], v[60:61] op_sel_hi:[1,0,1]
	v_pk_fma_f32 v[54:55], v[208:209], s[54:55], v[54:55] op_sel_hi:[1,0,1]
	v_pk_fma_f32 v[52:53], v[210:211], s[54:55], v[52:53] op_sel_hi:[1,0,1]
	v_pk_fma_f32 v[8:9], v[208:209], s[56:57], v[8:9] op_sel_hi:[1,0,1]
	v_pk_fma_f32 v[10:11], v[210:211], s[56:57], v[10:11] op_sel_hi:[1,0,1]
	v_pk_fma_f32 v[4:5], v[212:213], s[58:59], v[4:5] op_sel_hi:[1,0,1]
	v_pk_fma_f32 v[6:7], v[214:215], s[58:59], v[6:7] op_sel_hi:[1,0,1]
	v_pk_fma_f32 v[66:67], v[212:213], s[60:61], v[66:67] op_sel_hi:[1,0,1]
	v_pk_fma_f32 v[64:65], v[214:215], s[60:61], v[64:65] op_sel_hi:[1,0,1]
	v_pk_fma_f32 v[58:59], v[212:213], s[62:63], v[58:59] op_sel_hi:[1,0,1]
	v_pk_fma_f32 v[56:57], v[214:215], s[62:63], v[56:57] op_sel_hi:[1,0,1]
	v_pk_fma_f32 v[14:15], v[212:213], s[64:65], v[14:15] op_sel_hi:[1,0,1]
	v_pk_fma_f32 v[12:13], v[214:215], s[64:65], v[12:13] op_sel_hi:[1,0,1]
	s_waitcnt vmcnt(2)
	v_readlane_b32 s50, v81, 62
	v_readlane_b32 s52, v80, 62
	v_readlane_b32 s54, v79, 62
	v_readlane_b32 s56, v82, 62
	v_readlane_b32 s58, v78, 62
	v_readlane_b32 s60, v19, 62
	v_readlane_b32 s62, v76, 62
	v_readlane_b32 s64, v77, 62
	v_pk_fma_f32 v[70:71], v[216:217], s[50:51], v[70:71] op_sel_hi:[1,0,1]
	v_pk_fma_f32 v[68:69], v[218:219], s[50:51], v[68:69] op_sel_hi:[1,0,1]
	v_pk_fma_f32 v[62:63], v[216:217], s[52:53], v[62:63] op_sel_hi:[1,0,1]
	v_pk_fma_f32 v[60:61], v[218:219], s[52:53], v[60:61] op_sel_hi:[1,0,1]
	v_pk_fma_f32 v[54:55], v[216:217], s[54:55], v[54:55] op_sel_hi:[1,0,1]
	v_pk_fma_f32 v[52:53], v[218:219], s[54:55], v[52:53] op_sel_hi:[1,0,1]
	v_pk_fma_f32 v[8:9], v[216:217], s[56:57], v[8:9] op_sel_hi:[1,0,1]
	v_pk_fma_f32 v[10:11], v[218:219], s[56:57], v[10:11] op_sel_hi:[1,0,1]
	v_pk_fma_f32 v[4:5], v[220:221], s[58:59], v[4:5] op_sel_hi:[1,0,1]
	v_pk_fma_f32 v[6:7], v[222:223], s[58:59], v[6:7] op_sel_hi:[1,0,1]
	v_pk_fma_f32 v[66:67], v[220:221], s[60:61], v[66:67] op_sel_hi:[1,0,1]
	v_pk_fma_f32 v[64:65], v[222:223], s[60:61], v[64:65] op_sel_hi:[1,0,1]
	v_pk_fma_f32 v[58:59], v[220:221], s[62:63], v[58:59] op_sel_hi:[1,0,1]
	v_pk_fma_f32 v[56:57], v[222:223], s[62:63], v[56:57] op_sel_hi:[1,0,1]
	v_pk_fma_f32 v[14:15], v[220:221], s[64:65], v[14:15] op_sel_hi:[1,0,1]
	v_pk_fma_f32 v[12:13], v[222:223], s[64:65], v[12:13] op_sel_hi:[1,0,1]
	s_waitcnt vmcnt(0)
	v_readlane_b32 s50, v81, 63
	v_readlane_b32 s52, v80, 63
	v_readlane_b32 s54, v79, 63
	v_readlane_b32 s56, v82, 63
	v_readlane_b32 s58, v78, 63
	v_readlane_b32 s60, v19, 63
	v_readlane_b32 s62, v76, 63
	v_readlane_b32 s64, v77, 63
	v_pk_fma_f32 v[70:71], v[224:225], s[50:51], v[70:71] op_sel_hi:[1,0,1]
	v_pk_fma_f32 v[68:69], v[226:227], s[50:51], v[68:69] op_sel_hi:[1,0,1]
	v_pk_fma_f32 v[62:63], v[224:225], s[52:53], v[62:63] op_sel_hi:[1,0,1]
	v_pk_fma_f32 v[60:61], v[226:227], s[52:53], v[60:61] op_sel_hi:[1,0,1]
	v_pk_fma_f32 v[54:55], v[224:225], s[54:55], v[54:55] op_sel_hi:[1,0,1]
	v_pk_fma_f32 v[52:53], v[226:227], s[54:55], v[52:53] op_sel_hi:[1,0,1]
	v_pk_fma_f32 v[8:9], v[224:225], s[56:57], v[8:9] op_sel_hi:[1,0,1]
	v_pk_fma_f32 v[10:11], v[226:227], s[56:57], v[10:11] op_sel_hi:[1,0,1]
	v_pk_fma_f32 v[4:5], v[228:229], s[58:59], v[4:5] op_sel_hi:[1,0,1]
	v_pk_fma_f32 v[6:7], v[230:231], s[58:59], v[6:7] op_sel_hi:[1,0,1]
	v_pk_fma_f32 v[66:67], v[228:229], s[60:61], v[66:67] op_sel_hi:[1,0,1]
	v_pk_fma_f32 v[64:65], v[230:231], s[60:61], v[64:65] op_sel_hi:[1,0,1]
	v_pk_fma_f32 v[58:59], v[228:229], s[62:63], v[58:59] op_sel_hi:[1,0,1]
	v_pk_fma_f32 v[56:57], v[230:231], s[62:63], v[56:57] op_sel_hi:[1,0,1]
	v_pk_fma_f32 v[14:15], v[228:229], s[64:65], v[14:15] op_sel_hi:[1,0,1]
	v_pk_fma_f32 v[12:13], v[230:231], s[64:65], v[12:13] op_sel_hi:[1,0,1]
	v_mul_f32_e32 v19, 0xbfb8aa3b, v70
	v_exp_f32_e32 v19, v19
	v_mul_f32_e32 v70, 0xbfb8aa3b, v71
	v_exp_f32_e32 v70, v70
	v_mul_f32_e32 v68, 0xbfb8aa3b, v68
	v_add_f32_e32 v19, 1.0, v19
	v_div_scale_f32 v71, s[22:23], v19, v19, 1.0
	v_rcp_f32_e32 v72, v71
	v_div_scale_f32 v73, vcc, 1.0, v19, 1.0
	v_exp_f32_e32 v68, v68
	v_fma_f32 v74, -v71, v72, 1.0
	v_fmac_f32_e32 v72, v74, v72
	v_mul_f32_e32 v74, v73, v72
	v_fma_f32 v75, -v71, v74, v73
	v_fmac_f32_e32 v74, v75, v72
	v_fma_f32 v71, -v71, v74, v73
	v_div_fmas_f32 v71, v71, v72, v74
	v_div_fixup_f32 v19, v71, v19, 1.0
	v_add_f32_e32 v71, 1.0, v70
	v_div_scale_f32 v72, s[22:23], v71, v71, 1.0
	v_rcp_f32_e32 v73, v72
	v_mul_f32_e32 v19, 0xbf1b4598, v19
	v_mul_f32_e32 v19, 0x3fb8aa3b, v19
	v_exp_f32_e32 v70, v19
	v_fma_f32 v19, -v72, v73, 1.0
	v_fmac_f32_e32 v73, v19, v73
	v_div_scale_f32 v19, vcc, 1.0, v71, 1.0
	v_mul_f32_e32 v74, v19, v73
	v_fma_f32 v75, -v72, v74, v19
	v_fmac_f32_e32 v74, v75, v73
	v_add_f32_e32 v68, 1.0, v68
	v_fma_f32 v19, -v72, v74, v19
	v_div_scale_f32 v72, s[22:23], v68, v68, 1.0
	v_div_fmas_f32 v19, v19, v73, v74
	v_rcp_f32_e32 v73, v72
	v_div_fixup_f32 v19, v19, v71, 1.0
	v_mul_f32_e32 v19, 0xbf1b4598, v19
	v_mul_f32_e32 v19, 0x3fb8aa3b, v19
	v_exp_f32_e32 v71, v19
	v_fma_f32 v19, -v72, v73, 1.0
	v_fmac_f32_e32 v73, v19, v73
	v_div_scale_f32 v19, vcc, 1.0, v68, 1.0
	v_mul_f32_e32 v74, v19, v73
	v_mul_f32_e32 v69, 0xbfb8aa3b, v69
	v_fma_f32 v75, -v72, v74, v19
	v_exp_f32_e32 v69, v69
	v_fmac_f32_e32 v74, v75, v73
	v_fma_f32 v19, -v72, v74, v19
	v_div_fmas_f32 v19, v19, v73, v74
	v_div_fixup_f32 v19, v19, v68, 1.0
	v_add_f32_e32 v68, 1.0, v69
	v_div_scale_f32 v69, s[22:23], v68, v68, 1.0
	v_rcp_f32_e32 v73, v69
	v_mul_f32_e32 v19, 0xbf1b4598, v19
	v_mul_f32_e32 v19, 0x3fb8aa3b, v19
	v_exp_f32_e32 v72, v19
	v_fma_f32 v19, -v69, v73, 1.0
	v_fmac_f32_e32 v73, v19, v73
	v_div_scale_f32 v19, vcc, 1.0, v68, 1.0
	v_mul_f32_e32 v74, v19, v73
	v_fma_f32 v75, -v69, v74, v19
	v_fmac_f32_e32 v74, v75, v73
	v_fma_f32 v19, -v69, v74, v19
	v_div_fmas_f32 v19, v19, v73, v74
	v_div_fixup_f32 v19, v19, v68, 1.0
	v_mul_f32_e32 v19, 0xbf1b4598, v19
	v_mul_f32_e32 v19, 0x3fb8aa3b, v19
	v_exp_f32_e32 v73, v19
	v_mul_f32_e32 v19, 0xbfb8aa3b, v66
	v_exp_f32_e32 v66, v19
	v_mul_f32_e32 v19, 0xbfb8aa3b, v67
	v_exp_f32_e32 v67, v19
	v_mul_f32_e32 v19, 0xbfb8aa3b, v64
	v_exp_f32_e32 v64, v19
	v_mul_f32_e32 v19, 0xbfb8aa3b, v65
	v_pk_add_f32 v[66:67], v[66:67], 1.0 op_sel_hi:[1,0]
	v_exp_f32_e32 v65, v19
	v_div_scale_f32 v74, s[22:23], v67, v67, 1.0
	v_rcp_f32_e32 v75, v74
	global_store_dwordx4 v[50:51], v[70:73], off offset:3072
	v_lshl_add_u64 v[68:69], v[48:49], 0, v[116:117]
	v_div_scale_f32 v50, s[22:23], v66, v66, 1.0
	v_fma_f32 v19, -v74, v75, 1.0
	v_fmac_f32_e32 v75, v19, v75
	v_div_scale_f32 v19, vcc, 1.0, v67, 1.0
	v_mul_f32_e32 v48, v19, v75
	v_fma_f32 v49, -v74, v48, v19
	v_rcp_f32_e32 v70, v50
	v_fmac_f32_e32 v48, v49, v75
	v_fma_f32 v19, -v74, v48, v19
	v_div_fmas_f32 v19, v19, v75, v48
	v_div_fixup_f32 v49, v19, v67, 1.0
	v_fma_f32 v19, -v50, v70, 1.0
	v_fmac_f32_e32 v70, v19, v70
	v_div_scale_f32 v19, vcc, 1.0, v66, 1.0
	v_mul_f32_e32 v48, v19, v70
	v_fma_f32 v51, -v50, v48, v19
	v_fmac_f32_e32 v48, v51, v70
	v_fma_f32 v19, -v50, v48, v19
	v_pk_add_f32 v[50:51], v[64:65], 1.0 op_sel_hi:[1,0]
	v_div_fmas_f32 v19, v19, v70, v48
	v_div_scale_f32 v64, s[22:23], v51, v51, 1.0
	v_rcp_f32_e32 v65, v64
	v_div_fixup_f32 v48, v19, v66, 1.0
	v_mul_f32_e32 v62, 0xbfb8aa3b, v62
	v_exp_f32_e32 v62, v62
	v_fma_f32 v19, -v64, v65, 1.0
	v_fmac_f32_e32 v65, v19, v65
	v_div_scale_f32 v19, vcc, 1.0, v51, 1.0
	v_mul_f32_e32 v66, v19, v65
	v_fma_f32 v67, -v64, v66, v19
	v_fmac_f32_e32 v66, v67, v65
	v_fma_f32 v19, -v64, v66, v19
	v_div_scale_f32 v64, s[22:23], v50, v50, 1.0
	v_rcp_f32_e32 v67, v64
	v_div_fmas_f32 v19, v19, v65, v66
	v_div_fixup_f32 v51, v19, v51, 1.0
	s_movk_i32 s4, 0x1000
	v_fma_f32 v19, -v64, v67, 1.0
	v_fmac_f32_e32 v67, v19, v67
	v_div_scale_f32 v19, vcc, 1.0, v50, 1.0
	v_mul_f32_e32 v65, v19, v67
	v_fma_f32 v66, -v64, v65, v19
	v_fmac_f32_e32 v65, v66, v67
	v_fma_f32 v19, -v64, v65, v19
	v_div_fmas_f32 v19, v19, v67, v65
	v_div_fixup_f32 v50, v19, v50, 1.0
	v_add_f32_e32 v19, 1.0, v62
	v_div_scale_f32 v62, s[22:23], v19, v19, 1.0
	v_rcp_f32_e32 v66, v62
	v_add_co_u32_e32 v64, vcc, s4, v68
	v_mul_f32_e32 v14, 0xbfb8aa3b, v14
	s_nop 0
	v_addc_co_u32_e32 v65, vcc, 0, v69, vcc
	global_store_dwordx4 v[64:65], v[48:51], off
	v_mul_f32_e32 v15, 0xbfb8aa3b, v15
	v_exp_f32_e32 v14, v14
	v_fma_f32 v48, -v62, v66, 1.0
	v_fmac_f32_e32 v66, v48, v66
	v_div_scale_f32 v48, vcc, 1.0, v19, 1.0
	v_mul_f32_e32 v49, v48, v66
	v_fma_f32 v50, -v62, v49, v48
	v_fmac_f32_e32 v49, v50, v66
	v_mul_f32_e32 v50, 0xbfb8aa3b, v63
	v_exp_f32_e32 v50, v50
	v_fma_f32 v48, -v62, v49, v48
	v_div_fmas_f32 v48, v48, v66, v49
	v_div_fixup_f32 v19, v48, v19, 1.0
	v_add_f32_e32 v49, 1.0, v50
	v_div_scale_f32 v50, s[22:23], v49, v49, 1.0
	v_rcp_f32_e32 v51, v50
	v_mul_f32_e32 v19, 0xbf1b4598, v19
	v_mul_f32_e32 v19, 0x3fb8aa3b, v19
	v_exp_f32_e32 v48, v19
	v_fma_f32 v19, -v50, v51, 1.0
	v_fmac_f32_e32 v51, v19, v51
	v_div_scale_f32 v19, vcc, 1.0, v49, 1.0
	v_mul_f32_e32 v62, v19, v51
	v_fma_f32 v63, -v50, v62, v19
	v_fmac_f32_e32 v62, v63, v51
	v_fma_f32 v19, -v50, v62, v19
	v_mul_f32_e32 v50, 0xbfb8aa3b, v60
	v_exp_f32_e32 v50, v50
	v_div_fmas_f32 v19, v19, v51, v62
	v_div_fixup_f32 v19, v19, v49, 1.0
	v_mul_f32_e32 v19, 0xbf1b4598, v19
	v_add_f32_e32 v50, 1.0, v50
	v_div_scale_f32 v51, s[22:23], v50, v50, 1.0
	v_rcp_f32_e32 v60, v51
	v_mul_f32_e32 v19, 0x3fb8aa3b, v19
	v_exp_f32_e32 v49, v19
	v_exp_f32_e32 v15, v15
	v_fma_f32 v19, -v51, v60, 1.0
	v_fmac_f32_e32 v60, v19, v60
	v_div_scale_f32 v19, vcc, 1.0, v50, 1.0
	v_mul_f32_e32 v62, v19, v60
	v_fma_f32 v63, -v51, v62, v19
	v_fmac_f32_e32 v62, v63, v60
	v_fma_f32 v19, -v51, v62, v19
	v_mul_f32_e32 v51, 0xbfb8aa3b, v61
	v_exp_f32_e32 v51, v51
	v_div_fmas_f32 v19, v19, v60, v62
	v_div_fixup_f32 v19, v19, v50, 1.0
	v_mul_f32_e32 v19, 0xbf1b4598, v19
	v_add_f32_e32 v51, 1.0, v51
	v_div_scale_f32 v60, s[22:23], v51, v51, 1.0
	v_rcp_f32_e32 v61, v60
	v_mul_f32_e32 v19, 0x3fb8aa3b, v19
	v_exp_f32_e32 v50, v19
	v_mul_f32_e32 v12, 0xbfb8aa3b, v12
	v_fma_f32 v19, -v60, v61, 1.0
	v_fmac_f32_e32 v61, v19, v61
	v_div_scale_f32 v19, vcc, 1.0, v51, 1.0
	v_mul_f32_e32 v62, v19, v61
	v_fma_f32 v63, -v60, v62, v19
	v_fmac_f32_e32 v62, v63, v61
	v_fma_f32 v19, -v60, v62, v19
	v_div_fmas_f32 v19, v19, v61, v62
	v_div_fixup_f32 v19, v19, v51, 1.0
	v_mul_f32_e32 v19, 0xbf1b4598, v19
	v_mul_f32_e32 v19, 0x3fb8aa3b, v19
	v_exp_f32_e32 v51, v19
	v_mul_f32_e32 v19, 0xbfb8aa3b, v58
	v_exp_f32_e32 v58, v19
	v_mul_f32_e32 v19, 0xbfb8aa3b, v59
	v_exp_f32_e32 v59, v19
	v_mul_f32_e32 v19, 0xbfb8aa3b, v56
	v_exp_f32_e32 v56, v19
	v_mul_f32_e32 v19, 0xbfb8aa3b, v57
	v_pk_add_f32 v[58:59], v[58:59], 1.0 op_sel_hi:[1,0]
	v_exp_f32_e32 v57, v19
	v_div_scale_f32 v60, s[22:23], v59, v59, 1.0
	v_rcp_f32_e32 v61, v60
	global_store_dwordx4 v[46:47], v[48:51], off offset:3072
	v_div_scale_f32 v46, s[22:23], v58, v58, 1.0
	v_fma_f32 v19, -v60, v61, 1.0
	v_fmac_f32_e32 v61, v19, v61
	v_div_scale_f32 v19, vcc, 1.0, v59, 1.0
	v_lshl_add_u64 v[48:49], v[44:45], 0, v[116:117]
	v_mul_f32_e32 v44, v19, v61
	v_fma_f32 v45, -v60, v44, v19
	v_rcp_f32_e32 v50, v46
	v_fmac_f32_e32 v44, v45, v61
	v_fma_f32 v19, -v60, v44, v19
	v_div_fmas_f32 v19, v19, v61, v44
	v_div_fixup_f32 v45, v19, v59, 1.0
	v_fma_f32 v19, -v46, v50, 1.0
	v_fmac_f32_e32 v50, v19, v50
	v_div_scale_f32 v19, vcc, 1.0, v58, 1.0
	v_mul_f32_e32 v44, v19, v50
	v_fma_f32 v47, -v46, v44, v19
	v_fmac_f32_e32 v44, v47, v50
	v_fma_f32 v19, -v46, v44, v19
	v_pk_add_f32 v[46:47], v[56:57], 1.0 op_sel_hi:[1,0]
	v_div_fmas_f32 v19, v19, v50, v44
	v_div_scale_f32 v51, s[22:23], v47, v47, 1.0
	v_rcp_f32_e32 v56, v51
	v_div_fixup_f32 v44, v19, v58, 1.0
	v_mul_f32_e32 v8, 0xbfb8aa3b, v8
	v_exp_f32_e32 v8, v8
	v_fma_f32 v19, -v51, v56, 1.0
	v_fmac_f32_e32 v56, v19, v56
	v_div_scale_f32 v19, vcc, 1.0, v47, 1.0
	v_mul_f32_e32 v50, v19, v56
	v_fma_f32 v57, -v51, v50, v19
	v_fmac_f32_e32 v50, v57, v56
	v_fma_f32 v19, -v51, v50, v19
	v_div_scale_f32 v51, s[22:23], v46, v46, 1.0
	v_rcp_f32_e32 v57, v51
	v_div_fmas_f32 v19, v19, v56, v50
	v_div_fixup_f32 v47, v19, v47, 1.0
	v_add_f32_e32 v8, 1.0, v8
	v_fma_f32 v19, -v51, v57, 1.0
	v_fmac_f32_e32 v57, v19, v57
	v_div_scale_f32 v19, vcc, 1.0, v46, 1.0
	v_mul_f32_e32 v50, v19, v57
	v_fma_f32 v56, -v51, v50, v19
	v_fmac_f32_e32 v50, v56, v57
	v_fma_f32 v19, -v51, v50, v19
	v_mul_f32_e32 v51, 0xbfb8aa3b, v54
	v_exp_f32_e32 v51, v51
	v_div_fmas_f32 v19, v19, v57, v50
	v_div_fixup_f32 v46, v19, v46, 1.0
	v_add_co_u32_e32 v48, vcc, s4, v48
	v_add_f32_e32 v19, 1.0, v51
	v_div_scale_f32 v50, s[22:23], v19, v19, 1.0
	v_rcp_f32_e32 v51, v50
	v_addc_co_u32_e32 v49, vcc, 0, v49, vcc
	global_store_dwordx4 v[48:49], v[44:47], off
	v_lshl_add_u64 v[40:41], v[40:41], 0, v[116:117]
	v_mul_f32_e32 v9, 0xbfb8aa3b, v9
	v_fma_f32 v44, -v50, v51, 1.0
	v_fmac_f32_e32 v51, v44, v51
	v_div_scale_f32 v44, vcc, 1.0, v19, 1.0
	v_mul_f32_e32 v45, v44, v51
	v_fma_f32 v46, -v50, v45, v44
	v_fmac_f32_e32 v45, v46, v51
	v_mul_f32_e32 v46, 0xbfb8aa3b, v55
	v_exp_f32_e32 v46, v46
	v_fma_f32 v44, -v50, v45, v44
	v_div_fmas_f32 v44, v44, v51, v45
	v_div_fixup_f32 v19, v44, v19, 1.0
	v_add_f32_e32 v45, 1.0, v46
	v_div_scale_f32 v46, s[22:23], v45, v45, 1.0
	v_rcp_f32_e32 v47, v46
	v_mul_f32_e32 v19, 0xbf1b4598, v19
	v_mul_f32_e32 v19, 0x3fb8aa3b, v19
	v_exp_f32_e32 v44, v19
	v_fma_f32 v19, -v46, v47, 1.0
	v_fmac_f32_e32 v47, v19, v47
	v_div_scale_f32 v19, vcc, 1.0, v45, 1.0
	v_mul_f32_e32 v48, v19, v47
	v_fma_f32 v49, -v46, v48, v19
	v_fmac_f32_e32 v48, v49, v47
	v_fma_f32 v19, -v46, v48, v19
	v_mul_f32_e32 v46, 0xbfb8aa3b, v52
	v_exp_f32_e32 v46, v46
	v_div_fmas_f32 v19, v19, v47, v48
	v_div_fixup_f32 v19, v19, v45, 1.0
	v_mul_f32_e32 v19, 0xbf1b4598, v19
	v_add_f32_e32 v46, 1.0, v46
	v_div_scale_f32 v47, s[22:23], v46, v46, 1.0
	v_rcp_f32_e32 v48, v47
	v_mul_f32_e32 v19, 0x3fb8aa3b, v19
	v_exp_f32_e32 v45, v19
	v_exp_f32_e32 v9, v9
	v_fma_f32 v19, -v47, v48, 1.0
	v_fmac_f32_e32 v48, v19, v48
	v_div_scale_f32 v19, vcc, 1.0, v46, 1.0
	v_mul_f32_e32 v49, v19, v48
	v_fma_f32 v50, -v47, v49, v19
	v_fmac_f32_e32 v49, v50, v48
	v_fma_f32 v19, -v47, v49, v19
	v_mul_f32_e32 v47, 0xbfb8aa3b, v53
	v_exp_f32_e32 v47, v47
	v_div_fmas_f32 v19, v19, v48, v49
	v_div_fixup_f32 v19, v19, v46, 1.0
	v_mul_f32_e32 v19, 0xbf1b4598, v19
	v_add_f32_e32 v47, 1.0, v47
	v_div_scale_f32 v48, s[22:23], v47, v47, 1.0
	v_rcp_f32_e32 v49, v48
	v_mul_f32_e32 v19, 0x3fb8aa3b, v19
	v_exp_f32_e32 v46, v19
	v_add_f32_e32 v9, 1.0, v9
	v_fma_f32 v19, -v48, v49, 1.0
	v_fmac_f32_e32 v49, v19, v49
	v_div_scale_f32 v19, vcc, 1.0, v47, 1.0
	v_mul_f32_e32 v50, v19, v49
	v_fma_f32 v51, -v48, v50, v19
	v_fmac_f32_e32 v50, v51, v49
	v_fma_f32 v19, -v48, v50, v19
	v_div_fmas_f32 v19, v19, v49, v50
	v_div_fixup_f32 v19, v19, v47, 1.0
	v_mul_f32_e32 v19, 0xbf1b4598, v19
	v_mul_f32_e32 v19, 0x3fb8aa3b, v19
	v_exp_f32_e32 v47, v19
	v_exp_f32_e32 v48, v12
	v_mul_f32_e32 v19, 0xbfb8aa3b, v13
	v_pk_add_f32 v[12:13], v[14:15], 1.0 op_sel_hi:[1,0]
	v_exp_f32_e32 v49, v19
	v_div_scale_f32 v14, s[22:23], v13, v13, 1.0
	v_rcp_f32_e32 v15, v14
	global_store_dwordx4 v[42:43], v[44:47], off offset:3072
	v_mul_f32_e32 v10, 0xbfb8aa3b, v10
	v_exp_f32_e32 v10, v10
	v_fma_f32 v19, -v14, v15, 1.0
	v_fmac_f32_e32 v15, v19, v15
	v_div_scale_f32 v19, vcc, 1.0, v13, 1.0
	v_mul_f32_e32 v42, v19, v15
	v_fma_f32 v43, -v14, v42, v19
	v_fmac_f32_e32 v42, v43, v15
	v_fma_f32 v14, -v14, v42, v19
	v_div_scale_f32 v19, s[22:23], v12, v12, 1.0
	v_rcp_f32_e32 v43, v19
	v_div_fmas_f32 v14, v14, v15, v42
	v_div_fixup_f32 v13, v14, v13, 1.0
	v_add_f32_e32 v10, 1.0, v10
	v_fma_f32 v14, -v19, v43, 1.0
	v_fmac_f32_e32 v43, v14, v43
	v_div_scale_f32 v14, vcc, 1.0, v12, 1.0
	v_mul_f32_e32 v42, v14, v43
	v_fma_f32 v15, -v19, v42, v14
	v_fmac_f32_e32 v42, v15, v43
	v_fma_f32 v19, -v19, v42, v14
	v_pk_add_f32 v[14:15], v[48:49], 1.0 op_sel_hi:[1,0]
	v_div_fmas_f32 v19, v19, v43, v42
	v_div_scale_f32 v44, s[22:23], v15, v15, 1.0
	v_rcp_f32_e32 v45, v44
	v_div_fixup_f32 v12, v19, v12, 1.0
	v_mul_f32_e32 v11, 0xbfb8aa3b, v11
	v_exp_f32_e32 v11, v11
	v_fma_f32 v19, -v44, v45, 1.0
	v_fmac_f32_e32 v45, v19, v45
	v_div_scale_f32 v19, vcc, 1.0, v15, 1.0
	v_mul_f32_e32 v42, v19, v45
	v_fma_f32 v43, -v44, v42, v19
	v_fmac_f32_e32 v42, v43, v45
	v_div_scale_f32 v43, s[22:23], v14, v14, 1.0
	v_fma_f32 v19, -v44, v42, v19
	v_rcp_f32_e32 v44, v43
	v_div_fmas_f32 v19, v19, v45, v42
	v_div_fixup_f32 v15, v19, v15, 1.0
	v_add_f32_e32 v11, 1.0, v11
	v_fma_f32 v19, -v43, v44, 1.0
	v_fmac_f32_e32 v44, v19, v44
	v_div_scale_f32 v19, vcc, 1.0, v14, 1.0
	v_mul_f32_e32 v42, v19, v44
	v_fma_f32 v45, -v43, v42, v19
	v_fmac_f32_e32 v42, v45, v44
	v_fma_f32 v19, -v43, v42, v19
	v_div_fmas_f32 v19, v19, v44, v42
	v_div_fixup_f32 v14, v19, v14, 1.0
	v_div_scale_f32 v19, s[22:23], v8, v8, 1.0
	v_rcp_f32_e32 v42, v19
	v_add_co_u32_e32 v40, vcc, s4, v40
	v_mul_f32_e32 v4, 0xbfb8aa3b, v4
	s_nop 0
	v_addc_co_u32_e32 v41, vcc, 0, v41, vcc
	global_store_dwordx4 v[40:41], v[12:15], off
	v_mul_f32_e32 v5, 0xbfb8aa3b, v5
	v_exp_f32_e32 v4, v4
	v_fma_f32 v12, -v19, v42, 1.0
	v_fmac_f32_e32 v42, v12, v42
	v_div_scale_f32 v12, vcc, 1.0, v8, 1.0
	v_mul_f32_e32 v13, v12, v42
	v_fma_f32 v14, -v19, v13, v12
	v_fmac_f32_e32 v13, v14, v42
	v_fma_f32 v12, -v19, v13, v12
	v_div_fmas_f32 v12, v12, v42, v13
	v_div_fixup_f32 v8, v12, v8, 1.0
	v_div_scale_f32 v12, s[22:23], v9, v9, 1.0
	v_rcp_f32_e32 v13, v12
	v_exp_f32_e32 v5, v5
	v_mul_f32_e32 v8, 0xbf1b4598, v8
	v_mul_f32_e32 v8, 0x3fb8aa3b, v8
	v_fma_f32 v14, -v12, v13, 1.0
	v_fmac_f32_e32 v13, v14, v13
	v_div_scale_f32 v14, vcc, 1.0, v9, 1.0
	v_mul_f32_e32 v15, v14, v13
	v_fma_f32 v19, -v12, v15, v14
	v_fmac_f32_e32 v15, v19, v13
	v_fma_f32 v12, -v12, v15, v14
	v_div_fmas_f32 v12, v12, v13, v15
	v_div_fixup_f32 v9, v12, v9, 1.0
	v_div_scale_f32 v12, s[22:23], v10, v10, 1.0
	v_rcp_f32_e32 v13, v12
	v_mul_f32_e32 v9, 0xbf1b4598, v9
	v_pk_add_f32 v[4:5], v[4:5], 1.0 op_sel_hi:[1,0]
	v_mul_f32_e32 v9, 0x3fb8aa3b, v9
	v_fma_f32 v14, -v12, v13, 1.0
	v_fmac_f32_e32 v13, v14, v13
	v_div_scale_f32 v14, vcc, 1.0, v10, 1.0
	v_mul_f32_e32 v15, v14, v13
	v_fma_f32 v19, -v12, v15, v14
	v_fmac_f32_e32 v15, v19, v13
	v_fma_f32 v12, -v12, v15, v14
	v_div_fmas_f32 v12, v12, v13, v15
	v_div_fixup_f32 v10, v12, v10, 1.0
	v_div_scale_f32 v12, s[22:23], v11, v11, 1.0
	v_rcp_f32_e32 v13, v12
	v_mul_f32_e32 v10, 0xbf1b4598, v10
	v_mul_f32_e32 v10, 0x3fb8aa3b, v10
	v_exp_f32_e32 v8, v8
	v_fma_f32 v14, -v12, v13, 1.0
	v_fmac_f32_e32 v13, v14, v13
	v_div_scale_f32 v14, vcc, 1.0, v11, 1.0
	v_mul_f32_e32 v15, v14, v13
	v_fma_f32 v19, -v12, v15, v14
	v_fmac_f32_e32 v15, v19, v13
	v_fma_f32 v12, -v12, v15, v14
	v_div_fmas_f32 v12, v12, v13, v15
	v_div_fixup_f32 v11, v12, v11, 1.0
	v_mul_f32_e32 v11, 0xbf1b4598, v11
	v_mul_f32_e32 v11, 0x3fb8aa3b, v11
	v_div_scale_f32 v12, s[22:23], v5, v5, 1.0
	v_exp_f32_e32 v9, v9
	v_exp_f32_e32 v10, v10
	v_exp_f32_e32 v11, v11
	v_rcp_f32_e32 v13, v12
	v_mul_f32_e32 v6, 0xbfb8aa3b, v6
	v_mul_f32_e32 v7, 0xbfb8aa3b, v7
	global_store_dwordx4 v[38:39], v[8:11], off offset:3072
	v_exp_f32_e32 v6, v6
	v_exp_f32_e32 v7, v7
	v_fma_f32 v10, -v12, v13, 1.0
	v_fmac_f32_e32 v13, v10, v13
	v_div_scale_f32 v10, vcc, 1.0, v5, 1.0
	v_mul_f32_e32 v11, v10, v13
	v_fma_f32 v14, -v12, v11, v10
	v_fmac_f32_e32 v11, v14, v13
	v_fma_f32 v10, -v12, v11, v10
	v_div_scale_f32 v12, s[22:23], v4, v4, 1.0
	v_rcp_f32_e32 v14, v12
	v_div_fmas_f32 v10, v10, v13, v11
	v_div_fixup_f32 v5, v10, v5, 1.0
	v_pk_add_f32 v[6:7], v[6:7], 1.0 op_sel_hi:[1,0]
	v_fma_f32 v10, -v12, v14, 1.0
	v_fmac_f32_e32 v14, v10, v14
	v_div_scale_f32 v10, vcc, 1.0, v4, 1.0
	v_mul_f32_e32 v11, v10, v14
	v_fma_f32 v13, -v12, v11, v10
	v_fmac_f32_e32 v11, v13, v14
	v_fma_f32 v10, -v12, v11, v10
	v_div_scale_f32 v12, s[22:23], v7, v7, 1.0
	v_rcp_f32_e32 v13, v12
	v_div_fmas_f32 v10, v10, v14, v11
	v_div_fixup_f32 v4, v10, v4, 1.0
	v_lshl_add_u64 v[8:9], v[36:37], 0, v[116:117]
	v_fma_f32 v10, -v12, v13, 1.0
	v_fmac_f32_e32 v13, v10, v13
	v_div_scale_f32 v10, vcc, 1.0, v7, 1.0
	v_mul_f32_e32 v11, v10, v13
	v_fma_f32 v14, -v12, v11, v10
	v_fmac_f32_e32 v11, v14, v13
	v_fma_f32 v10, -v12, v11, v10
	v_div_scale_f32 v12, s[22:23], v6, v6, 1.0
	v_rcp_f32_e32 v14, v12
	v_div_fmas_f32 v10, v10, v13, v11
	v_div_fixup_f32 v7, v10, v7, 1.0
	v_readlane_b32 s4, v162, 8
	v_fma_f32 v10, -v12, v14, 1.0
	v_fmac_f32_e32 v14, v10, v14
	v_div_scale_f32 v10, vcc, 1.0, v6, 1.0
	v_mul_f32_e32 v11, v10, v14
	v_fma_f32 v13, -v12, v11, v10
	v_fmac_f32_e32 v11, v13, v14
	v_fma_f32 v10, -v12, v11, v10
	v_div_fmas_f32 v10, v10, v14, v11
	v_add_co_u32_e32 v8, vcc, 0x1000, v8
	v_add_u32_e32 v17, s4, v17
	s_nop 0
	v_addc_co_u32_e32 v9, vcc, 0, v9, vcc
	s_movk_i32 s4, 0x27ff
	v_cmp_lt_i32_e32 vcc, s4, v17
	v_div_fixup_f32 v6, v10, v6, 1.0
	s_or_b64 s[20:21], vcc, s[20:21]
	global_store_dwordx4 v[8:9], v[4:7], off
	s_andn2_b64 exec, exec, s[20:21]
	s_cbranch_execnz .LBB0_526

.LBB0_805:
	s_mov_b32 s66, 0x1000
	s_mov_b32 s67, 0
	v_mov_b32_e32 v232, v40
	v_mov_b32_e32 v233, v41
	v_mov_b32_e32 v216, 0
	v_mov_b32_e32 v217, 0
	v_mov_b32_e32 v218, 0
	v_mov_b32_e32 v219, 0
	v_mov_b32_e32 v220, 0
	v_mov_b32_e32 v221, 0
	v_mov_b32_e32 v222, 0
	v_mov_b32_e32 v223, 0
	v_mov_b32_e32 v224, 0
	v_mov_b32_e32 v225, 0
	v_mov_b32_e32 v226, 0
	v_mov_b32_e32 v227, 0
	v_mov_b32_e32 v228, 0
	v_mov_b32_e32 v229, 0
	v_mov_b32_e32 v230, 0
	v_mov_b32_e32 v231, 0
	global_load_dwordx4 v[168:171], v[232:233], off offset:-2048
	global_load_dwordx4 v[172:175], v[232:233], off offset:-1024
	global_load_dwordx4 v[176:179], v[232:233], off offset:0
	global_load_dwordx4 v[180:183], v[232:233], off offset:1024
	v_lshl_add_u64 v[232:233], v[232:233], 0, s[66:67]
	global_load_dwordx4 v[184:187], v[232:233], off offset:-2048
	global_load_dwordx4 v[188:191], v[232:233], off offset:-1024
	global_load_dwordx4 v[192:195], v[232:233], off offset:0
	global_load_dwordx4 v[196:199], v[232:233], off offset:1024
	v_lshl_add_u64 v[232:233], v[232:233], 0, s[66:67]
	global_load_dwordx4 v[200:203], v[232:233], off offset:-2048
	global_load_dwordx4 v[204:207], v[232:233], off offset:-1024
	global_load_dwordx4 v[208:211], v[232:233], off offset:0
	s_waitcnt vmcnt(10)
	v_readlane_b32 s50, v11, 0
	v_readlane_b32 s52, v54, 0
	v_readlane_b32 s54, v55, 0
	v_readlane_b32 s56, v56, 0
	v_pk_fma_f32 v[216:217], v[168:169], s[50:51], v[216:217] op_sel_hi:[1,0,1]
	v_pk_fma_f32 v[218:219], v[170:171], s[50:51], v[218:219] op_sel_hi:[1,0,1]
	v_pk_fma_f32 v[220:221], v[168:169], s[52:53], v[220:221] op_sel_hi:[1,0,1]
	v_pk_fma_f32 v[222:223], v[170:171], s[52:53], v[222:223] op_sel_hi:[1,0,1]
	v_pk_fma_f32 v[224:225], v[168:169], s[54:55], v[224:225] op_sel_hi:[1,0,1]
	v_pk_fma_f32 v[226:227], v[170:171], s[54:55], v[226:227] op_sel_hi:[1,0,1]
	v_pk_fma_f32 v[228:229], v[168:169], s[56:57], v[228:229] op_sel_hi:[1,0,1]
	v_pk_fma_f32 v[230:231], v[170:171], s[56:57], v[230:231] op_sel_hi:[1,0,1]
	global_load_dwordx4 v[212:215], v[232:233], off offset:1024
	v_lshl_add_u64 v[232:233], v[232:233], 0, s[66:67]
	s_waitcnt vmcnt(10)
	v_readlane_b32 s50, v11, 1
	v_readlane_b32 s52, v54, 1
	v_readlane_b32 s54, v55, 1
	v_readlane_b32 s56, v56, 1
	v_pk_fma_f32 v[216:217], v[172:173], s[50:51], v[216:217] op_sel_hi:[1,0,1]
	v_pk_fma_f32 v[218:219], v[174:175], s[50:51], v[218:219] op_sel_hi:[1,0,1]
	v_pk_fma_f32 v[220:221], v[172:173], s[52:53], v[220:221] op_sel_hi:[1,0,1]
	v_pk_fma_f32 v[222:223], v[174:175], s[52:53], v[222:223] op_sel_hi:[1,0,1]
	v_pk_fma_f32 v[224:225], v[172:173], s[54:55], v[224:225] op_sel_hi:[1,0,1]
	v_pk_fma_f32 v[226:227], v[174:175], s[54:55], v[226:227] op_sel_hi:[1,0,1]
	v_pk_fma_f32 v[228:229], v[172:173], s[56:57], v[228:229] op_sel_hi:[1,0,1]
	v_pk_fma_f32 v[230:231], v[174:175], s[56:57], v[230:231] op_sel_hi:[1,0,1]
	global_load_dwordx4 v[168:171], v[232:233], off offset:-2048
	s_waitcnt vmcnt(10)
	v_readlane_b32 s50, v11, 2
	v_readlane_b32 s52, v54, 2
	v_readlane_b32 s54, v55, 2
	v_readlane_b32 s56, v56, 2
	v_pk_fma_f32 v[216:217], v[176:177], s[50:51], v[216:217] op_sel_hi:[1,0,1]
	v_pk_fma_f32 v[218:219], v[178:179], s[50:51], v[218:219] op_sel_hi:[1,0,1]
	v_pk_fma_f32 v[220:221], v[176:177], s[52:53], v[220:221] op_sel_hi:[1,0,1]
	v_pk_fma_f32 v[222:223], v[178:179], s[52:53], v[222:223] op_sel_hi:[1,0,1]
	v_pk_fma_f32 v[224:225], v[176:177], s[54:55], v[224:225] op_sel_hi:[1,0,1]
	v_pk_fma_f32 v[226:227], v[178:179], s[54:55], v[226:227] op_sel_hi:[1,0,1]
	v_pk_fma_f32 v[228:229], v[176:177], s[56:57], v[228:229] op_sel_hi:[1,0,1]
	v_pk_fma_f32 v[230:231], v[178:179], s[56:57], v[230:231] op_sel_hi:[1,0,1]
	global_load_dwordx4 v[172:175], v[232:233], off offset:-1024
	s_waitcnt vmcnt(10)
	v_readlane_b32 s50, v11, 3
	v_readlane_b32 s52, v54, 3
	v_readlane_b32 s54, v55, 3
	v_readlane_b32 s56, v56, 3
	v_pk_fma_f32 v[216:217], v[180:181], s[50:51], v[216:217] op_sel_hi:[1,0,1]
	v_pk_fma_f32 v[218:219], v[182:183], s[50:51], v[218:219] op_sel_hi:[1,0,1]
	v_pk_fma_f32 v[220:221], v[180:181], s[52:53], v[220:221] op_sel_hi:[1,0,1]
	v_pk_fma_f32 v[222:223], v[182:183], s[52:53], v[222:223] op_sel_hi:[1,0,1]
	v_pk_fma_f32 v[224:225], v[180:181], s[54:55], v[224:225] op_sel_hi:[1,0,1]
	v_pk_fma_f32 v[226:227], v[182:183], s[54:55], v[226:227] op_sel_hi:[1,0,1]
	v_pk_fma_f32 v[228:229], v[180:181], s[56:57], v[228:229] op_sel_hi:[1,0,1]
	v_pk_fma_f32 v[230:231], v[182:183], s[56:57], v[230:231] op_sel_hi:[1,0,1]
	global_load_dwordx4 v[176:179], v[232:233], off offset:0
	s_waitcnt vmcnt(10)
	v_readlane_b32 s50, v11, 4
	v_readlane_b32 s52, v54, 4
	v_readlane_b32 s54, v55, 4
	v_readlane_b32 s56, v56, 4
	v_pk_fma_f32 v[216:217], v[184:185], s[50:51], v[216:217] op_sel_hi:[1,0,1]
	v_pk_fma_f32 v[218:219], v[186:187], s[50:51], v[218:219] op_sel_hi:[1,0,1]
	v_pk_fma_f32 v[220:221], v[184:185], s[52:53], v[220:221] op_sel_hi:[1,0,1]
	v_pk_fma_f32 v[222:223], v[186:187], s[52:53], v[222:223] op_sel_hi:[1,0,1]
	v_pk_fma_f32 v[224:225], v[184:185], s[54:55], v[224:225] op_sel_hi:[1,0,1]
	v_pk_fma_f32 v[226:227], v[186:187], s[54:55], v[226:227] op_sel_hi:[1,0,1]
	v_pk_fma_f32 v[228:229], v[184:185], s[56:57], v[228:229] op_sel_hi:[1,0,1]
	v_pk_fma_f32 v[230:231], v[186:187], s[56:57], v[230:231] op_sel_hi:[1,0,1]
	global_load_dwordx4 v[180:183], v[232:233], off offset:1024
	v_lshl_add_u64 v[232:233], v[232:233], 0, s[66:67]
	s_waitcnt vmcnt(10)
	v_readlane_b32 s50, v11, 5
	v_readlane_b32 s52, v54, 5
	v_readlane_b32 s54, v55, 5
	v_readlane_b32 s56, v56, 5
	v_pk_fma_f32 v[216:217], v[188:189], s[50:51], v[216:217] op_sel_hi:[1,0,1]
	v_pk_fma_f32 v[218:219], v[190:191], s[50:51], v[218:219] op_sel_hi:[1,0,1]
	v_pk_fma_f32 v[220:221], v[188:189], s[52:53], v[220:221] op_sel_hi:[1,0,1]
	v_pk_fma_f32 v[222:223], v[190:191], s[52:53], v[222:223] op_sel_hi:[1,0,1]
	v_pk_fma_f32 v[224:225], v[188:189], s[54:55], v[224:225] op_sel_hi:[1,0,1]
	v_pk_fma_f32 v[226:227], v[190:191], s[54:55], v[226:227] op_sel_hi:[1,0,1]
	v_pk_fma_f32 v[228:229], v[188:189], s[56:57], v[228:229] op_sel_hi:[1,0,1]
	v_pk_fma_f32 v[230:231], v[190:191], s[56:57], v[230:231] op_sel_hi:[1,0,1]
	global_load_dwordx4 v[184:187], v[232:233], off offset:-2048
	s_waitcnt vmcnt(10)
	v_readlane_b32 s50, v11, 6
	v_readlane_b32 s52, v54, 6
	v_readlane_b32 s54, v55, 6
	v_readlane_b32 s56, v56, 6
	v_pk_fma_f32 v[216:217], v[192:193], s[50:51], v[216:217] op_sel_hi:[1,0,1]
	v_pk_fma_f32 v[218:219], v[194:195], s[50:51], v[218:219] op_sel_hi:[1,0,1]
	v_pk_fma_f32 v[220:221], v[192:193], s[52:53], v[220:221] op_sel_hi:[1,0,1]
	v_pk_fma_f32 v[222:223], v[194:195], s[52:53], v[222:223] op_sel_hi:[1,0,1]
	v_pk_fma_f32 v[224:225], v[192:193], s[54:55], v[224:225] op_sel_hi:[1,0,1]
	v_pk_fma_f32 v[226:227], v[194:195], s[54:55], v[226:227] op_sel_hi:[1,0,1]
	v_pk_fma_f32 v[228:229], v[192:193], s[56:57], v[228:229] op_sel_hi:[1,0,1]
	v_pk_fma_f32 v[230:231], v[194:195], s[56:57], v[230:231] op_sel_hi:[1,0,1]
	global_load_dwordx4 v[188:191], v[232:233], off offset:-1024
	s_waitcnt vmcnt(10)
	v_readlane_b32 s50, v11, 7
	v_readlane_b32 s52, v54, 7
	v_readlane_b32 s54, v55, 7
	v_readlane_b32 s56, v56, 7
	v_pk_fma_f32 v[216:217], v[196:197], s[50:51], v[216:217] op_sel_hi:[1,0,1]
	v_pk_fma_f32 v[218:219], v[198:199], s[50:51], v[218:219] op_sel_hi:[1,0,1]
	v_pk_fma_f32 v[220:221], v[196:197], s[52:53], v[220:221] op_sel_hi:[1,0,1]
	v_pk_fma_f32 v[222:223], v[198:199], s[52:53], v[222:223] op_sel_hi:[1,0,1]
	v_pk_fma_f32 v[224:225], v[196:197], s[54:55], v[224:225] op_sel_hi:[1,0,1]
	v_pk_fma_f32 v[226:227], v[198:199], s[54:55], v[226:227] op_sel_hi:[1,0,1]
	v_pk_fma_f32 v[228:229], v[196:197], s[56:57], v[228:229] op_sel_hi:[1,0,1]
	v_pk_fma_f32 v[230:231], v[198:199], s[56:57], v[230:231] op_sel_hi:[1,0,1]
	global_load_dwordx4 v[192:195], v[232:233], off offset:0
	s_waitcnt vmcnt(10)
	v_readlane_b32 s50, v11, 8
	v_readlane_b32 s52, v54, 8
	v_readlane_b32 s54, v55, 8
	v_readlane_b32 s56, v56, 8
	v_pk_fma_f32 v[216:217], v[200:201], s[50:51], v[216:217] op_sel_hi:[1,0,1]
	v_pk_fma_f32 v[218:219], v[202:203], s[50:51], v[218:219] op_sel_hi:[1,0,1]
	v_pk_fma_f32 v[220:221], v[200:201], s[52:53], v[220:221] op_sel_hi:[1,0,1]
	v_pk_fma_f32 v[222:223], v[202:203], s[52:53], v[222:223] op_sel_hi:[1,0,1]
	v_pk_fma_f32 v[224:225], v[200:201], s[54:55], v[224:225] op_sel_hi:[1,0,1]
	v_pk_fma_f32 v[226:227], v[202:203], s[54:55], v[226:227] op_sel_hi:[1,0,1]
	v_pk_fma_f32 v[228:229], v[200:201], s[56:57], v[228:229] op_sel_hi:[1,0,1]
	v_pk_fma_f32 v[230:231], v[202:203], s[56:57], v[230:231] op_sel_hi:[1,0,1]
	global_load_dwordx4 v[196:199], v[232:233], off offset:1024
	v_lshl_add_u64 v[232:233], v[232:233], 0, s[66:67]
	s_waitcnt vmcnt(10)
	v_readlane_b32 s50, v11, 9
	v_readlane_b32 s52, v54, 9
	v_readlane_b32 s54, v55, 9
	v_readlane_b32 s56, v56, 9
	v_pk_fma_f32 v[216:217], v[204:205], s[50:51], v[216:217] op_sel_hi:[1,0,1]
	v_pk_fma_f32 v[218:219], v[206:207], s[50:51], v[218:219] op_sel_hi:[1,0,1]
	v_pk_fma_f32 v[220:221], v[204:205], s[52:53], v[220:221] op_sel_hi:[1,0,1]
	v_pk_fma_f32 v[222:223], v[206:207], s[52:53], v[222:223] op_sel_hi:[1,0,1]
	v_pk_fma_f32 v[224:225], v[204:205], s[54:55], v[224:225] op_sel_hi:[1,0,1]
	v_pk_fma_f32 v[226:227], v[206:207], s[54:55], v[226:227] op_sel_hi:[1,0,1]
	v_pk_fma_f32 v[228:229], v[204:205], s[56:57], v[228:229] op_sel_hi:[1,0,1]
	v_pk_fma_f32 v[230:231], v[206:207], s[56:57], v[230:231] op_sel_hi:[1,0,1]
	global_load_dwordx4 v[200:203], v[232:233], off offset:-2048
	s_waitcnt vmcnt(10)
	v_readlane_b32 s50, v11, 10
	v_readlane_b32 s52, v54, 10
	v_readlane_b32 s54, v55, 10
	v_readlane_b32 s56, v56, 10
	v_pk_fma_f32 v[216:217], v[208:209], s[50:51], v[216:217] op_sel_hi:[1,0,1]
	v_pk_fma_f32 v[218:219], v[210:211], s[50:51], v[218:219] op_sel_hi:[1,0,1]
	v_pk_fma_f32 v[220:221], v[208:209], s[52:53], v[220:221] op_sel_hi:[1,0,1]
	v_pk_fma_f32 v[222:223], v[210:211], s[52:53], v[222:223] op_sel_hi:[1,0,1]
	v_pk_fma_f32 v[224:225], v[208:209], s[54:55], v[224:225] op_sel_hi:[1,0,1]
	v_pk_fma_f32 v[226:227], v[210:211], s[54:55], v[226:227] op_sel_hi:[1,0,1]
	v_pk_fma_f32 v[228:229], v[208:209], s[56:57], v[228:229] op_sel_hi:[1,0,1]
	v_pk_fma_f32 v[230:231], v[210:211], s[56:57], v[230:231] op_sel_hi:[1,0,1]
	global_load_dwordx4 v[204:207], v[232:233], off offset:-1024
	s_waitcnt vmcnt(10)
	v_readlane_b32 s50, v11, 11
	v_readlane_b32 s52, v54, 11
	v_readlane_b32 s54, v55, 11
	v_readlane_b32 s56, v56, 11
	v_pk_fma_f32 v[216:217], v[212:213], s[50:51], v[216:217] op_sel_hi:[1,0,1]
	v_pk_fma_f32 v[218:219], v[214:215], s[50:51], v[218:219] op_sel_hi:[1,0,1]
	v_pk_fma_f32 v[220:221], v[212:213], s[52:53], v[220:221] op_sel_hi:[1,0,1]
	v_pk_fma_f32 v[222:223], v[214:215], s[52:53], v[222:223] op_sel_hi:[1,0,1]
	v_pk_fma_f32 v[224:225], v[212:213], s[54:55], v[224:225] op_sel_hi:[1,0,1]
	v_pk_fma_f32 v[226:227], v[214:215], s[54:55], v[226:227] op_sel_hi:[1,0,1]
	v_pk_fma_f32 v[228:229], v[212:213], s[56:57], v[228:229] op_sel_hi:[1,0,1]
	v_pk_fma_f32 v[230:231], v[214:215], s[56:57], v[230:231] op_sel_hi:[1,0,1]
	global_load_dwordx4 v[208:211], v[232:233], off offset:0
	s_waitcnt vmcnt(10)
	v_readlane_b32 s50, v11, 12
	v_readlane_b32 s52, v54, 12
	v_readlane_b32 s54, v55, 12
	v_readlane_b32 s56, v56, 12
	v_pk_fma_f32 v[216:217], v[168:169], s[50:51], v[216:217] op_sel_hi:[1,0,1]
	v_pk_fma_f32 v[218:219], v[170:171], s[50:51], v[218:219] op_sel_hi:[1,0,1]
	v_pk_fma_f32 v[220:221], v[168:169], s[52:53], v[220:221] op_sel_hi:[1,0,1]
	v_pk_fma_f32 v[222:223], v[170:171], s[52:53], v[222:223] op_sel_hi:[1,0,1]
	v_pk_fma_f32 v[224:225], v[168:169], s[54:55], v[224:225] op_sel_hi:[1,0,1]
	v_pk_fma_f32 v[226:227], v[170:171], s[54:55], v[226:227] op_sel_hi:[1,0,1]
	v_pk_fma_f32 v[228:229], v[168:169], s[56:57], v[228:229] op_sel_hi:[1,0,1]
	v_pk_fma_f32 v[230:231], v[170:171], s[56:57], v[230:231] op_sel_hi:[1,0,1]
	global_load_dwordx4 v[212:215], v[232:233], off offset:1024
	v_lshl_add_u64 v[232:233], v[232:233], 0, s[66:67]
	s_waitcnt vmcnt(10)
	v_readlane_b32 s50, v11, 13
	v_readlane_b32 s52, v54, 13
	v_readlane_b32 s54, v55, 13
	v_readlane_b32 s56, v56, 13
	v_pk_fma_f32 v[216:217], v[172:173], s[50:51], v[216:217] op_sel_hi:[1,0,1]
	v_pk_fma_f32 v[218:219], v[174:175], s[50:51], v[218:219] op_sel_hi:[1,0,1]
	v_pk_fma_f32 v[220:221], v[172:173], s[52:53], v[220:221] op_sel_hi:[1,0,1]
	v_pk_fma_f32 v[222:223], v[174:175], s[52:53], v[222:223] op_sel_hi:[1,0,1]
	v_pk_fma_f32 v[224:225], v[172:173], s[54:55], v[224:225] op_sel_hi:[1,0,1]
	v_pk_fma_f32 v[226:227], v[174:175], s[54:55], v[226:227] op_sel_hi:[1,0,1]
	v_pk_fma_f32 v[228:229], v[172:173], s[56:57], v[228:229] op_sel_hi:[1,0,1]
	v_pk_fma_f32 v[230:231], v[174:175], s[56:57], v[230:231] op_sel_hi:[1,0,1]
	global_load_dwordx4 v[168:171], v[232:233], off offset:-2048
	s_waitcnt vmcnt(10)
	v_readlane_b32 s50, v11, 14
	v_readlane_b32 s52, v54, 14
	v_readlane_b32 s54, v55, 14
	v_readlane_b32 s56, v56, 14
	v_pk_fma_f32 v[216:217], v[176:177], s[50:51], v[216:217] op_sel_hi:[1,0,1]
	v_pk_fma_f32 v[218:219], v[178:179], s[50:51], v[218:219] op_sel_hi:[1,0,1]
	v_pk_fma_f32 v[220:221], v[176:177], s[52:53], v[220:221] op_sel_hi:[1,0,1]
	v_pk_fma_f32 v[222:223], v[178:179], s[52:53], v[222:223] op_sel_hi:[1,0,1]
	v_pk_fma_f32 v[224:225], v[176:177], s[54:55], v[224:225] op_sel_hi:[1,0,1]
	v_pk_fma_f32 v[226:227], v[178:179], s[54:55], v[226:227] op_sel_hi:[1,0,1]
	v_pk_fma_f32 v[228:229], v[176:177], s[56:57], v[228:229] op_sel_hi:[1,0,1]
	v_pk_fma_f32 v[230:231], v[178:179], s[56:57], v[230:231] op_sel_hi:[1,0,1]
	global_load_dwordx4 v[172:175], v[232:233], off offset:-1024
	s_waitcnt vmcnt(10)
	v_readlane_b32 s50, v11, 15
	v_readlane_b32 s52, v54, 15
	v_readlane_b32 s54, v55, 15
	v_readlane_b32 s56, v56, 15
	v_pk_fma_f32 v[216:217], v[180:181], s[50:51], v[216:217] op_sel_hi:[1,0,1]
	v_pk_fma_f32 v[218:219], v[182:183], s[50:51], v[218:219] op_sel_hi:[1,0,1]
	v_pk_fma_f32 v[220:221], v[180:181], s[52:53], v[220:221] op_sel_hi:[1,0,1]
	v_pk_fma_f32 v[222:223], v[182:183], s[52:53], v[222:223] op_sel_hi:[1,0,1]
	v_pk_fma_f32 v[224:225], v[180:181], s[54:55], v[224:225] op_sel_hi:[1,0,1]
	v_pk_fma_f32 v[226:227], v[182:183], s[54:55], v[226:227] op_sel_hi:[1,0,1]
	v_pk_fma_f32 v[228:229], v[180:181], s[56:57], v[228:229] op_sel_hi:[1,0,1]
	v_pk_fma_f32 v[230:231], v[182:183], s[56:57], v[230:231] op_sel_hi:[1,0,1]
	global_load_dwordx4 v[176:179], v[232:233], off offset:0
	s_waitcnt vmcnt(10)
	v_readlane_b32 s50, v11, 16
	v_readlane_b32 s52, v54, 16
	v_readlane_b32 s54, v55, 16
	v_readlane_b32 s56, v56, 16
	v_pk_fma_f32 v[216:217], v[184:185], s[50:51], v[216:217] op_sel_hi:[1,0,1]
	v_pk_fma_f32 v[218:219], v[186:187], s[50:51], v[218:219] op_sel_hi:[1,0,1]
	v_pk_fma_f32 v[220:221], v[184:185], s[52:53], v[220:221] op_sel_hi:[1,0,1]
	v_pk_fma_f32 v[222:223], v[186:187], s[52:53], v[222:223] op_sel_hi:[1,0,1]
	v_pk_fma_f32 v[224:225], v[184:185], s[54:55], v[224:225] op_sel_hi:[1,0,1]
	v_pk_fma_f32 v[226:227], v[186:187], s[54:55], v[226:227] op_sel_hi:[1,0,1]
	v_pk_fma_f32 v[228:229], v[184:185], s[56:57], v[228:229] op_sel_hi:[1,0,1]
	v_pk_fma_f32 v[230:231], v[186:187], s[56:57], v[230:231] op_sel_hi:[1,0,1]
	global_load_dwordx4 v[180:183], v[232:233], off offset:1024
	v_lshl_add_u64 v[232:233], v[232:233], 0, s[66:67]
	s_waitcnt vmcnt(10)
	v_readlane_b32 s50, v11, 17
	v_readlane_b32 s52, v54, 17
	v_readlane_b32 s54, v55, 17
	v_readlane_b32 s56, v56, 17
	v_pk_fma_f32 v[216:217], v[188:189], s[50:51], v[216:217] op_sel_hi:[1,0,1]
	v_pk_fma_f32 v[218:219], v[190:191], s[50:51], v[218:219] op_sel_hi:[1,0,1]
	v_pk_fma_f32 v[220:221], v[188:189], s[52:53], v[220:221] op_sel_hi:[1,0,1]
	v_pk_fma_f32 v[222:223], v[190:191], s[52:53], v[222:223] op_sel_hi:[1,0,1]
	v_pk_fma_f32 v[224:225], v[188:189], s[54:55], v[224:225] op_sel_hi:[1,0,1]
	v_pk_fma_f32 v[226:227], v[190:191], s[54:55], v[226:227] op_sel_hi:[1,0,1]
	v_pk_fma_f32 v[228:229], v[188:189], s[56:57], v[228:229] op_sel_hi:[1,0,1]
	v_pk_fma_f32 v[230:231], v[190:191], s[56:57], v[230:231] op_sel_hi:[1,0,1]
	global_load_dwordx4 v[184:187], v[232:233], off offset:-2048
	s_waitcnt vmcnt(10)
	v_readlane_b32 s50, v11, 18
	v_readlane_b32 s52, v54, 18
	v_readlane_b32 s54, v55, 18
	v_readlane_b32 s56, v56, 18
	v_pk_fma_f32 v[216:217], v[192:193], s[50:51], v[216:217] op_sel_hi:[1,0,1]
	v_pk_fma_f32 v[218:219], v[194:195], s[50:51], v[218:219] op_sel_hi:[1,0,1]
	v_pk_fma_f32 v[220:221], v[192:193], s[52:53], v[220:221] op_sel_hi:[1,0,1]
	v_pk_fma_f32 v[222:223], v[194:195], s[52:53], v[222:223] op_sel_hi:[1,0,1]
	v_pk_fma_f32 v[224:225], v[192:193], s[54:55], v[224:225] op_sel_hi:[1,0,1]
	v_pk_fma_f32 v[226:227], v[194:195], s[54:55], v[226:227] op_sel_hi:[1,0,1]
	v_pk_fma_f32 v[228:229], v[192:193], s[56:57], v[228:229] op_sel_hi:[1,0,1]
	v_pk_fma_f32 v[230:231], v[194:195], s[56:57], v[230:231] op_sel_hi:[1,0,1]
	global_load_dwordx4 v[188:191], v[232:233], off offset:-1024
	s_waitcnt vmcnt(10)
	v_readlane_b32 s50, v11, 19
	v_readlane_b32 s52, v54, 19
	v_readlane_b32 s54, v55, 19
	v_readlane_b32 s56, v56, 19
	v_pk_fma_f32 v[216:217], v[196:197], s[50:51], v[216:217] op_sel_hi:[1,0,1]
	v_pk_fma_f32 v[218:219], v[198:199], s[50:51], v[218:219] op_sel_hi:[1,0,1]
	v_pk_fma_f32 v[220:221], v[196:197], s[52:53], v[220:221] op_sel_hi:[1,0,1]
	v_pk_fma_f32 v[222:223], v[198:199], s[52:53], v[222:223] op_sel_hi:[1,0,1]
	v_pk_fma_f32 v[224:225], v[196:197], s[54:55], v[224:225] op_sel_hi:[1,0,1]
	v_pk_fma_f32 v[226:227], v[198:199], s[54:55], v[226:227] op_sel_hi:[1,0,1]
	v_pk_fma_f32 v[228:229], v[196:197], s[56:57], v[228:229] op_sel_hi:[1,0,1]
	v_pk_fma_f32 v[230:231], v[198:199], s[56:57], v[230:231] op_sel_hi:[1,0,1]
	global_load_dwordx4 v[192:195], v[232:233], off offset:0
	s_waitcnt vmcnt(10)
	v_readlane_b32 s50, v11, 20
	v_readlane_b32 s52, v54, 20
	v_readlane_b32 s54, v55, 20
	v_readlane_b32 s56, v56, 20
	v_pk_fma_f32 v[216:217], v[200:201], s[50:51], v[216:217] op_sel_hi:[1,0,1]
	v_pk_fma_f32 v[218:219], v[202:203], s[50:51], v[218:219] op_sel_hi:[1,0,1]
	v_pk_fma_f32 v[220:221], v[200:201], s[52:53], v[220:221] op_sel_hi:[1,0,1]
	v_pk_fma_f32 v[222:223], v[202:203], s[52:53], v[222:223] op_sel_hi:[1,0,1]
	v_pk_fma_f32 v[224:225], v[200:201], s[54:55], v[224:225] op_sel_hi:[1,0,1]
	v_pk_fma_f32 v[226:227], v[202:203], s[54:55], v[226:227] op_sel_hi:[1,0,1]
	v_pk_fma_f32 v[228:229], v[200:201], s[56:57], v[228:229] op_sel_hi:[1,0,1]
	v_pk_fma_f32 v[230:231], v[202:203], s[56:57], v[230:231] op_sel_hi:[1,0,1]
	global_load_dwordx4 v[196:199], v[232:233], off offset:1024
	v_lshl_add_u64 v[232:233], v[232:233], 0, s[66:67]
	s_waitcnt vmcnt(10)
	v_readlane_b32 s50, v11, 21
	v_readlane_b32 s52, v54, 21
	v_readlane_b32 s54, v55, 21
	v_readlane_b32 s56, v56, 21
	v_pk_fma_f32 v[216:217], v[204:205], s[50:51], v[216:217] op_sel_hi:[1,0,1]
	v_pk_fma_f32 v[218:219], v[206:207], s[50:51], v[218:219] op_sel_hi:[1,0,1]
	v_pk_fma_f32 v[220:221], v[204:205], s[52:53], v[220:221] op_sel_hi:[1,0,1]
	v_pk_fma_f32 v[222:223], v[206:207], s[52:53], v[222:223] op_sel_hi:[1,0,1]
	v_pk_fma_f32 v[224:225], v[204:205], s[54:55], v[224:225] op_sel_hi:[1,0,1]
	v_pk_fma_f32 v[226:227], v[206:207], s[54:55], v[226:227] op_sel_hi:[1,0,1]
	v_pk_fma_f32 v[228:229], v[204:205], s[56:57], v[228:229] op_sel_hi:[1,0,1]
	v_pk_fma_f32 v[230:231], v[206:207], s[56:57], v[230:231] op_sel_hi:[1,0,1]
	global_load_dwordx4 v[200:203], v[232:233], off offset:-2048
	s_waitcnt vmcnt(10)
	v_readlane_b32 s50, v11, 22
	v_readlane_b32 s52, v54, 22
	v_readlane_b32 s54, v55, 22
	v_readlane_b32 s56, v56, 22
	v_pk_fma_f32 v[216:217], v[208:209], s[50:51], v[216:217] op_sel_hi:[1,0,1]
	v_pk_fma_f32 v[218:219], v[210:211], s[50:51], v[218:219] op_sel_hi:[1,0,1]
	v_pk_fma_f32 v[220:221], v[208:209], s[52:53], v[220:221] op_sel_hi:[1,0,1]
	v_pk_fma_f32 v[222:223], v[210:211], s[52:53], v[222:223] op_sel_hi:[1,0,1]
	v_pk_fma_f32 v[224:225], v[208:209], s[54:55], v[224:225] op_sel_hi:[1,0,1]
	v_pk_fma_f32 v[226:227], v[210:211], s[54:55], v[226:227] op_sel_hi:[1,0,1]
	v_pk_fma_f32 v[228:229], v[208:209], s[56:57], v[228:229] op_sel_hi:[1,0,1]
	v_pk_fma_f32 v[230:231], v[210:211], s[56:57], v[230:231] op_sel_hi:[1,0,1]
	global_load_dwordx4 v[204:207], v[232:233], off offset:-1024
	s_waitcnt vmcnt(10)
	v_readlane_b32 s50, v11, 23
	v_readlane_b32 s52, v54, 23
	v_readlane_b32 s54, v55, 23
	v_readlane_b32 s56, v56, 23
	v_pk_fma_f32 v[216:217], v[212:213], s[50:51], v[216:217] op_sel_hi:[1,0,1]
	v_pk_fma_f32 v[218:219], v[214:215], s[50:51], v[218:219] op_sel_hi:[1,0,1]
	v_pk_fma_f32 v[220:221], v[212:213], s[52:53], v[220:221] op_sel_hi:[1,0,1]
	v_pk_fma_f32 v[222:223], v[214:215], s[52:53], v[222:223] op_sel_hi:[1,0,1]
	v_pk_fma_f32 v[224:225], v[212:213], s[54:55], v[224:225] op_sel_hi:[1,0,1]
	v_pk_fma_f32 v[226:227], v[214:215], s[54:55], v[226:227] op_sel_hi:[1,0,1]
	v_pk_fma_f32 v[228:229], v[212:213], s[56:57], v[228:229] op_sel_hi:[1,0,1]
	v_pk_fma_f32 v[230:231], v[214:215], s[56:57], v[230:231] op_sel_hi:[1,0,1]
	global_load_dwordx4 v[208:211], v[232:233], off offset:0
	s_waitcnt vmcnt(10)
	v_readlane_b32 s50, v11, 24
	v_readlane_b32 s52, v54, 24
	v_readlane_b32 s54, v55, 24
	v_readlane_b32 s56, v56, 24
	v_pk_fma_f32 v[216:217], v[168:169], s[50:51], v[216:217] op_sel_hi:[1,0,1]
	v_pk_fma_f32 v[218:219], v[170:171], s[50:51], v[218:219] op_sel_hi:[1,0,1]
	v_pk_fma_f32 v[220:221], v[168:169], s[52:53], v[220:221] op_sel_hi:[1,0,1]
	v_pk_fma_f32 v[222:223], v[170:171], s[52:53], v[222:223] op_sel_hi:[1,0,1]
	v_pk_fma_f32 v[224:225], v[168:169], s[54:55], v[224:225] op_sel_hi:[1,0,1]
	v_pk_fma_f32 v[226:227], v[170:171], s[54:55], v[226:227] op_sel_hi:[1,0,1]
	v_pk_fma_f32 v[228:229], v[168:169], s[56:57], v[228:229] op_sel_hi:[1,0,1]
	v_pk_fma_f32 v[230:231], v[170:171], s[56:57], v[230:231] op_sel_hi:[1,0,1]
	global_load_dwordx4 v[212:215], v[232:233], off offset:1024
	v_lshl_add_u64 v[232:233], v[232:233], 0, s[66:67]
	s_waitcnt vmcnt(10)
	v_readlane_b32 s50, v11, 25
	v_readlane_b32 s52, v54, 25
	v_readlane_b32 s54, v55, 25
	v_readlane_b32 s56, v56, 25
	v_pk_fma_f32 v[216:217], v[172:173], s[50:51], v[216:217] op_sel_hi:[1,0,1]
	v_pk_fma_f32 v[218:219], v[174:175], s[50:51], v[218:219] op_sel_hi:[1,0,1]
	v_pk_fma_f32 v[220:221], v[172:173], s[52:53], v[220:221] op_sel_hi:[1,0,1]
	v_pk_fma_f32 v[222:223], v[174:175], s[52:53], v[222:223] op_sel_hi:[1,0,1]
	v_pk_fma_f32 v[224:225], v[172:173], s[54:55], v[224:225] op_sel_hi:[1,0,1]
	v_pk_fma_f32 v[226:227], v[174:175], s[54:55], v[226:227] op_sel_hi:[1,0,1]
	v_pk_fma_f32 v[228:229], v[172:173], s[56:57], v[228:229] op_sel_hi:[1,0,1]
	v_pk_fma_f32 v[230:231], v[174:175], s[56:57], v[230:231] op_sel_hi:[1,0,1]
	global_load_dwordx4 v[168:171], v[232:233], off offset:-2048
	s_waitcnt vmcnt(10)
	v_readlane_b32 s50, v11, 26
	v_readlane_b32 s52, v54, 26
	v_readlane_b32 s54, v55, 26
	v_readlane_b32 s56, v56, 26
	v_pk_fma_f32 v[216:217], v[176:177], s[50:51], v[216:217] op_sel_hi:[1,0,1]
	v_pk_fma_f32 v[218:219], v[178:179], s[50:51], v[218:219] op_sel_hi:[1,0,1]
	v_pk_fma_f32 v[220:221], v[176:177], s[52:53], v[220:221] op_sel_hi:[1,0,1]
	v_pk_fma_f32 v[222:223], v[178:179], s[52:53], v[222:223] op_sel_hi:[1,0,1]
	v_pk_fma_f32 v[224:225], v[176:177], s[54:55], v[224:225] op_sel_hi:[1,0,1]
	v_pk_fma_f32 v[226:227], v[178:179], s[54:55], v[226:227] op_sel_hi:[1,0,1]
	v_pk_fma_f32 v[228:229], v[176:177], s[56:57], v[228:229] op_sel_hi:[1,0,1]
	v_pk_fma_f32 v[230:231], v[178:179], s[56:57], v[230:231] op_sel_hi:[1,0,1]
	global_load_dwordx4 v[172:175], v[232:233], off offset:-1024
	s_waitcnt vmcnt(10)
	v_readlane_b32 s50, v11, 27
	v_readlane_b32 s52, v54, 27
	v_readlane_b32 s54, v55, 27
	v_readlane_b32 s56, v56, 27
	v_pk_fma_f32 v[216:217], v[180:181], s[50:51], v[216:217] op_sel_hi:[1,0,1]
	v_pk_fma_f32 v[218:219], v[182:183], s[50:51], v[218:219] op_sel_hi:[1,0,1]
	v_pk_fma_f32 v[220:221], v[180:181], s[52:53], v[220:221] op_sel_hi:[1,0,1]
	v_pk_fma_f32 v[222:223], v[182:183], s[52:53], v[222:223] op_sel_hi:[1,0,1]
	v_pk_fma_f32 v[224:225], v[180:181], s[54:55], v[224:225] op_sel_hi:[1,0,1]
	v_pk_fma_f32 v[226:227], v[182:183], s[54:55], v[226:227] op_sel_hi:[1,0,1]
	v_pk_fma_f32 v[228:229], v[180:181], s[56:57], v[228:229] op_sel_hi:[1,0,1]
	v_pk_fma_f32 v[230:231], v[182:183], s[56:57], v[230:231] op_sel_hi:[1,0,1]
	global_load_dwordx4 v[176:179], v[232:233], off offset:0
	s_waitcnt vmcnt(10)
	v_readlane_b32 s50, v11, 28
	v_readlane_b32 s52, v54, 28
	v_readlane_b32 s54, v55, 28
	v_readlane_b32 s56, v56, 28
	v_pk_fma_f32 v[216:217], v[184:185], s[50:51], v[216:217] op_sel_hi:[1,0,1]
	v_pk_fma_f32 v[218:219], v[186:187], s[50:51], v[218:219] op_sel_hi:[1,0,1]
	v_pk_fma_f32 v[220:221], v[184:185], s[52:53], v[220:221] op_sel_hi:[1,0,1]
	v_pk_fma_f32 v[222:223], v[186:187], s[52:53], v[222:223] op_sel_hi:[1,0,1]
	v_pk_fma_f32 v[224:225], v[184:185], s[54:55], v[224:225] op_sel_hi:[1,0,1]
	v_pk_fma_f32 v[226:227], v[186:187], s[54:55], v[226:227] op_sel_hi:[1,0,1]
	v_pk_fma_f32 v[228:229], v[184:185], s[56:57], v[228:229] op_sel_hi:[1,0,1]
	v_pk_fma_f32 v[230:231], v[186:187], s[56:57], v[230:231] op_sel_hi:[1,0,1]
	global_load_dwordx4 v[180:183], v[232:233], off offset:1024
	v_lshl_add_u64 v[232:233], v[232:233], 0, s[66:67]
	s_waitcnt vmcnt(10)
	v_readlane_b32 s50, v11, 29
	v_readlane_b32 s52, v54, 29
	v_readlane_b32 s54, v55, 29
	v_readlane_b32 s56, v56, 29
	v_pk_fma_f32 v[216:217], v[188:189], s[50:51], v[216:217] op_sel_hi:[1,0,1]
	v_pk_fma_f32 v[218:219], v[190:191], s[50:51], v[218:219] op_sel_hi:[1,0,1]
	v_pk_fma_f32 v[220:221], v[188:189], s[52:53], v[220:221] op_sel_hi:[1,0,1]
	v_pk_fma_f32 v[222:223], v[190:191], s[52:53], v[222:223] op_sel_hi:[1,0,1]
	v_pk_fma_f32 v[224:225], v[188:189], s[54:55], v[224:225] op_sel_hi:[1,0,1]
	v_pk_fma_f32 v[226:227], v[190:191], s[54:55], v[226:227] op_sel_hi:[1,0,1]
	v_pk_fma_f32 v[228:229], v[188:189], s[56:57], v[228:229] op_sel_hi:[1,0,1]
	v_pk_fma_f32 v[230:231], v[190:191], s[56:57], v[230:231] op_sel_hi:[1,0,1]
	global_load_dwordx4 v[184:187], v[232:233], off offset:-2048
	s_waitcnt vmcnt(10)
	v_readlane_b32 s50, v11, 30
	v_readlane_b32 s52, v54, 30
	v_readlane_b32 s54, v55, 30
	v_readlane_b32 s56, v56, 30
	v_pk_fma_f32 v[216:217], v[192:193], s[50:51], v[216:217] op_sel_hi:[1,0,1]
	v_pk_fma_f32 v[218:219], v[194:195], s[50:51], v[218:219] op_sel_hi:[1,0,1]
	v_pk_fma_f32 v[220:221], v[192:193], s[52:53], v[220:221] op_sel_hi:[1,0,1]
	v_pk_fma_f32 v[222:223], v[194:195], s[52:53], v[222:223] op_sel_hi:[1,0,1]
	v_pk_fma_f32 v[224:225], v[192:193], s[54:55], v[224:225] op_sel_hi:[1,0,1]
	v_pk_fma_f32 v[226:227], v[194:195], s[54:55], v[226:227] op_sel_hi:[1,0,1]
	v_pk_fma_f32 v[228:229], v[192:193], s[56:57], v[228:229] op_sel_hi:[1,0,1]
	v_pk_fma_f32 v[230:231], v[194:195], s[56:57], v[230:231] op_sel_hi:[1,0,1]
	global_load_dwordx4 v[188:191], v[232:233], off offset:-1024
	s_waitcnt vmcnt(10)
	v_readlane_b32 s50, v11, 31
	v_readlane_b32 s52, v54, 31
	v_readlane_b32 s54, v55, 31
	v_readlane_b32 s56, v56, 31
	v_pk_fma_f32 v[216:217], v[196:197], s[50:51], v[216:217] op_sel_hi:[1,0,1]
	v_pk_fma_f32 v[218:219], v[198:199], s[50:51], v[218:219] op_sel_hi:[1,0,1]
	v_pk_fma_f32 v[220:221], v[196:197], s[52:53], v[220:221] op_sel_hi:[1,0,1]
	v_pk_fma_f32 v[222:223], v[198:199], s[52:53], v[222:223] op_sel_hi:[1,0,1]
	v_pk_fma_f32 v[224:225], v[196:197], s[54:55], v[224:225] op_sel_hi:[1,0,1]
	v_pk_fma_f32 v[226:227], v[198:199], s[54:55], v[226:227] op_sel_hi:[1,0,1]
	v_pk_fma_f32 v[228:229], v[196:197], s[56:57], v[228:229] op_sel_hi:[1,0,1]
	v_pk_fma_f32 v[230:231], v[198:199], s[56:57], v[230:231] op_sel_hi:[1,0,1]
	global_load_dwordx4 v[192:195], v[232:233], off offset:0
	s_waitcnt vmcnt(10)
	v_readlane_b32 s50, v11, 32
	v_readlane_b32 s52, v54, 32
	v_readlane_b32 s54, v55, 32
	v_readlane_b32 s56, v56, 32
	v_pk_fma_f32 v[216:217], v[200:201], s[50:51], v[216:217] op_sel_hi:[1,0,1]
	v_pk_fma_f32 v[218:219], v[202:203], s[50:51], v[218:219] op_sel_hi:[1,0,1]
	v_pk_fma_f32 v[220:221], v[200:201], s[52:53], v[220:221] op_sel_hi:[1,0,1]
	v_pk_fma_f32 v[222:223], v[202:203], s[52:53], v[222:223] op_sel_hi:[1,0,1]
	v_pk_fma_f32 v[224:225], v[200:201], s[54:55], v[224:225] op_sel_hi:[1,0,1]
	v_pk_fma_f32 v[226:227], v[202:203], s[54:55], v[226:227] op_sel_hi:[1,0,1]
	v_pk_fma_f32 v[228:229], v[200:201], s[56:57], v[228:229] op_sel_hi:[1,0,1]
	v_pk_fma_f32 v[230:231], v[202:203], s[56:57], v[230:231] op_sel_hi:[1,0,1]
	global_load_dwordx4 v[196:199], v[232:233], off offset:1024
	v_lshl_add_u64 v[232:233], v[232:233], 0, s[66:67]
	s_waitcnt vmcnt(10)
	v_readlane_b32 s50, v11, 33
	v_readlane_b32 s52, v54, 33
	v_readlane_b32 s54, v55, 33
	v_readlane_b32 s56, v56, 33
	v_pk_fma_f32 v[216:217], v[204:205], s[50:51], v[216:217] op_sel_hi:[1,0,1]
	v_pk_fma_f32 v[218:219], v[206:207], s[50:51], v[218:219] op_sel_hi:[1,0,1]
	v_pk_fma_f32 v[220:221], v[204:205], s[52:53], v[220:221] op_sel_hi:[1,0,1]
	v_pk_fma_f32 v[222:223], v[206:207], s[52:53], v[222:223] op_sel_hi:[1,0,1]
	v_pk_fma_f32 v[224:225], v[204:205], s[54:55], v[224:225] op_sel_hi:[1,0,1]
	v_pk_fma_f32 v[226:227], v[206:207], s[54:55], v[226:227] op_sel_hi:[1,0,1]
	v_pk_fma_f32 v[228:229], v[204:205], s[56:57], v[228:229] op_sel_hi:[1,0,1]
	v_pk_fma_f32 v[230:231], v[206:207], s[56:57], v[230:231] op_sel_hi:[1,0,1]
	global_load_dwordx4 v[200:203], v[232:233], off offset:-2048
	s_waitcnt vmcnt(10)
	v_readlane_b32 s50, v11, 34
	v_readlane_b32 s52, v54, 34
	v_readlane_b32 s54, v55, 34
	v_readlane_b32 s56, v56, 34
	v_pk_fma_f32 v[216:217], v[208:209], s[50:51], v[216:217] op_sel_hi:[1,0,1]
	v_pk_fma_f32 v[218:219], v[210:211], s[50:51], v[218:219] op_sel_hi:[1,0,1]
	v_pk_fma_f32 v[220:221], v[208:209], s[52:53], v[220:221] op_sel_hi:[1,0,1]
	v_pk_fma_f32 v[222:223], v[210:211], s[52:53], v[222:223] op_sel_hi:[1,0,1]
	v_pk_fma_f32 v[224:225], v[208:209], s[54:55], v[224:225] op_sel_hi:[1,0,1]
	v_pk_fma_f32 v[226:227], v[210:211], s[54:55], v[226:227] op_sel_hi:[1,0,1]
	v_pk_fma_f32 v[228:229], v[208:209], s[56:57], v[228:229] op_sel_hi:[1,0,1]
	v_pk_fma_f32 v[230:231], v[210:211], s[56:57], v[230:231] op_sel_hi:[1,0,1]
	global_load_dwordx4 v[204:207], v[232:233], off offset:-1024
	s_waitcnt vmcnt(10)
	v_readlane_b32 s50, v11, 35
	v_readlane_b32 s52, v54, 35
	v_readlane_b32 s54, v55, 35
	v_readlane_b32 s56, v56, 35
	v_pk_fma_f32 v[216:217], v[212:213], s[50:51], v[216:217] op_sel_hi:[1,0,1]
	v_pk_fma_f32 v[218:219], v[214:215], s[50:51], v[218:219] op_sel_hi:[1,0,1]
	v_pk_fma_f32 v[220:221], v[212:213], s[52:53], v[220:221] op_sel_hi:[1,0,1]
	v_pk_fma_f32 v[222:223], v[214:215], s[52:53], v[222:223] op_sel_hi:[1,0,1]
	v_pk_fma_f32 v[224:225], v[212:213], s[54:55], v[224:225] op_sel_hi:[1,0,1]
	v_pk_fma_f32 v[226:227], v[214:215], s[54:55], v[226:227] op_sel_hi:[1,0,1]
	v_pk_fma_f32 v[228:229], v[212:213], s[56:57], v[228:229] op_sel_hi:[1,0,1]
	v_pk_fma_f32 v[230:231], v[214:215], s[56:57], v[230:231] op_sel_hi:[1,0,1]
	global_load_dwordx4 v[208:211], v[232:233], off offset:0
	s_waitcnt vmcnt(10)
	v_readlane_b32 s50, v11, 36
	v_readlane_b32 s52, v54, 36
	v_readlane_b32 s54, v55, 36
	v_readlane_b32 s56, v56, 36
	v_pk_fma_f32 v[216:217], v[168:169], s[50:51], v[216:217] op_sel_hi:[1,0,1]
	v_pk_fma_f32 v[218:219], v[170:171], s[50:51], v[218:219] op_sel_hi:[1,0,1]
	v_pk_fma_f32 v[220:221], v[168:169], s[52:53], v[220:221] op_sel_hi:[1,0,1]
	v_pk_fma_f32 v[222:223], v[170:171], s[52:53], v[222:223] op_sel_hi:[1,0,1]
	v_pk_fma_f32 v[224:225], v[168:169], s[54:55], v[224:225] op_sel_hi:[1,0,1]
	v_pk_fma_f32 v[226:227], v[170:171], s[54:55], v[226:227] op_sel_hi:[1,0,1]
	v_pk_fma_f32 v[228:229], v[168:169], s[56:57], v[228:229] op_sel_hi:[1,0,1]
	v_pk_fma_f32 v[230:231], v[170:171], s[56:57], v[230:231] op_sel_hi:[1,0,1]
	global_load_dwordx4 v[212:215], v[232:233], off offset:1024
	v_lshl_add_u64 v[232:233], v[232:233], 0, s[66:67]
	s_waitcnt vmcnt(10)
	v_readlane_b32 s50, v11, 37
	v_readlane_b32 s52, v54, 37
	v_readlane_b32 s54, v55, 37
	v_readlane_b32 s56, v56, 37
	v_pk_fma_f32 v[216:217], v[172:173], s[50:51], v[216:217] op_sel_hi:[1,0,1]
	v_pk_fma_f32 v[218:219], v[174:175], s[50:51], v[218:219] op_sel_hi:[1,0,1]
	v_pk_fma_f32 v[220:221], v[172:173], s[52:53], v[220:221] op_sel_hi:[1,0,1]
	v_pk_fma_f32 v[222:223], v[174:175], s[52:53], v[222:223] op_sel_hi:[1,0,1]
	v_pk_fma_f32 v[224:225], v[172:173], s[54:55], v[224:225] op_sel_hi:[1,0,1]
	v_pk_fma_f32 v[226:227], v[174:175], s[54:55], v[226:227] op_sel_hi:[1,0,1]
	v_pk_fma_f32 v[228:229], v[172:173], s[56:57], v[228:229] op_sel_hi:[1,0,1]
	v_pk_fma_f32 v[230:231], v[174:175], s[56:57], v[230:231] op_sel_hi:[1,0,1]
	global_load_dwordx4 v[168:171], v[232:233], off offset:-2048
	s_waitcnt vmcnt(10)
	v_readlane_b32 s50, v11, 38
	v_readlane_b32 s52, v54, 38
	v_readlane_b32 s54, v55, 38
	v_readlane_b32 s56, v56, 38
	v_pk_fma_f32 v[216:217], v[176:177], s[50:51], v[216:217] op_sel_hi:[1,0,1]
	v_pk_fma_f32 v[218:219], v[178:179], s[50:51], v[218:219] op_sel_hi:[1,0,1]
	v_pk_fma_f32 v[220:221], v[176:177], s[52:53], v[220:221] op_sel_hi:[1,0,1]
	v_pk_fma_f32 v[222:223], v[178:179], s[52:53], v[222:223] op_sel_hi:[1,0,1]
	v_pk_fma_f32 v[224:225], v[176:177], s[54:55], v[224:225] op_sel_hi:[1,0,1]
	v_pk_fma_f32 v[226:227], v[178:179], s[54:55], v[226:227] op_sel_hi:[1,0,1]
	v_pk_fma_f32 v[228:229], v[176:177], s[56:57], v[228:229] op_sel_hi:[1,0,1]
	v_pk_fma_f32 v[230:231], v[178:179], s[56:57], v[230:231] op_sel_hi:[1,0,1]
	global_load_dwordx4 v[172:175], v[232:233], off offset:-1024
	s_waitcnt vmcnt(10)
	v_readlane_b32 s50, v11, 39
	v_readlane_b32 s52, v54, 39
	v_readlane_b32 s54, v55, 39
	v_readlane_b32 s56, v56, 39
	v_pk_fma_f32 v[216:217], v[180:181], s[50:51], v[216:217] op_sel_hi:[1,0,1]
	v_pk_fma_f32 v[218:219], v[182:183], s[50:51], v[218:219] op_sel_hi:[1,0,1]
	v_pk_fma_f32 v[220:221], v[180:181], s[52:53], v[220:221] op_sel_hi:[1,0,1]
	v_pk_fma_f32 v[222:223], v[182:183], s[52:53], v[222:223] op_sel_hi:[1,0,1]
	v_pk_fma_f32 v[224:225], v[180:181], s[54:55], v[224:225] op_sel_hi:[1,0,1]
	v_pk_fma_f32 v[226:227], v[182:183], s[54:55], v[226:227] op_sel_hi:[1,0,1]
	v_pk_fma_f32 v[228:229], v[180:181], s[56:57], v[228:229] op_sel_hi:[1,0,1]
	v_pk_fma_f32 v[230:231], v[182:183], s[56:57], v[230:231] op_sel_hi:[1,0,1]
	global_load_dwordx4 v[176:179], v[232:233], off offset:0
	s_waitcnt vmcnt(10)
	v_readlane_b32 s50, v11, 40
	v_readlane_b32 s52, v54, 40
	v_readlane_b32 s54, v55, 40
	v_readlane_b32 s56, v56, 40
	v_pk_fma_f32 v[216:217], v[184:185], s[50:51], v[216:217] op_sel_hi:[1,0,1]
	v_pk_fma_f32 v[218:219], v[186:187], s[50:51], v[218:219] op_sel_hi:[1,0,1]
	v_pk_fma_f32 v[220:221], v[184:185], s[52:53], v[220:221] op_sel_hi:[1,0,1]
	v_pk_fma_f32 v[222:223], v[186:187], s[52:53], v[222:223] op_sel_hi:[1,0,1]
	v_pk_fma_f32 v[224:225], v[184:185], s[54:55], v[224:225] op_sel_hi:[1,0,1]
	v_pk_fma_f32 v[226:227], v[186:187], s[54:55], v[226:227] op_sel_hi:[1,0,1]
	v_pk_fma_f32 v[228:229], v[184:185], s[56:57], v[228:229] op_sel_hi:[1,0,1]
	v_pk_fma_f32 v[230:231], v[186:187], s[56:57], v[230:231] op_sel_hi:[1,0,1]
	global_load_dwordx4 v[180:183], v[232:233], off offset:1024
	v_lshl_add_u64 v[232:233], v[232:233], 0, s[66:67]
	s_waitcnt vmcnt(10)
	v_readlane_b32 s50, v11, 41
	v_readlane_b32 s52, v54, 41
	v_readlane_b32 s54, v55, 41
	v_readlane_b32 s56, v56, 41
	v_pk_fma_f32 v[216:217], v[188:189], s[50:51], v[216:217] op_sel_hi:[1,0,1]
	v_pk_fma_f32 v[218:219], v[190:191], s[50:51], v[218:219] op_sel_hi:[1,0,1]
	v_pk_fma_f32 v[220:221], v[188:189], s[52:53], v[220:221] op_sel_hi:[1,0,1]
	v_pk_fma_f32 v[222:223], v[190:191], s[52:53], v[222:223] op_sel_hi:[1,0,1]
	v_pk_fma_f32 v[224:225], v[188:189], s[54:55], v[224:225] op_sel_hi:[1,0,1]
	v_pk_fma_f32 v[226:227], v[190:191], s[54:55], v[226:227] op_sel_hi:[1,0,1]
	v_pk_fma_f32 v[228:229], v[188:189], s[56:57], v[228:229] op_sel_hi:[1,0,1]
	v_pk_fma_f32 v[230:231], v[190:191], s[56:57], v[230:231] op_sel_hi:[1,0,1]
	global_load_dwordx4 v[184:187], v[232:233], off offset:-2048
	s_waitcnt vmcnt(10)
	v_readlane_b32 s50, v11, 42
	v_readlane_b32 s52, v54, 42
	v_readlane_b32 s54, v55, 42
	v_readlane_b32 s56, v56, 42
	v_pk_fma_f32 v[216:217], v[192:193], s[50:51], v[216:217] op_sel_hi:[1,0,1]
	v_pk_fma_f32 v[218:219], v[194:195], s[50:51], v[218:219] op_sel_hi:[1,0,1]
	v_pk_fma_f32 v[220:221], v[192:193], s[52:53], v[220:221] op_sel_hi:[1,0,1]
	v_pk_fma_f32 v[222:223], v[194:195], s[52:53], v[222:223] op_sel_hi:[1,0,1]
	v_pk_fma_f32 v[224:225], v[192:193], s[54:55], v[224:225] op_sel_hi:[1,0,1]
	v_pk_fma_f32 v[226:227], v[194:195], s[54:55], v[226:227] op_sel_hi:[1,0,1]
	v_pk_fma_f32 v[228:229], v[192:193], s[56:57], v[228:229] op_sel_hi:[1,0,1]
	v_pk_fma_f32 v[230:231], v[194:195], s[56:57], v[230:231] op_sel_hi:[1,0,1]
	global_load_dwordx4 v[188:191], v[232:233], off offset:-1024
	s_waitcnt vmcnt(10)
	v_readlane_b32 s50, v11, 43
	v_readlane_b32 s52, v54, 43
	v_readlane_b32 s54, v55, 43
	v_readlane_b32 s56, v56, 43
	v_pk_fma_f32 v[216:217], v[196:197], s[50:51], v[216:217] op_sel_hi:[1,0,1]
	v_pk_fma_f32 v[218:219], v[198:199], s[50:51], v[218:219] op_sel_hi:[1,0,1]
	v_pk_fma_f32 v[220:221], v[196:197], s[52:53], v[220:221] op_sel_hi:[1,0,1]
	v_pk_fma_f32 v[222:223], v[198:199], s[52:53], v[222:223] op_sel_hi:[1,0,1]
	v_pk_fma_f32 v[224:225], v[196:197], s[54:55], v[224:225] op_sel_hi:[1,0,1]
	v_pk_fma_f32 v[226:227], v[198:199], s[54:55], v[226:227] op_sel_hi:[1,0,1]
	v_pk_fma_f32 v[228:229], v[196:197], s[56:57], v[228:229] op_sel_hi:[1,0,1]
	v_pk_fma_f32 v[230:231], v[198:199], s[56:57], v[230:231] op_sel_hi:[1,0,1]
	global_load_dwordx4 v[192:195], v[232:233], off offset:0
	s_waitcnt vmcnt(10)
	v_readlane_b32 s50, v11, 44
	v_readlane_b32 s52, v54, 44
	v_readlane_b32 s54, v55, 44
	v_readlane_b32 s56, v56, 44
	v_pk_fma_f32 v[216:217], v[200:201], s[50:51], v[216:217] op_sel_hi:[1,0,1]
	v_pk_fma_f32 v[218:219], v[202:203], s[50:51], v[218:219] op_sel_hi:[1,0,1]
	v_pk_fma_f32 v[220:221], v[200:201], s[52:53], v[220:221] op_sel_hi:[1,0,1]
	v_pk_fma_f32 v[222:223], v[202:203], s[52:53], v[222:223] op_sel_hi:[1,0,1]
	v_pk_fma_f32 v[224:225], v[200:201], s[54:55], v[224:225] op_sel_hi:[1,0,1]
	v_pk_fma_f32 v[226:227], v[202:203], s[54:55], v[226:227] op_sel_hi:[1,0,1]
	v_pk_fma_f32 v[228:229], v[200:201], s[56:57], v[228:229] op_sel_hi:[1,0,1]
	v_pk_fma_f32 v[230:231], v[202:203], s[56:57], v[230:231] op_sel_hi:[1,0,1]
	global_load_dwordx4 v[196:199], v[232:233], off offset:1024
	v_lshl_add_u64 v[232:233], v[232:233], 0, s[66:67]
	s_waitcnt vmcnt(10)
	v_readlane_b32 s50, v11, 45
	v_readlane_b32 s52, v54, 45
	v_readlane_b32 s54, v55, 45
	v_readlane_b32 s56, v56, 45
	v_pk_fma_f32 v[216:217], v[204:205], s[50:51], v[216:217] op_sel_hi:[1,0,1]
	v_pk_fma_f32 v[218:219], v[206:207], s[50:51], v[218:219] op_sel_hi:[1,0,1]
	v_pk_fma_f32 v[220:221], v[204:205], s[52:53], v[220:221] op_sel_hi:[1,0,1]
	v_pk_fma_f32 v[222:223], v[206:207], s[52:53], v[222:223] op_sel_hi:[1,0,1]
	v_pk_fma_f32 v[224:225], v[204:205], s[54:55], v[224:225] op_sel_hi:[1,0,1]
	v_pk_fma_f32 v[226:227], v[206:207], s[54:55], v[226:227] op_sel_hi:[1,0,1]
	v_pk_fma_f32 v[228:229], v[204:205], s[56:57], v[228:229] op_sel_hi:[1,0,1]
	v_pk_fma_f32 v[230:231], v[206:207], s[56:57], v[230:231] op_sel_hi:[1,0,1]
	global_load_dwordx4 v[200:203], v[232:233], off offset:-2048
	s_waitcnt vmcnt(10)
	v_readlane_b32 s50, v11, 46
	v_readlane_b32 s52, v54, 46
	v_readlane_b32 s54, v55, 46
	v_readlane_b32 s56, v56, 46
	v_pk_fma_f32 v[216:217], v[208:209], s[50:51], v[216:217] op_sel_hi:[1,0,1]
	v_pk_fma_f32 v[218:219], v[210:211], s[50:51], v[218:219] op_sel_hi:[1,0,1]
	v_pk_fma_f32 v[220:221], v[208:209], s[52:53], v[220:221] op_sel_hi:[1,0,1]
	v_pk_fma_f32 v[222:223], v[210:211], s[52:53], v[222:223] op_sel_hi:[1,0,1]
	v_pk_fma_f32 v[224:225], v[208:209], s[54:55], v[224:225] op_sel_hi:[1,0,1]
	v_pk_fma_f32 v[226:227], v[210:211], s[54:55], v[226:227] op_sel_hi:[1,0,1]
	v_pk_fma_f32 v[228:229], v[208:209], s[56:57], v[228:229] op_sel_hi:[1,0,1]
	v_pk_fma_f32 v[230:231], v[210:211], s[56:57], v[230:231] op_sel_hi:[1,0,1]
	global_load_dwordx4 v[204:207], v[232:233], off offset:-1024
	s_waitcnt vmcnt(10)
	v_readlane_b32 s50, v11, 47
	v_readlane_b32 s52, v54, 47
	v_readlane_b32 s54, v55, 47
	v_readlane_b32 s56, v56, 47
	v_pk_fma_f32 v[216:217], v[212:213], s[50:51], v[216:217] op_sel_hi:[1,0,1]
	v_pk_fma_f32 v[218:219], v[214:215], s[50:51], v[218:219] op_sel_hi:[1,0,1]
	v_pk_fma_f32 v[220:221], v[212:213], s[52:53], v[220:221] op_sel_hi:[1,0,1]
	v_pk_fma_f32 v[222:223], v[214:215], s[52:53], v[222:223] op_sel_hi:[1,0,1]
	v_pk_fma_f32 v[224:225], v[212:213], s[54:55], v[224:225] op_sel_hi:[1,0,1]
	v_pk_fma_f32 v[226:227], v[214:215], s[54:55], v[226:227] op_sel_hi:[1,0,1]
	v_pk_fma_f32 v[228:229], v[212:213], s[56:57], v[228:229] op_sel_hi:[1,0,1]
	v_pk_fma_f32 v[230:231], v[214:215], s[56:57], v[230:231] op_sel_hi:[1,0,1]
	global_load_dwordx4 v[208:211], v[232:233], off offset:0
	s_waitcnt vmcnt(10)
	v_readlane_b32 s50, v11, 48
	v_readlane_b32 s52, v54, 48
	v_readlane_b32 s54, v55, 48
	v_readlane_b32 s56, v56, 48
	v_pk_fma_f32 v[216:217], v[168:169], s[50:51], v[216:217] op_sel_hi:[1,0,1]
	v_pk_fma_f32 v[218:219], v[170:171], s[50:51], v[218:219] op_sel_hi:[1,0,1]
	v_pk_fma_f32 v[220:221], v[168:169], s[52:53], v[220:221] op_sel_hi:[1,0,1]
	v_pk_fma_f32 v[222:223], v[170:171], s[52:53], v[222:223] op_sel_hi:[1,0,1]
	v_pk_fma_f32 v[224:225], v[168:169], s[54:55], v[224:225] op_sel_hi:[1,0,1]
	v_pk_fma_f32 v[226:227], v[170:171], s[54:55], v[226:227] op_sel_hi:[1,0,1]
	v_pk_fma_f32 v[228:229], v[168:169], s[56:57], v[228:229] op_sel_hi:[1,0,1]
	v_pk_fma_f32 v[230:231], v[170:171], s[56:57], v[230:231] op_sel_hi:[1,0,1]
	global_load_dwordx4 v[212:215], v[232:233], off offset:1024
	v_lshl_add_u64 v[232:233], v[232:233], 0, s[66:67]
	s_waitcnt vmcnt(10)
	v_readlane_b32 s50, v11, 49
	v_readlane_b32 s52, v54, 49
	v_readlane_b32 s54, v55, 49
	v_readlane_b32 s56, v56, 49
	v_pk_fma_f32 v[216:217], v[172:173], s[50:51], v[216:217] op_sel_hi:[1,0,1]
	v_pk_fma_f32 v[218:219], v[174:175], s[50:51], v[218:219] op_sel_hi:[1,0,1]
	v_pk_fma_f32 v[220:221], v[172:173], s[52:53], v[220:221] op_sel_hi:[1,0,1]
	v_pk_fma_f32 v[222:223], v[174:175], s[52:53], v[222:223] op_sel_hi:[1,0,1]
	v_pk_fma_f32 v[224:225], v[172:173], s[54:55], v[224:225] op_sel_hi:[1,0,1]
	v_pk_fma_f32 v[226:227], v[174:175], s[54:55], v[226:227] op_sel_hi:[1,0,1]
	v_pk_fma_f32 v[228:229], v[172:173], s[56:57], v[228:229] op_sel_hi:[1,0,1]
	v_pk_fma_f32 v[230:231], v[174:175], s[56:57], v[230:231] op_sel_hi:[1,0,1]
	global_load_dwordx4 v[168:171], v[232:233], off offset:-2048
	s_waitcnt vmcnt(10)
	v_readlane_b32 s50, v11, 50
	v_readlane_b32 s52, v54, 50
	v_readlane_b32 s54, v55, 50
	v_readlane_b32 s56, v56, 50
	v_pk_fma_f32 v[216:217], v[176:177], s[50:51], v[216:217] op_sel_hi:[1,0,1]
	v_pk_fma_f32 v[218:219], v[178:179], s[50:51], v[218:219] op_sel_hi:[1,0,1]
	v_pk_fma_f32 v[220:221], v[176:177], s[52:53], v[220:221] op_sel_hi:[1,0,1]
	v_pk_fma_f32 v[222:223], v[178:179], s[52:53], v[222:223] op_sel_hi:[1,0,1]
	v_pk_fma_f32 v[224:225], v[176:177], s[54:55], v[224:225] op_sel_hi:[1,0,1]
	v_pk_fma_f32 v[226:227], v[178:179], s[54:55], v[226:227] op_sel_hi:[1,0,1]
	v_pk_fma_f32 v[228:229], v[176:177], s[56:57], v[228:229] op_sel_hi:[1,0,1]
	v_pk_fma_f32 v[230:231], v[178:179], s[56:57], v[230:231] op_sel_hi:[1,0,1]
	global_load_dwordx4 v[172:175], v[232:233], off offset:-1024
	s_waitcnt vmcnt(10)
	v_readlane_b32 s50, v11, 51
	v_readlane_b32 s52, v54, 51
	v_readlane_b32 s54, v55, 51
	v_readlane_b32 s56, v56, 51
	v_pk_fma_f32 v[216:217], v[180:181], s[50:51], v[216:217] op_sel_hi:[1,0,1]
	v_pk_fma_f32 v[218:219], v[182:183], s[50:51], v[218:219] op_sel_hi:[1,0,1]
	v_pk_fma_f32 v[220:221], v[180:181], s[52:53], v[220:221] op_sel_hi:[1,0,1]
	v_pk_fma_f32 v[222:223], v[182:183], s[52:53], v[222:223] op_sel_hi:[1,0,1]
	v_pk_fma_f32 v[224:225], v[180:181], s[54:55], v[224:225] op_sel_hi:[1,0,1]
	v_pk_fma_f32 v[226:227], v[182:183], s[54:55], v[226:227] op_sel_hi:[1,0,1]
	v_pk_fma_f32 v[228:229], v[180:181], s[56:57], v[228:229] op_sel_hi:[1,0,1]
	v_pk_fma_f32 v[230:231], v[182:183], s[56:57], v[230:231] op_sel_hi:[1,0,1]
	global_load_dwordx4 v[176:179], v[232:233], off offset:0
	s_waitcnt vmcnt(10)
	v_readlane_b32 s50, v11, 52
	v_readlane_b32 s52, v54, 52
	v_readlane_b32 s54, v55, 52
	v_readlane_b32 s56, v56, 52
	v_pk_fma_f32 v[216:217], v[184:185], s[50:51], v[216:217] op_sel_hi:[1,0,1]
	v_pk_fma_f32 v[218:219], v[186:187], s[50:51], v[218:219] op_sel_hi:[1,0,1]
	v_pk_fma_f32 v[220:221], v[184:185], s[52:53], v[220:221] op_sel_hi:[1,0,1]
	v_pk_fma_f32 v[222:223], v[186:187], s[52:53], v[222:223] op_sel_hi:[1,0,1]
	v_pk_fma_f32 v[224:225], v[184:185], s[54:55], v[224:225] op_sel_hi:[1,0,1]
	v_pk_fma_f32 v[226:227], v[186:187], s[54:55], v[226:227] op_sel_hi:[1,0,1]
	v_pk_fma_f32 v[228:229], v[184:185], s[56:57], v[228:229] op_sel_hi:[1,0,1]
	v_pk_fma_f32 v[230:231], v[186:187], s[56:57], v[230:231] op_sel_hi:[1,0,1]
	global_load_dwordx4 v[180:183], v[232:233], off offset:1024
	s_waitcnt vmcnt(10)
	v_readlane_b32 s50, v11, 53
	v_readlane_b32 s52, v54, 53
	v_readlane_b32 s54, v55, 53
	v_readlane_b32 s56, v56, 53
	v_pk_fma_f32 v[216:217], v[188:189], s[50:51], v[216:217] op_sel_hi:[1,0,1]
	v_pk_fma_f32 v[218:219], v[190:191], s[50:51], v[218:219] op_sel_hi:[1,0,1]
	v_pk_fma_f32 v[220:221], v[188:189], s[52:53], v[220:221] op_sel_hi:[1,0,1]
	v_pk_fma_f32 v[222:223], v[190:191], s[52:53], v[222:223] op_sel_hi:[1,0,1]
	v_pk_fma_f32 v[224:225], v[188:189], s[54:55], v[224:225] op_sel_hi:[1,0,1]
	v_pk_fma_f32 v[226:227], v[190:191], s[54:55], v[226:227] op_sel_hi:[1,0,1]
	v_pk_fma_f32 v[228:229], v[188:189], s[56:57], v[228:229] op_sel_hi:[1,0,1]
	v_pk_fma_f32 v[230:231], v[190:191], s[56:57], v[230:231] op_sel_hi:[1,0,1]
	s_waitcnt vmcnt(9)
	v_readlane_b32 s50, v11, 54
	v_readlane_b32 s52, v54, 54
	v_readlane_b32 s54, v55, 54
	v_readlane_b32 s56, v56, 54
	v_pk_fma_f32 v[216:217], v[192:193], s[50:51], v[216:217] op_sel_hi:[1,0,1]
	v_pk_fma_f32 v[218:219], v[194:195], s[50:51], v[218:219] op_sel_hi:[1,0,1]
	v_pk_fma_f32 v[220:221], v[192:193], s[52:53], v[220:221] op_sel_hi:[1,0,1]
	v_pk_fma_f32 v[222:223], v[194:195], s[52:53], v[222:223] op_sel_hi:[1,0,1]
	v_pk_fma_f32 v[224:225], v[192:193], s[54:55], v[224:225] op_sel_hi:[1,0,1]
	v_pk_fma_f32 v[226:227], v[194:195], s[54:55], v[226:227] op_sel_hi:[1,0,1]
	v_pk_fma_f32 v[228:229], v[192:193], s[56:57], v[228:229] op_sel_hi:[1,0,1]
	v_pk_fma_f32 v[230:231], v[194:195], s[56:57], v[230:231] op_sel_hi:[1,0,1]
	s_waitcnt vmcnt(8)
	v_readlane_b32 s50, v11, 55
	v_readlane_b32 s52, v54, 55
	v_readlane_b32 s54, v55, 55
	v_readlane_b32 s56, v56, 55
	v_pk_fma_f32 v[216:217], v[196:197], s[50:51], v[216:217] op_sel_hi:[1,0,1]
	v_pk_fma_f32 v[218:219], v[198:199], s[50:51], v[218:219] op_sel_hi:[1,0,1]
	v_pk_fma_f32 v[220:221], v[196:197], s[52:53], v[220:221] op_sel_hi:[1,0,1]
	v_pk_fma_f32 v[222:223], v[198:199], s[52:53], v[222:223] op_sel_hi:[1,0,1]
	v_pk_fma_f32 v[224:225], v[196:197], s[54:55], v[224:225] op_sel_hi:[1,0,1]
	v_pk_fma_f32 v[226:227], v[198:199], s[54:55], v[226:227] op_sel_hi:[1,0,1]
	v_pk_fma_f32 v[228:229], v[196:197], s[56:57], v[228:229] op_sel_hi:[1,0,1]
	v_pk_fma_f32 v[230:231], v[198:199], s[56:57], v[230:231] op_sel_hi:[1,0,1]
	s_waitcnt vmcnt(7)
	v_readlane_b32 s50, v11, 56
	v_readlane_b32 s52, v54, 56
	v_readlane_b32 s54, v55, 56
	v_readlane_b32 s56, v56, 56
	v_pk_fma_f32 v[216:217], v[200:201], s[50:51], v[216:217] op_sel_hi:[1,0,1]
	v_pk_fma_f32 v[218:219], v[202:203], s[50:51], v[218:219] op_sel_hi:[1,0,1]
	v_pk_fma_f32 v[220:221], v[200:201], s[52:53], v[220:221] op_sel_hi:[1,0,1]
	v_pk_fma_f32 v[222:223], v[202:203], s[52:53], v[222:223] op_sel_hi:[1,0,1]
	v_pk_fma_f32 v[224:225], v[200:201], s[54:55], v[224:225] op_sel_hi:[1,0,1]
	v_pk_fma_f32 v[226:227], v[202:203], s[54:55], v[226:227] op_sel_hi:[1,0,1]
	v_pk_fma_f32 v[228:229], v[200:201], s[56:57], v[228:229] op_sel_hi:[1,0,1]
	v_pk_fma_f32 v[230:231], v[202:203], s[56:57], v[230:231] op_sel_hi:[1,0,1]
	s_waitcnt vmcnt(6)
	v_readlane_b32 s50, v11, 57
	v_readlane_b32 s52, v54, 57
	v_readlane_b32 s54, v55, 57
	v_readlane_b32 s56, v56, 57
	v_pk_fma_f32 v[216:217], v[204:205], s[50:51], v[216:217] op_sel_hi:[1,0,1]
	v_pk_fma_f32 v[218:219], v[206:207], s[50:51], v[218:219] op_sel_hi:[1,0,1]
	v_pk_fma_f32 v[220:221], v[204:205], s[52:53], v[220:221] op_sel_hi:[1,0,1]
	v_pk_fma_f32 v[222:223], v[206:207], s[52:53], v[222:223] op_sel_hi:[1,0,1]
	v_pk_fma_f32 v[224:225], v[204:205], s[54:55], v[224:225] op_sel_hi:[1,0,1]
	v_pk_fma_f32 v[226:227], v[206:207], s[54:55], v[226:227] op_sel_hi:[1,0,1]
	v_pk_fma_f32 v[228:229], v[204:205], s[56:57], v[228:229] op_sel_hi:[1,0,1]
	v_pk_fma_f32 v[230:231], v[206:207], s[56:57], v[230:231] op_sel_hi:[1,0,1]
	s_waitcnt vmcnt(5)
	v_readlane_b32 s50, v11, 58
	v_readlane_b32 s52, v54, 58
	v_readlane_b32 s54, v55, 58
	v_readlane_b32 s56, v56, 58
	v_pk_fma_f32 v[216:217], v[208:209], s[50:51], v[216:217] op_sel_hi:[1,0,1]
	v_pk_fma_f32 v[218:219], v[210:211], s[50:51], v[218:219] op_sel_hi:[1,0,1]
	v_pk_fma_f32 v[220:221], v[208:209], s[52:53], v[220:221] op_sel_hi:[1,0,1]
	v_pk_fma_f32 v[222:223], v[210:211], s[52:53], v[222:223] op_sel_hi:[1,0,1]
	v_pk_fma_f32 v[224:225], v[208:209], s[54:55], v[224:225] op_sel_hi:[1,0,1]
	v_pk_fma_f32 v[226:227], v[210:211], s[54:55], v[226:227] op_sel_hi:[1,0,1]
	v_pk_fma_f32 v[228:229], v[208:209], s[56:57], v[228:229] op_sel_hi:[1,0,1]
	v_pk_fma_f32 v[230:231], v[210:211], s[56:57], v[230:231] op_sel_hi:[1,0,1]
	s_waitcnt vmcnt(4)
	v_readlane_b32 s50, v11, 59
	v_readlane_b32 s52, v54, 59
	v_readlane_b32 s54, v55, 59
	v_readlane_b32 s56, v56, 59
	v_pk_fma_f32 v[216:217], v[212:213], s[50:51], v[216:217] op_sel_hi:[1,0,1]
	v_pk_fma_f32 v[218:219], v[214:215], s[50:51], v[218:219] op_sel_hi:[1,0,1]
	v_pk_fma_f32 v[220:221], v[212:213], s[52:53], v[220:221] op_sel_hi:[1,0,1]
	v_pk_fma_f32 v[222:223], v[214:215], s[52:53], v[222:223] op_sel_hi:[1,0,1]
	v_pk_fma_f32 v[224:225], v[212:213], s[54:55], v[224:225] op_sel_hi:[1,0,1]
	v_pk_fma_f32 v[226:227], v[214:215], s[54:55], v[226:227] op_sel_hi:[1,0,1]
	v_pk_fma_f32 v[228:229], v[212:213], s[56:57], v[228:229] op_sel_hi:[1,0,1]
	v_pk_fma_f32 v[230:231], v[214:215], s[56:57], v[230:231] op_sel_hi:[1,0,1]
	s_waitcnt vmcnt(3)
	v_readlane_b32 s50, v11, 60
	v_readlane_b32 s52, v54, 60
	v_readlane_b32 s54, v55, 60
	v_readlane_b32 s56, v56, 60
	v_pk_fma_f32 v[216:217], v[168:169], s[50:51], v[216:217] op_sel_hi:[1,0,1]
	v_pk_fma_f32 v[218:219], v[170:171], s[50:51], v[218:219] op_sel_hi:[1,0,1]
	v_pk_fma_f32 v[220:221], v[168:169], s[52:53], v[220:221] op_sel_hi:[1,0,1]
	v_pk_fma_f32 v[222:223], v[170:171], s[52:53], v[222:223] op_sel_hi:[1,0,1]
	v_pk_fma_f32 v[224:225], v[168:169], s[54:55], v[224:225] op_sel_hi:[1,0,1]
	v_pk_fma_f32 v[226:227], v[170:171], s[54:55], v[226:227] op_sel_hi:[1,0,1]
	v_pk_fma_f32 v[228:229], v[168:169], s[56:57], v[228:229] op_sel_hi:[1,0,1]
	v_pk_fma_f32 v[230:231], v[170:171], s[56:57], v[230:231] op_sel_hi:[1,0,1]
	s_waitcnt vmcnt(2)
	v_readlane_b32 s50, v11, 61
	v_readlane_b32 s52, v54, 61
	v_readlane_b32 s54, v55, 61
	v_readlane_b32 s56, v56, 61
	v_pk_fma_f32 v[216:217], v[172:173], s[50:51], v[216:217] op_sel_hi:[1,0,1]
	v_pk_fma_f32 v[218:219], v[174:175], s[50:51], v[218:219] op_sel_hi:[1,0,1]
	v_pk_fma_f32 v[220:221], v[172:173], s[52:53], v[220:221] op_sel_hi:[1,0,1]
	v_pk_fma_f32 v[222:223], v[174:175], s[52:53], v[222:223] op_sel_hi:[1,0,1]
	v_pk_fma_f32 v[224:225], v[172:173], s[54:55], v[224:225] op_sel_hi:[1,0,1]
	v_pk_fma_f32 v[226:227], v[174:175], s[54:55], v[226:227] op_sel_hi:[1,0,1]
	v_pk_fma_f32 v[228:229], v[172:173], s[56:57], v[228:229] op_sel_hi:[1,0,1]
	v_pk_fma_f32 v[230:231], v[174:175], s[56:57], v[230:231] op_sel_hi:[1,0,1]
	s_waitcnt vmcnt(1)
	v_readlane_b32 s50, v11, 62
	v_readlane_b32 s52, v54, 62
	v_readlane_b32 s54, v55, 62
	v_readlane_b32 s56, v56, 62
	v_pk_fma_f32 v[216:217], v[176:177], s[50:51], v[216:217] op_sel_hi:[1,0,1]
	v_pk_fma_f32 v[218:219], v[178:179], s[50:51], v[218:219] op_sel_hi:[1,0,1]
	v_pk_fma_f32 v[220:221], v[176:177], s[52:53], v[220:221] op_sel_hi:[1,0,1]
	v_pk_fma_f32 v[222:223], v[178:179], s[52:53], v[222:223] op_sel_hi:[1,0,1]
	v_pk_fma_f32 v[224:225], v[176:177], s[54:55], v[224:225] op_sel_hi:[1,0,1]
	v_pk_fma_f32 v[226:227], v[178:179], s[54:55], v[226:227] op_sel_hi:[1,0,1]
	v_pk_fma_f32 v[228:229], v[176:177], s[56:57], v[228:229] op_sel_hi:[1,0,1]
	v_pk_fma_f32 v[230:231], v[178:179], s[56:57], v[230:231] op_sel_hi:[1,0,1]
	s_waitcnt vmcnt(0)
	v_readlane_b32 s50, v11, 63
	v_readlane_b32 s52, v54, 63
	v_readlane_b32 s54, v55, 63
	v_readlane_b32 s56, v56, 63
	v_pk_fma_f32 v[216:217], v[180:181], s[50:51], v[216:217] op_sel_hi:[1,0,1]
	v_pk_fma_f32 v[218:219], v[182:183], s[50:51], v[218:219] op_sel_hi:[1,0,1]
	v_pk_fma_f32 v[220:221], v[180:181], s[52:53], v[220:221] op_sel_hi:[1,0,1]
	v_pk_fma_f32 v[222:223], v[182:183], s[52:53], v[222:223] op_sel_hi:[1,0,1]
	v_pk_fma_f32 v[224:225], v[180:181], s[54:55], v[224:225] op_sel_hi:[1,0,1]
	v_pk_fma_f32 v[226:227], v[182:183], s[54:55], v[226:227] op_sel_hi:[1,0,1]
	v_pk_fma_f32 v[228:229], v[180:181], s[56:57], v[228:229] op_sel_hi:[1,0,1]
	v_pk_fma_f32 v[230:231], v[182:183], s[56:57], v[230:231] op_sel_hi:[1,0,1]
	v_mov_b32_e32 v52, v216
	v_mov_b32_e32 v53, v218
	v_mov_b32_e32 v50, v217
	v_mov_b32_e32 v51, v219
	v_mov_b32_e32 v46, v220
	v_mov_b32_e32 v47, v222
	v_mov_b32_e32 v44, v221
	v_mov_b32_e32 v45, v223
	v_mov_b32_e32 v36, v224
	v_mov_b32_e32 v37, v226
	v_mov_b32_e32 v34, v225
	v_mov_b32_e32 v35, v227
	v_mov_b32_e32 v28, v228
	v_mov_b32_e32 v29, v230
	v_mov_b32_e32 v26, v229
	v_mov_b32_e32 v27, v231
	v_lshlrev_b64 v[40:41], 10, v[12:13]
	v_lshl_add_u64 v[40:41], v[16:17], 0, v[40:41]
	global_load_dwordx4 v[54:57], v[40:41], off
	v_add_co_u32_e32 v40, vcc, 0xa00000, v40
	v_readlane_b32 s4, v162, 8
	s_nop 0
	v_addc_co_u32_e32 v41, vcc, 0, v41, vcc
	global_load_dwordx4 v[58:61], v[40:41], off
	s_waitcnt vmcnt(1)
	v_mov_b32_e32 v62, v54
	v_mov_b32_e32 v63, v56
	v_mov_b32_e32 v56, v55
	s_waitcnt vmcnt(0)
	v_mov_b32_e32 v64, v58
	v_mov_b32_e32 v65, v60
	v_mov_b32_e32 v60, v59
	v_pk_add_f32 v[62:63], v[62:63], v[64:65]
	v_pk_add_f32 v[64:65], v[56:57], v[60:61]
	s_nop 0
	v_pk_add_f32 v[54:55], v[62:63], v[64:65]
	s_nop 0
	v_add_f32_e32 v11, v54, v55
	s_nop 1
	v_add_f32_dpp v11, v11, v11 quad_perm:[1,0,3,2] row_mask:0xf bank_mask:0xf bound_ctrl:1
	s_nop 1
	v_add_f32_dpp v11, v11, v11 quad_perm:[2,3,0,1] row_mask:0xf bank_mask:0xf bound_ctrl:1
	s_nop 1
	v_add_f32_dpp v11, v11, v11 row_half_mirror row_mask:0xf bank_mask:0xf bound_ctrl:1
	s_nop 1
	v_add_f32_dpp v11, v11, v11 row_mirror row_mask:0xf bank_mask:0xf bound_ctrl:1
	v_mul_f32_e32 v66, 0x3c800000, v11
	v_mov_b32_e32 v11, v117
	v_lshl_add_u64 v[48:49], v[48:49], 0, v[10:11]
	v_add_co_u32_e32 v48, vcc, s96, v48
	v_pk_add_f32 v[64:65], v[64:65], v[66:67] op_sel_hi:[1,0] neg_lo:[0,1] neg_hi:[0,1]
	s_nop 0
	v_addc_co_u32_e32 v49, vcc, 0, v49, vcc
	global_load_dwordx4 v[54:57], v[48:49], off
	global_load_dwordx4 v[58:61], v[48:49], off offset:1024
	v_pk_add_f32 v[62:63], v[62:63], v[66:67] op_sel_hi:[1,0] neg_lo:[0,1] neg_hi:[0,1]
	v_lshl_add_u64 v[42:43], v[42:43], 0, v[10:11]
	v_lshl_add_u64 v[32:33], v[32:33], 0, v[10:11]
	v_lshl_add_u64 v[24:25], v[24:25], 0, v[10:11]
	s_waitcnt vmcnt(1)
	v_mov_b32_e32 v68, v55
	s_waitcnt vmcnt(0)
	v_mov_b32_e32 v70, v59
	v_mov_b32_e32 v55, v57
	v_mov_b32_e32 v59, v61
	v_mov_b32_e32 v69, v56
	v_mov_b32_e32 v71, v60
	v_pk_mul_f32 v[54:55], v[54:55], v[58:59]
	v_pk_mul_f32 v[68:69], v[68:69], v[70:71]
	v_pk_mul_f32 v[54:55], v[0:1], v[54:55]
	s_nop 0
	v_pk_fma_f32 v[54:55], v[14:15], v[68:69], v[54:55]
	s_nop 0
	v_add_f32_e32 v54, v54, v55
	s_nop 1
	v_add_f32_dpp v54, v54, v54 quad_perm:[1,0,3,2] row_mask:0xf bank_mask:0xf bound_ctrl:1
	s_nop 1
	v_add_f32_dpp v54, v54, v54 quad_perm:[2,3,0,1] row_mask:0xf bank_mask:0xf bound_ctrl:1
	s_nop 1
	v_add_f32_dpp v54, v54, v54 row_half_mirror row_mask:0xf bank_mask:0xf bound_ctrl:1
	s_nop 1
	v_add_f32_dpp v58, v54, v54 row_mirror row_mask:0xf bank_mask:0xf bound_ctrl:1
	v_lshlrev_b64 v[54:55], 11, v[12:13]
	v_lshl_add_u64 v[60:61], v[2:3], 0, v[54:55]
	v_pk_mul_f32 v[54:55], v[64:65], v[64:65]
	v_add_u32_e32 v12, s4, v12
	v_pk_fma_f32 v[54:55], v[62:63], v[62:63], v[54:55]
	s_nop 0
	v_add_f32_e32 v13, v54, v55
	s_nop 1
	v_add_f32_dpp v13, v13, v13 quad_perm:[1,0,3,2] row_mask:0xf bank_mask:0xf bound_ctrl:1
	s_nop 1
	v_add_f32_dpp v13, v13, v13 quad_perm:[2,3,0,1] row_mask:0xf bank_mask:0xf bound_ctrl:1
	s_nop 1
	v_add_f32_dpp v13, v13, v13 row_half_mirror row_mask:0xf bank_mask:0xf bound_ctrl:1
	s_nop 1
	v_add_f32_dpp v13, v13, v13 row_mirror row_mask:0xf bank_mask:0xf bound_ctrl:1
	v_fmamk_f32 v13, v13, 0x3c800000, v132
	v_cmp_gt_f32_e32 vcc, s5, v13
	v_mul_f32_e32 v54, 0x4b800000, v13
	s_nop 0
	v_cndmask_b32_e32 v13, v13, v54, vcc
	v_rsq_f32_e32 v13, v13
	s_nop 0
	v_mul_f32_e32 v54, 0x45800000, v13
	v_cndmask_b32_e32 v66, v13, v54, vcc
	global_load_dwordx4 v[54:57], v[48:49], off offset:2048
	v_pk_mul_f32 v[48:49], v[62:63], v[66:67] op_sel_hi:[1,0]
	v_add_co_u32_e32 v42, vcc, s96, v42
	v_pk_fma_f32 v[48:49], v[8:9], v[48:49], v[4:5]
	s_nop 0
	v_addc_co_u32_e32 v43, vcc, 0, v43, vcc
	s_waitcnt vmcnt(0)
	v_mov_b32_e32 v62, v54
	v_mov_b32_e32 v63, v56
	v_pk_fma_f32 v[48:49], v[62:63], v[58:59], v[48:49] op_sel_hi:[1,0,1]
	v_mov_b32_e32 v56, v55
	v_pk_mul_f32 v[48:49], v[52:53], v[48:49]
	v_pk_mul_f32 v[52:53], v[64:65], v[66:67] op_sel_hi:[1,0]
	v_and_b32_sdwa v13, v49, v129 dst_sel:DWORD dst_unused:UNUSED_PAD src0_sel:WORD_1 src1_sel:DWORD
	v_pk_fma_f32 v[52:53], v[20:21], v[52:53], v[18:19]
	v_add3_u32 v13, v49, v13, s88
	v_pk_fma_f32 v[52:53], v[56:57], v[58:59], v[52:53] op_sel_hi:[1,0,1]
	s_nop 0
	v_pk_mul_f32 v[50:51], v[50:51], v[52:53]
	v_and_b32_sdwa v52, v48, v129 dst_sel:DWORD dst_unused:UNUSED_PAD src0_sel:WORD_1 src1_sel:DWORD
	v_add3_u32 v48, v48, v52, s88
	v_and_b32_sdwa v49, v51, v129 dst_sel:DWORD dst_unused:UNUSED_PAD src0_sel:WORD_1 src1_sel:DWORD
	v_and_b32_sdwa v52, v50, v129 dst_sel:DWORD dst_unused:UNUSED_PAD src0_sel:WORD_1 src1_sel:DWORD
	v_add3_u32 v49, v51, v49, s88
	v_add3_u32 v50, v50, v52, s88
	v_and_b32_e32 v49, 0xffff0000, v49
	v_and_b32_e32 v50, 0xffff0000, v50
	v_or_b32_sdwa v49, v49, v13 dst_sel:DWORD dst_unused:UNUSED_PAD src0_sel:DWORD src1_sel:WORD_1
	v_or_b32_sdwa v48, v50, v48 dst_sel:DWORD dst_unused:UNUSED_PAD src0_sel:DWORD src1_sel:WORD_1
	global_store_dwordx2 v[60:61], v[48:49], off offset:1536
	v_lshlrev_b64 v[48:49], 10, v[38:39]
	v_lshl_add_u64 v[48:49], v[16:17], 0, v[48:49]
	global_load_dwordx4 v[50:53], v[48:49], off
	global_load_dwordx4 v[54:57], v[40:41], off offset:1024
	v_lshlrev_b64 v[38:39], 11, v[38:39]
	v_lshl_add_u64 v[38:39], v[2:3], 0, v[38:39]
	s_waitcnt vmcnt(1)
	v_mov_b32_e32 v48, v50
	v_mov_b32_e32 v49, v52
	s_waitcnt vmcnt(0)
	v_mov_b32_e32 v58, v54
	v_mov_b32_e32 v59, v56
	v_mov_b32_e32 v52, v51
	v_mov_b32_e32 v56, v55
	v_pk_add_f32 v[48:49], v[48:49], v[58:59]
	v_pk_add_f32 v[50:51], v[52:53], v[56:57]
	global_load_dwordx4 v[54:57], v[42:43], off
	global_load_dwordx4 v[58:61], v[42:43], off offset:1024
	v_pk_add_f32 v[52:53], v[48:49], v[50:51]
	s_waitcnt vmcnt(1)
	v_mov_b32_e32 v62, v55
	v_add_f32_e32 v13, v52, v53
	s_waitcnt vmcnt(0)
	v_mov_b32_e32 v64, v59
	v_mov_b32_e32 v55, v57
	v_add_f32_dpp v13, v13, v13 quad_perm:[1,0,3,2] row_mask:0xf bank_mask:0xf bound_ctrl:1
	v_mov_b32_e32 v59, v61
	v_mov_b32_e32 v63, v56
	v_add_f32_dpp v13, v13, v13 quad_perm:[2,3,0,1] row_mask:0xf bank_mask:0xf bound_ctrl:1
	v_mov_b32_e32 v65, v60
	v_pk_mul_f32 v[54:55], v[54:55], v[58:59]
	v_add_f32_dpp v13, v13, v13 row_half_mirror row_mask:0xf bank_mask:0xf bound_ctrl:1
	v_pk_mul_f32 v[62:63], v[62:63], v[64:65]
	v_pk_mul_f32 v[54:55], v[0:1], v[54:55]
	v_add_f32_dpp v13, v13, v13 row_mirror row_mask:0xf bank_mask:0xf bound_ctrl:1
	v_pk_fma_f32 v[54:55], v[14:15], v[62:63], v[54:55]
	v_mul_f32_e32 v52, 0x3c800000, v13
	v_add_f32_e32 v13, v54, v55
	v_pk_add_f32 v[56:57], v[48:49], v[52:53] op_sel_hi:[1,0] neg_lo:[0,1] neg_hi:[0,1]
	v_pk_add_f32 v[52:53], v[50:51], v[52:53] op_sel_hi:[1,0] neg_lo:[0,1] neg_hi:[0,1]
	v_add_f32_dpp v13, v13, v13 quad_perm:[1,0,3,2] row_mask:0xf bank_mask:0xf bound_ctrl:1
	v_pk_mul_f32 v[48:49], v[52:53], v[52:53]
	s_nop 0
	v_add_f32_dpp v13, v13, v13 quad_perm:[2,3,0,1] row_mask:0xf bank_mask:0xf bound_ctrl:1
	v_pk_fma_f32 v[48:49], v[56:57], v[56:57], v[48:49]
	s_nop 0
	v_add_f32_dpp v13, v13, v13 row_half_mirror row_mask:0xf bank_mask:0xf bound_ctrl:1
	s_nop 1
	v_add_f32_dpp v54, v13, v13 row_mirror row_mask:0xf bank_mask:0xf bound_ctrl:1
	v_add_f32_e32 v13, v48, v49
	s_nop 1
	v_add_f32_dpp v13, v13, v13 quad_perm:[1,0,3,2] row_mask:0xf bank_mask:0xf bound_ctrl:1
	s_nop 1
	v_add_f32_dpp v13, v13, v13 quad_perm:[2,3,0,1] row_mask:0xf bank_mask:0xf bound_ctrl:1
	s_nop 1
	v_add_f32_dpp v13, v13, v13 row_half_mirror row_mask:0xf bank_mask:0xf bound_ctrl:1
	s_nop 1
	v_add_f32_dpp v13, v13, v13 row_mirror row_mask:0xf bank_mask:0xf bound_ctrl:1
	v_fmamk_f32 v13, v13, 0x3c800000, v132
	v_cmp_gt_f32_e32 vcc, s5, v13
	v_mul_f32_e32 v48, 0x4b800000, v13
	s_nop 0
	v_cndmask_b32_e32 v13, v13, v48, vcc
	v_rsq_f32_e32 v13, v13
	s_nop 0
	v_mul_f32_e32 v48, 0x45800000, v13
	v_cndmask_b32_e32 v58, v13, v48, vcc
	global_load_dwordx4 v[48:51], v[42:43], off offset:2048
	v_pk_mul_f32 v[42:43], v[56:57], v[58:59] op_sel_hi:[1,0]
	v_add_co_u32_e32 v32, vcc, s96, v32
	v_pk_fma_f32 v[42:43], v[8:9], v[42:43], v[4:5]
	s_nop 0
	v_addc_co_u32_e32 v33, vcc, 0, v33, vcc
	s_waitcnt vmcnt(0)
	v_mov_b32_e32 v56, v48
	v_mov_b32_e32 v57, v50
	v_pk_fma_f32 v[42:43], v[56:57], v[54:55], v[42:43] op_sel_hi:[1,0,1]
	v_mov_b32_e32 v50, v49
	v_pk_mul_f32 v[42:43], v[46:47], v[42:43]
	v_pk_mul_f32 v[46:47], v[52:53], v[58:59] op_sel_hi:[1,0]
	v_and_b32_sdwa v13, v43, v129 dst_sel:DWORD dst_unused:UNUSED_PAD src0_sel:WORD_1 src1_sel:DWORD
	v_pk_fma_f32 v[46:47], v[20:21], v[46:47], v[18:19]
	v_add3_u32 v13, v43, v13, s88
	v_pk_fma_f32 v[46:47], v[50:51], v[54:55], v[46:47] op_sel_hi:[1,0,1]
	s_nop 0
	v_pk_mul_f32 v[44:45], v[44:45], v[46:47]
	v_and_b32_sdwa v46, v42, v129 dst_sel:DWORD dst_unused:UNUSED_PAD src0_sel:WORD_1 src1_sel:DWORD
	v_add3_u32 v42, v42, v46, s88
	v_and_b32_sdwa v43, v45, v129 dst_sel:DWORD dst_unused:UNUSED_PAD src0_sel:WORD_1 src1_sel:DWORD
	v_and_b32_sdwa v46, v44, v129 dst_sel:DWORD dst_unused:UNUSED_PAD src0_sel:WORD_1 src1_sel:DWORD
	v_add3_u32 v43, v45, v43, s88
	v_add3_u32 v44, v44, v46, s88
	v_and_b32_e32 v43, 0xffff0000, v43
	v_and_b32_e32 v44, 0xffff0000, v44
	v_or_b32_sdwa v43, v43, v13 dst_sel:DWORD dst_unused:UNUSED_PAD src0_sel:DWORD src1_sel:WORD_1
	v_or_b32_sdwa v42, v44, v42 dst_sel:DWORD dst_unused:UNUSED_PAD src0_sel:DWORD src1_sel:WORD_1
	global_store_dwordx2 v[38:39], v[42:43], off offset:1536
	v_lshlrev_b64 v[38:39], 10, v[30:31]
	v_lshl_add_u64 v[38:39], v[16:17], 0, v[38:39]
	global_load_dwordx4 v[42:45], v[38:39], off
	global_load_dwordx4 v[46:49], v[40:41], off offset:2048
	v_lshlrev_b64 v[30:31], 11, v[30:31]
	s_waitcnt vmcnt(1)
	v_mov_b32_e32 v38, v42
	v_mov_b32_e32 v39, v44
	s_waitcnt vmcnt(0)
	v_mov_b32_e32 v50, v46
	v_mov_b32_e32 v51, v48
	v_mov_b32_e32 v44, v43
	v_mov_b32_e32 v48, v47
	v_pk_add_f32 v[38:39], v[38:39], v[50:51]
	v_pk_add_f32 v[42:43], v[44:45], v[48:49]
	global_load_dwordx4 v[46:49], v[32:33], off
	global_load_dwordx4 v[50:53], v[32:33], off offset:1024
	v_pk_add_f32 v[44:45], v[38:39], v[42:43]
	s_waitcnt vmcnt(1)
	v_mov_b32_e32 v54, v47
	v_add_f32_e32 v13, v44, v45
	s_waitcnt vmcnt(0)
	v_mov_b32_e32 v56, v51
	v_mov_b32_e32 v47, v49
	v_add_f32_dpp v13, v13, v13 quad_perm:[1,0,3,2] row_mask:0xf bank_mask:0xf bound_ctrl:1
	v_mov_b32_e32 v51, v53
	v_mov_b32_e32 v55, v48
	v_add_f32_dpp v13, v13, v13 quad_perm:[2,3,0,1] row_mask:0xf bank_mask:0xf bound_ctrl:1
	v_mov_b32_e32 v57, v52
	v_pk_mul_f32 v[46:47], v[46:47], v[50:51]
	v_add_f32_dpp v13, v13, v13 row_half_mirror row_mask:0xf bank_mask:0xf bound_ctrl:1
	v_pk_mul_f32 v[54:55], v[54:55], v[56:57]
	v_pk_mul_f32 v[46:47], v[0:1], v[46:47]
	v_add_f32_dpp v13, v13, v13 row_mirror row_mask:0xf bank_mask:0xf bound_ctrl:1
	v_pk_fma_f32 v[46:47], v[14:15], v[54:55], v[46:47]
	v_mul_f32_e32 v44, 0x3c800000, v13
	v_add_f32_e32 v13, v46, v47
	v_pk_add_f32 v[42:43], v[42:43], v[44:45] op_sel_hi:[1,0] neg_lo:[0,1] neg_hi:[0,1]
	v_lshl_add_u64 v[48:49], v[2:3], 0, v[30:31]
	v_add_f32_dpp v13, v13, v13 quad_perm:[1,0,3,2] row_mask:0xf bank_mask:0xf bound_ctrl:1
	v_pk_add_f32 v[38:39], v[38:39], v[44:45] op_sel_hi:[1,0] neg_lo:[0,1] neg_hi:[0,1]
	v_pk_mul_f32 v[30:31], v[42:43], v[42:43]
	v_add_f32_dpp v13, v13, v13 quad_perm:[2,3,0,1] row_mask:0xf bank_mask:0xf bound_ctrl:1
	v_pk_fma_f32 v[30:31], v[38:39], v[38:39], v[30:31]
	s_nop 0
	v_add_f32_dpp v13, v13, v13 row_half_mirror row_mask:0xf bank_mask:0xf bound_ctrl:1
	s_nop 1
	v_add_f32_dpp v46, v13, v13 row_mirror row_mask:0xf bank_mask:0xf bound_ctrl:1
	v_add_f32_e32 v13, v30, v31
	s_nop 1
	v_add_f32_dpp v13, v13, v13 quad_perm:[1,0,3,2] row_mask:0xf bank_mask:0xf bound_ctrl:1
	s_nop 1
	v_add_f32_dpp v13, v13, v13 quad_perm:[2,3,0,1] row_mask:0xf bank_mask:0xf bound_ctrl:1
	s_nop 1
	v_add_f32_dpp v13, v13, v13 row_half_mirror row_mask:0xf bank_mask:0xf bound_ctrl:1
	s_nop 1
	v_add_f32_dpp v13, v13, v13 row_mirror row_mask:0xf bank_mask:0xf bound_ctrl:1
	v_fmamk_f32 v13, v13, 0x3c800000, v132
	v_cmp_gt_f32_e32 vcc, s5, v13
	v_mul_f32_e32 v30, 0x4b800000, v13
	s_nop 0
	v_cndmask_b32_e32 v13, v13, v30, vcc
	v_rsq_f32_e32 v13, v13
	s_nop 0
	v_mul_f32_e32 v30, 0x45800000, v13
	v_cndmask_b32_e32 v44, v13, v30, vcc
	global_load_dwordx4 v[30:33], v[32:33], off offset:2048
	v_pk_mul_f32 v[38:39], v[38:39], v[44:45] op_sel_hi:[1,0]
	v_add_co_u32_e32 v24, vcc, s96, v24
	v_pk_fma_f32 v[38:39], v[8:9], v[38:39], v[4:5]
	s_nop 0
	v_addc_co_u32_e32 v25, vcc, 0, v25, vcc
	s_waitcnt vmcnt(0)
	v_mov_b32_e32 v50, v30
	v_mov_b32_e32 v51, v32
	v_pk_fma_f32 v[38:39], v[50:51], v[46:47], v[38:39] op_sel_hi:[1,0,1]
	v_mov_b32_e32 v32, v31
	v_pk_mul_f32 v[36:37], v[36:37], v[38:39]
	v_pk_mul_f32 v[38:39], v[42:43], v[44:45] op_sel_hi:[1,0]
	v_and_b32_sdwa v13, v37, v129 dst_sel:DWORD dst_unused:UNUSED_PAD src0_sel:WORD_1 src1_sel:DWORD
	v_pk_fma_f32 v[38:39], v[20:21], v[38:39], v[18:19]
	v_add3_u32 v13, v37, v13, s88
	v_pk_fma_f32 v[30:31], v[32:33], v[46:47], v[38:39] op_sel_hi:[1,0,1]
	v_and_b32_sdwa v32, v36, v129 dst_sel:DWORD dst_unused:UNUSED_PAD src0_sel:WORD_1 src1_sel:DWORD
	v_pk_mul_f32 v[30:31], v[34:35], v[30:31]
	v_add3_u32 v32, v36, v32, s88
	v_and_b32_sdwa v33, v31, v129 dst_sel:DWORD dst_unused:UNUSED_PAD src0_sel:WORD_1 src1_sel:DWORD
	v_and_b32_sdwa v34, v30, v129 dst_sel:DWORD dst_unused:UNUSED_PAD src0_sel:WORD_1 src1_sel:DWORD
	v_add3_u32 v31, v31, v33, s88
	v_add3_u32 v30, v30, v34, s88
	v_and_b32_e32 v31, 0xffff0000, v31
	v_and_b32_e32 v30, 0xffff0000, v30
	v_or_b32_sdwa v31, v31, v13 dst_sel:DWORD dst_unused:UNUSED_PAD src0_sel:DWORD src1_sel:WORD_1
	v_or_b32_sdwa v30, v30, v32 dst_sel:DWORD dst_unused:UNUSED_PAD src0_sel:DWORD src1_sel:WORD_1
	global_store_dwordx2 v[48:49], v[30:31], off offset:1536
	v_lshlrev_b64 v[30:31], 10, v[22:23]
	v_lshl_add_u64 v[30:31], v[16:17], 0, v[30:31]
	global_load_dwordx4 v[32:35], v[30:31], off
	global_load_dwordx4 v[36:39], v[40:41], off offset:3072
	v_lshlrev_b64 v[22:23], 11, v[22:23]
	s_waitcnt vmcnt(1)
	v_mov_b32_e32 v30, v32
	v_mov_b32_e32 v31, v34
	s_waitcnt vmcnt(0)
	v_mov_b32_e32 v40, v36
	v_mov_b32_e32 v41, v38
	v_mov_b32_e32 v34, v33
	v_mov_b32_e32 v38, v37
	v_pk_add_f32 v[30:31], v[30:31], v[40:41]
	v_pk_add_f32 v[32:33], v[34:35], v[38:39]
	global_load_dwordx4 v[36:39], v[24:25], off
	global_load_dwordx4 v[40:43], v[24:25], off offset:1024
	v_pk_add_f32 v[34:35], v[30:31], v[32:33]
	s_waitcnt vmcnt(1)
	v_mov_b32_e32 v44, v37
	v_add_f32_e32 v13, v34, v35
	s_waitcnt vmcnt(0)
	v_mov_b32_e32 v46, v41
	v_mov_b32_e32 v37, v39
	v_add_f32_dpp v13, v13, v13 quad_perm:[1,0,3,2] row_mask:0xf bank_mask:0xf bound_ctrl:1
	v_mov_b32_e32 v41, v43
	v_mov_b32_e32 v45, v38
	v_add_f32_dpp v13, v13, v13 quad_perm:[2,3,0,1] row_mask:0xf bank_mask:0xf bound_ctrl:1
	v_mov_b32_e32 v47, v42
	v_pk_mul_f32 v[36:37], v[36:37], v[40:41]
	v_add_f32_dpp v13, v13, v13 row_half_mirror row_mask:0xf bank_mask:0xf bound_ctrl:1
	v_pk_mul_f32 v[44:45], v[44:45], v[46:47]
	v_pk_mul_f32 v[36:37], v[0:1], v[36:37]
	v_add_f32_dpp v13, v13, v13 row_mirror row_mask:0xf bank_mask:0xf bound_ctrl:1
	v_pk_fma_f32 v[36:37], v[14:15], v[44:45], v[36:37]
	v_mul_f32_e32 v34, 0x3c800000, v13
	v_add_f32_e32 v11, v36, v37
	v_pk_add_f32 v[32:33], v[32:33], v[34:35] op_sel_hi:[1,0] neg_lo:[0,1] neg_hi:[0,1]
	v_lshl_add_u64 v[38:39], v[2:3], 0, v[22:23]
	v_add_f32_dpp v11, v11, v11 quad_perm:[1,0,3,2] row_mask:0xf bank_mask:0xf bound_ctrl:1
	v_pk_add_f32 v[30:31], v[30:31], v[34:35] op_sel_hi:[1,0] neg_lo:[0,1] neg_hi:[0,1]
	v_pk_mul_f32 v[22:23], v[32:33], v[32:33]
	v_add_f32_dpp v11, v11, v11 quad_perm:[2,3,0,1] row_mask:0xf bank_mask:0xf bound_ctrl:1
	v_pk_fma_f32 v[22:23], v[30:31], v[30:31], v[22:23]
	s_nop 0
	v_add_f32_dpp v11, v11, v11 row_half_mirror row_mask:0xf bank_mask:0xf bound_ctrl:1
	s_nop 1
	v_add_f32_dpp v36, v11, v11 row_mirror row_mask:0xf bank_mask:0xf bound_ctrl:1
	v_add_f32_e32 v11, v22, v23
	global_load_dwordx4 v[22:25], v[24:25], off offset:2048
	s_waitcnt vmcnt(0)
	v_mov_b32_e32 v40, v22
	v_add_f32_dpp v11, v11, v11 quad_perm:[1,0,3,2] row_mask:0xf bank_mask:0xf bound_ctrl:1
	v_mov_b32_e32 v41, v24
	v_mov_b32_e32 v24, v23
	v_add_f32_dpp v11, v11, v11 quad_perm:[2,3,0,1] row_mask:0xf bank_mask:0xf bound_ctrl:1
	s_nop 1
	v_add_f32_dpp v11, v11, v11 row_half_mirror row_mask:0xf bank_mask:0xf bound_ctrl:1
	s_nop 1
	v_add_f32_dpp v11, v11, v11 row_mirror row_mask:0xf bank_mask:0xf bound_ctrl:1
	v_fmamk_f32 v11, v11, 0x3c800000, v132
	v_cmp_gt_f32_e32 vcc, s5, v11
	v_mul_f32_e32 v13, 0x4b800000, v11
	s_nop 0
	v_cndmask_b32_e32 v11, v11, v13, vcc
	v_rsq_f32_e32 v11, v11
	s_nop 0
	v_mul_f32_e32 v13, 0x45800000, v11
	v_cndmask_b32_e32 v34, v11, v13, vcc
	v_pk_mul_f32 v[30:31], v[30:31], v[34:35] op_sel_hi:[1,0]
	v_cmp_lt_i32_e32 vcc, s6, v12
	v_pk_fma_f32 v[30:31], v[8:9], v[30:31], v[4:5]
	s_or_b64 s[20:21], vcc, s[20:21]
	v_pk_fma_f32 v[30:31], v[40:41], v[36:37], v[30:31] op_sel_hi:[1,0,1]
	s_nop 0
	v_pk_mul_f32 v[28:29], v[28:29], v[30:31]
	v_pk_mul_f32 v[30:31], v[32:33], v[34:35] op_sel_hi:[1,0]
	v_and_b32_sdwa v11, v29, v129 dst_sel:DWORD dst_unused:UNUSED_PAD src0_sel:WORD_1 src1_sel:DWORD
	v_pk_fma_f32 v[30:31], v[20:21], v[30:31], v[18:19]
	v_and_b32_sdwa v13, v28, v129 dst_sel:DWORD dst_unused:UNUSED_PAD src0_sel:WORD_1 src1_sel:DWORD
	v_pk_fma_f32 v[22:23], v[24:25], v[36:37], v[30:31] op_sel_hi:[1,0,1]
	v_add3_u32 v13, v28, v13, s88
	v_pk_mul_f32 v[22:23], v[26:27], v[22:23]
	v_add3_u32 v11, v29, v11, s88
	v_and_b32_sdwa v24, v23, v129 dst_sel:DWORD dst_unused:UNUSED_PAD src0_sel:WORD_1 src1_sel:DWORD
	v_and_b32_sdwa v25, v22, v129 dst_sel:DWORD dst_unused:UNUSED_PAD src0_sel:WORD_1 src1_sel:DWORD
	v_add3_u32 v23, v23, v24, s88
	v_add3_u32 v22, v22, v25, s88
	v_and_b32_e32 v23, 0xffff0000, v23
	v_and_b32_e32 v22, 0xffff0000, v22
	v_or_b32_sdwa v23, v23, v11 dst_sel:DWORD dst_unused:UNUSED_PAD src0_sel:DWORD src1_sel:WORD_1
	v_or_b32_sdwa v22, v22, v13 dst_sel:DWORD dst_unused:UNUSED_PAD src0_sel:DWORD src1_sel:WORD_1
	global_store_dwordx2 v[38:39], v[22:23], off offset:1536
	s_andn2_b64 exec, exec, s[20:21]
	s_cbranch_execnz .LBB0_804
